# k-inner+snake MFMA order, mid-segment s_setprio 0/3 flip removed (32 MFMAs at constant prio 3)
# speedup vs baseline: 1.0087x; 1.0087x over previous
; #define PG8_STAGE(bufoff, gbase, voff) do { _Pragma("unroll") for (int _i = 0; _i < 2; ++_i) \
;         __builtin_amdgcn_global_load_lds((const unsigned*)((const char*)(gbase) + (voff)[_i]), (PG8_LAS unsigned*)(lds + (bufoff) + ldsw + _i * 8192), 16, 0, 0); } while (0)
; #define PG8_LDA(dst, b, h) do { _Pragma("unroll") for (int m = 0; m < 4; ++m) _Pragma("unroll") for (int k = 0; k < 2; ++k) dst[m][k] = *(const PG8_LAS bf16x8*)(lds + PG8_SA(b, h) + aoff + m * 2048 + k * 1024); } while (0)
; #define PG8_MMA(ai, bj, At, Bt) do { __builtin_amdgcn_s_setprio(3); _Pragma("unroll") for (int m = 0; m < 4; ++m) _Pragma("unroll") for (int n = 0; n < 2; ++n) _Pragma("unroll") for (int k = 0; k < 2; ++k) \
;         acc[ai][bj][m][n] = __builtin_amdgcn_mfma_f32_16x16x32_bf16(Bt[n][k], At[m][k], acc[ai][bj][m][n], 0, 0, 0); __builtin_amdgcn_s_setprio(0); } while (0)
; #define PG8_WAIT_V(n) asm volatile("s_waitcnt vmcnt(" #n ")" ::: "memory")
; #define PG8_WAIT_L(n) asm volatile("s_waitcnt lgkmcnt(" #n ")" ::: "memory")
; #define PG8_BAR __builtin_amdgcn_s_barrier()
; #define PG8_SCHED __builtin_amdgcn_sched_barrier(0)
; template <class Epi, class Sched, bool ALIGN_EPI = false, bool SP2 = false>
; __device__ __forceinline__ void gemm_phase(PG8_LAS unsigned char* lds, const Gemm g, const Sched& S, const Epi& E) {
;     ...
;             PG8_WAIT_V(8); PG8_WAIT_L(0); PG8_BAR; PG8_MMA(0, 0, At, B0); PG8_MMA(0, 1, At, B1); PG8_BAR; PG8_SCHED;
;             PG8_LDA(At, 0, 1); PG8_STAGE(PG8_SB(0, 0), b2, voffB); PG8_STAGE(PG8_SB(0, 1), b2 + hstepB, voffB); PG8_STAGE(PG8_SA(0, 0), a2, voffA);
;             PG8_WAIT_V(8); PG8_WAIT_L(0); PG8_BAR; PG8_MMA(1, 0, At, B0); PG8_MMA(1, 1, At, B1); PG8_BAR; PG8_SCHED;
.Lengw1_e:
	s_waitcnt lgkmcnt(0)
	s_barrier
	s_setprio 3
	s_waitcnt lgkmcnt(0)
	v_mfma_f32_16x16x32_bf16 v[126:129], v[130:133], v[192:195], v[126:129]
	v_mfma_f32_16x16x32_bf16 v[126:129], v[134:137], v[196:199], v[126:129]
	v_mfma_f32_16x16x32_bf16 v[118:121], v[156:159], v[192:195], v[118:121]
	v_mfma_f32_16x16x32_bf16 v[118:121], v[172:175], v[196:199], v[118:121]
	v_mfma_f32_16x16x32_bf16 v[102:105], v[156:159], v[200:203], v[102:105]
	v_mfma_f32_16x16x32_bf16 v[102:105], v[172:175], v[204:207], v[102:105]
	v_mfma_f32_16x16x32_bf16 v[110:113], v[130:133], v[200:203], v[110:113]
	v_mfma_f32_16x16x32_bf16 v[110:113], v[134:137], v[204:207], v[110:113]
	v_mfma_f32_16x16x32_bf16 v[94:97], v[130:133], v[208:211], v[94:97]
	v_mfma_f32_16x16x32_bf16 v[94:97], v[134:137], v[212:215], v[94:97]
	v_mfma_f32_16x16x32_bf16 v[86:89], v[156:159], v[208:211], v[86:89]
	v_mfma_f32_16x16x32_bf16 v[86:89], v[172:175], v[212:215], v[86:89]
	v_mfma_f32_16x16x32_bf16 v[70:73], v[156:159], v[216:219], v[70:73]
	v_mfma_f32_16x16x32_bf16 v[70:73], v[172:175], v[220:223], v[70:73]
	v_mfma_f32_16x16x32_bf16 v[78:81], v[130:133], v[216:219], v[78:81]
	v_mfma_f32_16x16x32_bf16 v[78:81], v[134:137], v[220:223], v[78:81]
	v_mfma_f32_16x16x32_bf16 v[122:125], v[176:179], v[192:195], v[122:125]
	v_mfma_f32_16x16x32_bf16 v[122:125], v[180:183], v[196:199], v[122:125]
	v_mfma_f32_16x16x32_bf16 v[114:117], v[184:187], v[192:195], v[114:117]
	v_mfma_f32_16x16x32_bf16 v[114:117], v[188:191], v[196:199], v[114:117]
	v_mfma_f32_16x16x32_bf16 v[98:101], v[184:187], v[200:203], v[98:101]
	v_mfma_f32_16x16x32_bf16 v[98:101], v[188:191], v[204:207], v[98:101]
	v_mfma_f32_16x16x32_bf16 v[106:109], v[176:179], v[200:203], v[106:109]
	v_mfma_f32_16x16x32_bf16 v[106:109], v[180:183], v[204:207], v[106:109]
	v_mfma_f32_16x16x32_bf16 v[90:93], v[176:179], v[208:211], v[90:93]
	v_mfma_f32_16x16x32_bf16 v[90:93], v[180:183], v[212:215], v[90:93]
	v_mfma_f32_16x16x32_bf16 v[82:85], v[184:187], v[208:211], v[82:85]
	v_mfma_f32_16x16x32_bf16 v[82:85], v[188:191], v[212:215], v[82:85]
	v_mfma_f32_16x16x32_bf16 v[66:69], v[184:187], v[216:219], v[66:69]
	v_mfma_f32_16x16x32_bf16 v[66:69], v[188:191], v[220:223], v[66:69]
	v_mfma_f32_16x16x32_bf16 v[74:77], v[176:179], v[216:219], v[74:77]
	v_mfma_f32_16x16x32_bf16 v[74:77], v[180:183], v[220:223], v[74:77]
	s_setprio 0
	s_barrier
	s_add_i32 s56, s83, s66
	v_lshl_add_u64 v[160:161], s[8:9], 0, v[140:141]
	s_mov_b32 m0, s56
	ds_read_b128 v[192:195], v169 offset:16384
	ds_read_b128 v[196:199], v169 offset:17408
	ds_read_b128 v[200:203], v169 offset:18432
	ds_read_b128 v[204:207], v169 offset:19456
	ds_read_b128 v[208:211], v169 offset:20480
	ds_read_b128 v[212:215], v169 offset:21504
	ds_read_b128 v[216:219], v169 offset:22528
	ds_read_b128 v[220:223], v169 offset:23552
	global_load_lds_dwordx4 v[160:161], off
	s_add_i32 m0, s56, 0x2000
	s_add_u32 s56, s8, 0x100000
	v_lshl_add_u64 v[224:225], s[8:9], 0, v[144:145]
	s_addc_u32 s57, s9, 0
	s_add_i32 s58, s89, s66
	global_load_lds_dwordx4 v[224:225], off
	v_lshl_add_u64 v[226:227], s[56:57], 0, v[140:141]
	s_mov_b32 m0, s58
	v_lshl_add_u64 v[228:229], s[36:37], 0, v[142:143]
	global_load_lds_dwordx4 v[226:227], off
	v_lshl_add_u64 v[226:227], s[56:57], 0, v[144:145]
	s_add_i32 m0, s58, 0x2000
	s_nop 0
	global_load_lds_dwordx4 v[226:227], off
	v_lshl_add_u64 v[226:227], s[36:37], 0, v[138:139]
	s_mov_b32 m0, s55
	s_nop 0
	global_load_lds_dwordx4 v[226:227], off
	s_mov_b32 m0, s67
	s_nop 0
	global_load_lds_dwordx4 v[228:229], off
	s_cmp_eq_u32 s97, 0
	s_cbranch_scc1 .Lengw2_a
	s_cmp_eq_u32 s97, 2
	s_cbranch_scc1 .Lengw2_b
	s_cmp_eq_u32 s97, 4
	s_cbranch_scc1 .Lengw2_c
	s_waitcnt vmcnt(16)
	s_branch .Lengw2_e

; #define PG8_STAGE(bufoff, gbase, voff) do { _Pragma("unroll") for (int _i = 0; _i < 2; ++_i) \
;         __builtin_amdgcn_global_load_lds((const unsigned*)((const char*)(gbase) + (voff)[_i]), (PG8_LAS unsigned*)(lds + (bufoff) + ldsw + _i * 8192), 16, 0, 0); } while (0)
; #define PG8_LDA(dst, b, h) do { _Pragma("unroll") for (int m = 0; m < 4; ++m) _Pragma("unroll") for (int k = 0; k < 2; ++k) dst[m][k] = *(const PG8_LAS bf16x8*)(lds + PG8_SA(b, h) + aoff + m * 2048 + k * 1024); } while (0)
; #define PG8_LDB(dst, b, h) do { _Pragma("unroll") for (int n = 0; n < 2; ++n) _Pragma("unroll") for (int k = 0; k < 2; ++k) dst[n][k] = *(const PG8_LAS bf16x8*)(lds + PG8_SB(b, h) + boff + n * 2048 + k * 1024); } while (0)
; #define PG8_MMA(ai, bj, At, Bt) do { __builtin_amdgcn_s_setprio(3); _Pragma("unroll") for (int m = 0; m < 4; ++m) _Pragma("unroll") for (int n = 0; n < 2; ++n) _Pragma("unroll") for (int k = 0; k < 2; ++k) \
;         acc[ai][bj][m][n] = __builtin_amdgcn_mfma_f32_16x16x32_bf16(Bt[n][k], At[m][k], acc[ai][bj][m][n], 0, 0, 0); __builtin_amdgcn_s_setprio(0); } while (0)
; #define PG8_WAIT_V(n) asm volatile("s_waitcnt vmcnt(" #n ")" ::: "memory")
; #define PG8_WAIT_L(n) asm volatile("s_waitcnt lgkmcnt(" #n ")" ::: "memory")
; #define PG8_BAR __builtin_amdgcn_s_barrier()
; #define PG8_SCHED __builtin_amdgcn_sched_barrier(0)
; template <class Epi, class Sched, bool ALIGN_EPI = false, bool SP2 = false>
; __device__ __forceinline__ void gemm_phase(PG8_LAS unsigned char* lds, const Gemm g, const Sched& S, const Epi& E) {
;     ...
;             PG8_WAIT_V(8); PG8_WAIT_L(0); PG8_BAR; PG8_MMA(1, 0, At, B0); PG8_MMA(1, 1, At, B1); PG8_BAR; PG8_SCHED;
;             PG8_LDB(B0, 1, 0); PG8_LDB(B1, 1, 1); PG8_SCHED; PG8_LDA(At, 1, 0); PG8_STAGE(PG8_SA(0, 1), a2 + hstepA, voffA);
;             PG8_WAIT_V(8); PG8_WAIT_L(0); PG8_BAR; PG8_MMA(0, 0, At, B0); PG8_MMA(0, 1, At, B1); PG8_BAR; PG8_SCHED;
.Lengw2_e:
	s_waitcnt lgkmcnt(0)
	s_barrier
	s_setprio 3
	s_waitcnt lgkmcnt(0)
	v_mfma_f32_16x16x32_bf16 v[62:65], v[130:133], v[192:195], v[62:65]
	v_mfma_f32_16x16x32_bf16 v[62:65], v[134:137], v[196:199], v[62:65]
	v_mfma_f32_16x16x32_bf16 v[54:57], v[156:159], v[192:195], v[54:57]
	v_mfma_f32_16x16x32_bf16 v[54:57], v[172:175], v[196:199], v[54:57]
	v_mfma_f32_16x16x32_bf16 v[38:41], v[156:159], v[200:203], v[38:41]
	v_mfma_f32_16x16x32_bf16 v[38:41], v[172:175], v[204:207], v[38:41]
	v_mfma_f32_16x16x32_bf16 v[46:49], v[130:133], v[200:203], v[46:49]
	v_mfma_f32_16x16x32_bf16 v[46:49], v[134:137], v[204:207], v[46:49]
	v_mfma_f32_16x16x32_bf16 v[30:33], v[130:133], v[208:211], v[30:33]
	v_mfma_f32_16x16x32_bf16 v[30:33], v[134:137], v[212:215], v[30:33]
	v_mfma_f32_16x16x32_bf16 v[22:25], v[156:159], v[208:211], v[22:25]
	v_mfma_f32_16x16x32_bf16 v[22:25], v[172:175], v[212:215], v[22:25]
	v_mfma_f32_16x16x32_bf16 v[6:9], v[156:159], v[216:219], v[6:9]
	v_mfma_f32_16x16x32_bf16 v[6:9], v[172:175], v[220:223], v[6:9]
	v_mfma_f32_16x16x32_bf16 v[14:17], v[130:133], v[216:219], v[14:17]
	v_mfma_f32_16x16x32_bf16 v[14:17], v[134:137], v[220:223], v[14:17]
	v_mfma_f32_16x16x32_bf16 v[58:61], v[176:179], v[192:195], v[58:61]
	v_mfma_f32_16x16x32_bf16 v[58:61], v[180:183], v[196:199], v[58:61]
	v_mfma_f32_16x16x32_bf16 v[50:53], v[184:187], v[192:195], v[50:53]
	v_mfma_f32_16x16x32_bf16 v[50:53], v[188:191], v[196:199], v[50:53]
	v_mfma_f32_16x16x32_bf16 v[34:37], v[184:187], v[200:203], v[34:37]
	v_mfma_f32_16x16x32_bf16 v[34:37], v[188:191], v[204:207], v[34:37]
	v_mfma_f32_16x16x32_bf16 v[42:45], v[176:179], v[200:203], v[42:45]
	v_mfma_f32_16x16x32_bf16 v[42:45], v[180:183], v[204:207], v[42:45]
	v_mfma_f32_16x16x32_bf16 v[26:29], v[176:179], v[208:211], v[26:29]
	v_mfma_f32_16x16x32_bf16 v[26:29], v[180:183], v[212:215], v[26:29]
	v_mfma_f32_16x16x32_bf16 v[18:21], v[184:187], v[208:211], v[18:21]
	v_mfma_f32_16x16x32_bf16 v[18:21], v[188:191], v[212:215], v[18:21]
	v_mfma_f32_16x16x32_bf16 v[2:5], v[184:187], v[216:219], v[2:5]
	v_mfma_f32_16x16x32_bf16 v[2:5], v[188:191], v[220:223], v[2:5]
	v_mfma_f32_16x16x32_bf16 v[10:13], v[176:179], v[216:219], v[10:13]
	v_mfma_f32_16x16x32_bf16 v[10:13], v[180:183], v[220:223], v[10:13]
	s_setprio 0
	s_barrier
	s_add_i32 s56, 0, 0x18000
	v_add_u32_e32 v146, s56, v164
	s_add_i32 s57, 0, 0x1c000
	ds_read_b128 v[130:133], v146
	ds_read_b128 v[134:137], v146 offset:1024
	ds_read_b128 v[156:159], v146 offset:2048
	ds_read_b128 v[172:175], v146 offset:3072
	v_add_u32_e32 v146, s57, v164
	ds_read_b128 v[176:179], v146
	ds_read_b128 v[180:183], v146 offset:1024
	ds_read_b128 v[184:187], v146 offset:2048
	ds_read_b128 v[188:191], v146 offset:3072
	s_add_u32 s36, s36, 0x100000
	s_addc_u32 s37, s37, 0
	s_mov_b32 m0, s72
	v_lshl_add_u64 v[230:231], s[36:37], 0, v[138:139]
	ds_read_b128 v[192:195], v169 offset:32768
	ds_read_b128 v[196:199], v169 offset:33792
	ds_read_b128 v[200:203], v169 offset:34816
	ds_read_b128 v[204:207], v169 offset:35840
	ds_read_b128 v[208:211], v169 offset:36864
	ds_read_b128 v[212:215], v169 offset:37888
	ds_read_b128 v[216:219], v169 offset:38912
	ds_read_b128 v[220:223], v169 offset:39936
	global_load_lds_dwordx4 v[230:231], off
	v_lshl_add_u64 v[230:231], s[36:37], 0, v[142:143]
	s_mov_b32 m0, s73
	s_nop 0
	global_load_lds_dwordx4 v[230:231], off
	s_cmp_eq_u32 s97, 4
	s_cbranch_scc1 .Lengw3_c
	s_cmp_eq_u32 s97, 8
	s_cbranch_scc1 .Lengw3_d
	s_waitcnt vmcnt(8)
	s_branch .Lengw3_e

; #define PG8_STAGE(bufoff, gbase, voff) do { _Pragma("unroll") for (int _i = 0; _i < 2; ++_i) \
;         __builtin_amdgcn_global_load_lds((const unsigned*)((const char*)(gbase) + (voff)[_i]), (PG8_LAS unsigned*)(lds + (bufoff) + ldsw + _i * 8192), 16, 0, 0); } while (0)
; #define PG8_LDA(dst, b, h) do { _Pragma("unroll") for (int m = 0; m < 4; ++m) _Pragma("unroll") for (int k = 0; k < 2; ++k) dst[m][k] = *(const PG8_LAS bf16x8*)(lds + PG8_SA(b, h) + aoff + m * 2048 + k * 1024); } while (0)
; #define PG8_MMA(ai, bj, At, Bt) do { __builtin_amdgcn_s_setprio(3); _Pragma("unroll") for (int m = 0; m < 4; ++m) _Pragma("unroll") for (int n = 0; n < 2; ++n) _Pragma("unroll") for (int k = 0; k < 2; ++k) \
;         acc[ai][bj][m][n] = __builtin_amdgcn_mfma_f32_16x16x32_bf16(Bt[n][k], At[m][k], acc[ai][bj][m][n], 0, 0, 0); __builtin_amdgcn_s_setprio(0); } while (0)
; #define PG8_WAIT_V(n) asm volatile("s_waitcnt vmcnt(" #n ")" ::: "memory")
; #define PG8_WAIT_L(n) asm volatile("s_waitcnt lgkmcnt(" #n ")" ::: "memory")
; #define PG8_BAR __builtin_amdgcn_s_barrier()
; #define PG8_SCHED __builtin_amdgcn_sched_barrier(0)
; template <class Epi, class Sched, bool ALIGN_EPI = false, bool SP2 = false>
; __device__ __forceinline__ void gemm_phase(PG8_LAS unsigned char* lds, const Gemm g, const Sched& S, const Epi& E) {
;     ...
;             PG8_WAIT_V(8); PG8_WAIT_L(0); PG8_BAR; PG8_MMA(0, 0, At, B0); PG8_MMA(0, 1, At, B1); PG8_BAR; PG8_SCHED;
;             PG8_LDA(At, 1, 1); PG8_STAGE(PG8_SB(1, 0), b3, voffB); PG8_STAGE(PG8_SB(1, 1), b3 + hstepB, voffB); PG8_STAGE(PG8_SA(1, 0), a3, voffA);
;             PG8_WAIT_V(8); PG8_WAIT_L(0); PG8_BAR; PG8_MMA(1, 0, At, B0); PG8_MMA(1, 1, At, B1); PG8_BAR; PG8_SCHED;
;     ...
;         if constexpr (ALIGN_EPI) { if (wr == 0) PG8_BAR; }
;         if constexpr (!Epi::AFTER_DRAIN) { E(acc, cur, wr, wc, fr, fq); S.done(cur); }
.Lengw3_e:
	s_waitcnt lgkmcnt(0)
	s_barrier
	s_setprio 3
	s_waitcnt lgkmcnt(0)
	v_mfma_f32_16x16x32_bf16 v[126:129], v[130:133], v[192:195], v[126:129]
	v_mfma_f32_16x16x32_bf16 v[126:129], v[134:137], v[196:199], v[126:129]
	v_mfma_f32_16x16x32_bf16 v[118:121], v[156:159], v[192:195], v[118:121]
	v_mfma_f32_16x16x32_bf16 v[118:121], v[172:175], v[196:199], v[118:121]
	v_mfma_f32_16x16x32_bf16 v[102:105], v[156:159], v[200:203], v[102:105]
	v_mfma_f32_16x16x32_bf16 v[102:105], v[172:175], v[204:207], v[102:105]
	v_mfma_f32_16x16x32_bf16 v[110:113], v[130:133], v[200:203], v[110:113]
	v_mfma_f32_16x16x32_bf16 v[110:113], v[134:137], v[204:207], v[110:113]
	v_mfma_f32_16x16x32_bf16 v[94:97], v[130:133], v[208:211], v[94:97]
	v_mfma_f32_16x16x32_bf16 v[94:97], v[134:137], v[212:215], v[94:97]
	v_mfma_f32_16x16x32_bf16 v[86:89], v[156:159], v[208:211], v[86:89]
	v_mfma_f32_16x16x32_bf16 v[86:89], v[172:175], v[212:215], v[86:89]
	v_mfma_f32_16x16x32_bf16 v[70:73], v[156:159], v[216:219], v[70:73]
	v_mfma_f32_16x16x32_bf16 v[70:73], v[172:175], v[220:223], v[70:73]
	v_mfma_f32_16x16x32_bf16 v[78:81], v[130:133], v[216:219], v[78:81]
	v_mfma_f32_16x16x32_bf16 v[78:81], v[134:137], v[220:223], v[78:81]
	v_mfma_f32_16x16x32_bf16 v[122:125], v[176:179], v[192:195], v[122:125]
	v_mfma_f32_16x16x32_bf16 v[122:125], v[180:183], v[196:199], v[122:125]
	v_mfma_f32_16x16x32_bf16 v[114:117], v[184:187], v[192:195], v[114:117]
	v_mfma_f32_16x16x32_bf16 v[114:117], v[188:191], v[196:199], v[114:117]
	v_mfma_f32_16x16x32_bf16 v[98:101], v[184:187], v[200:203], v[98:101]
	v_mfma_f32_16x16x32_bf16 v[98:101], v[188:191], v[204:207], v[98:101]
	v_mfma_f32_16x16x32_bf16 v[106:109], v[176:179], v[200:203], v[106:109]
	v_mfma_f32_16x16x32_bf16 v[106:109], v[180:183], v[204:207], v[106:109]
	v_mfma_f32_16x16x32_bf16 v[90:93], v[176:179], v[208:211], v[90:93]
	v_mfma_f32_16x16x32_bf16 v[90:93], v[180:183], v[212:215], v[90:93]
	v_mfma_f32_16x16x32_bf16 v[82:85], v[184:187], v[208:211], v[82:85]
	v_mfma_f32_16x16x32_bf16 v[82:85], v[188:191], v[212:215], v[82:85]
	v_mfma_f32_16x16x32_bf16 v[66:69], v[184:187], v[216:219], v[66:69]
	v_mfma_f32_16x16x32_bf16 v[66:69], v[188:191], v[220:223], v[66:69]
	v_mfma_f32_16x16x32_bf16 v[74:77], v[176:179], v[216:219], v[74:77]
	v_mfma_f32_16x16x32_bf16 v[74:77], v[180:183], v[220:223], v[74:77]
	s_setprio 0
	s_barrier
	s_add_i32 s36, s56, s66
	v_lshl_add_u64 v[160:161], v[160:161], 0, s[18:19]
	s_mov_b32 m0, s36
	ds_read_b128 v[192:195], v169 offset:49152
	ds_read_b128 v[196:199], v169 offset:50176
	ds_read_b128 v[200:203], v169 offset:51200
	ds_read_b128 v[204:207], v169 offset:52224
	ds_read_b128 v[208:211], v169 offset:53248
	ds_read_b128 v[212:215], v169 offset:54272
	ds_read_b128 v[216:219], v169 offset:55296
	ds_read_b128 v[220:223], v169 offset:56320
	global_load_lds_dwordx4 v[160:161], off
	s_add_i32 m0, s36, 0x2000
	s_add_u32 s8, s8, 0x100080
	v_lshl_add_u64 v[160:161], v[224:225], 0, s[18:19]
	s_addc_u32 s9, s9, 0
	s_add_i32 s36, s57, s66
	global_load_lds_dwordx4 v[160:161], off
	v_lshl_add_u64 v[160:161], s[8:9], 0, v[140:141]
	s_mov_b32 m0, s36
	s_nop 0
	global_load_lds_dwordx4 v[160:161], off
	v_lshl_add_u64 v[160:161], s[8:9], 0, v[144:145]
	s_add_i32 m0, s36, 0x2000
	s_nop 0
	global_load_lds_dwordx4 v[160:161], off
	v_lshl_add_u64 v[160:161], v[226:227], 0, s[18:19]
	s_mov_b32 m0, s75
	s_nop 0
	global_load_lds_dwordx4 v[160:161], off
	v_lshl_add_u64 v[160:161], v[228:229], 0, s[18:19]
	s_mov_b32 m0, s76
	s_nop 0
	global_load_lds_dwordx4 v[160:161], off
	s_waitcnt vmcnt(8)
	s_waitcnt lgkmcnt(0)
	s_barrier
	s_setprio 3
	s_waitcnt lgkmcnt(0)
	v_mfma_f32_16x16x32_bf16 v[62:65], v[130:133], v[192:195], v[62:65]
	v_mfma_f32_16x16x32_bf16 v[62:65], v[134:137], v[196:199], v[62:65]
	v_mfma_f32_16x16x32_bf16 v[54:57], v[156:159], v[192:195], v[54:57]
	v_mfma_f32_16x16x32_bf16 v[54:57], v[172:175], v[196:199], v[54:57]
	v_mfma_f32_16x16x32_bf16 v[38:41], v[156:159], v[200:203], v[38:41]
	v_mfma_f32_16x16x32_bf16 v[38:41], v[172:175], v[204:207], v[38:41]
	v_mfma_f32_16x16x32_bf16 v[46:49], v[130:133], v[200:203], v[46:49]
	v_mfma_f32_16x16x32_bf16 v[46:49], v[134:137], v[204:207], v[46:49]
	v_mfma_f32_16x16x32_bf16 v[30:33], v[130:133], v[208:211], v[30:33]
	v_mfma_f32_16x16x32_bf16 v[30:33], v[134:137], v[212:215], v[30:33]
	v_mfma_f32_16x16x32_bf16 v[22:25], v[156:159], v[208:211], v[22:25]
	v_mfma_f32_16x16x32_bf16 v[22:25], v[172:175], v[212:215], v[22:25]
	v_mfma_f32_16x16x32_bf16 v[6:9], v[156:159], v[216:219], v[6:9]
	v_mfma_f32_16x16x32_bf16 v[6:9], v[172:175], v[220:223], v[6:9]
	v_mfma_f32_16x16x32_bf16 v[14:17], v[130:133], v[216:219], v[14:17]
	v_mfma_f32_16x16x32_bf16 v[14:17], v[134:137], v[220:223], v[14:17]
	v_mfma_f32_16x16x32_bf16 v[58:61], v[176:179], v[192:195], v[58:61]
	v_mfma_f32_16x16x32_bf16 v[58:61], v[180:183], v[196:199], v[58:61]
	v_mfma_f32_16x16x32_bf16 v[50:53], v[184:187], v[192:195], v[50:53]
	v_mfma_f32_16x16x32_bf16 v[50:53], v[188:191], v[196:199], v[50:53]
	v_mfma_f32_16x16x32_bf16 v[34:37], v[184:187], v[200:203], v[34:37]
	v_mfma_f32_16x16x32_bf16 v[34:37], v[188:191], v[204:207], v[34:37]
	v_mfma_f32_16x16x32_bf16 v[42:45], v[176:179], v[200:203], v[42:45]
	v_mfma_f32_16x16x32_bf16 v[42:45], v[180:183], v[204:207], v[42:45]
	v_mfma_f32_16x16x32_bf16 v[26:29], v[176:179], v[208:211], v[26:29]
	v_mfma_f32_16x16x32_bf16 v[26:29], v[180:183], v[212:215], v[26:29]
	v_mfma_f32_16x16x32_bf16 v[18:21], v[184:187], v[208:211], v[18:21]
	v_mfma_f32_16x16x32_bf16 v[18:21], v[188:191], v[212:215], v[18:21]
	v_mfma_f32_16x16x32_bf16 v[2:5], v[184:187], v[216:219], v[2:5]
	v_mfma_f32_16x16x32_bf16 v[2:5], v[188:191], v[220:223], v[2:5]
	v_mfma_f32_16x16x32_bf16 v[10:13], v[176:179], v[216:219], v[10:13]
	v_mfma_f32_16x16x32_bf16 v[10:13], v[180:183], v[220:223], v[10:13]
	s_setprio 0
	s_barrier
	s_add_i32 s45, s45, 2
	s_add_u32 s6, s6, 0x100
	s_addc_u32 s7, s7, 0
	s_add_u32 s33, s33, 0x100
	s_addc_u32 s44, s44, 0
	s_cmp_gt_u32 s45, 61
	s_cbranch_scc0 .LBB0_143
	s_and_b64 vcc, exec, s[20:21]
	s_cbranch_vccz .LBB0_148
	s_barrier
	v_lshl_add_u32 v156, s0, 8, v163
	s_cmp_lt_i32 s54, 40
	s_mov_b64 s[0:1], -1
	s_cbranch_scc1 .LBB0_149

; #define PG8_STAGE(bufoff, gbase, voff) do { _Pragma("unroll") for (int _i = 0; _i < 2; ++_i) \
;         __builtin_amdgcn_global_load_lds((const unsigned*)((const char*)(gbase) + (voff)[_i]), (PG8_LAS unsigned*)(lds + (bufoff) + ldsw + _i * 8192), 16, 0, 0); } while (0)
; #define PG8_LDA(dst, b, h) do { _Pragma("unroll") for (int m = 0; m < 4; ++m) _Pragma("unroll") for (int k = 0; k < 2; ++k) dst[m][k] = *(const PG8_LAS bf16x8*)(lds + PG8_SA(b, h) + aoff + m * 2048 + k * 1024); } while (0)
; #define PG8_LDB(dst, b, h) do { _Pragma("unroll") for (int n = 0; n < 2; ++n) _Pragma("unroll") for (int k = 0; k < 2; ++k) dst[n][k] = *(const PG8_LAS bf16x8*)(lds + PG8_SB(b, h) + boff + n * 2048 + k * 1024); } while (0)
; #define PG8_MMA(ai, bj, At, Bt) do { __builtin_amdgcn_s_setprio(3); _Pragma("unroll") for (int m = 0; m < 4; ++m) _Pragma("unroll") for (int n = 0; n < 2; ++n) _Pragma("unroll") for (int k = 0; k < 2; ++k) \
;         acc[ai][bj][m][n] = __builtin_amdgcn_mfma_f32_16x16x32_bf16(Bt[n][k], At[m][k], acc[ai][bj][m][n], 0, 0, 0); __builtin_amdgcn_s_setprio(0); } while (0)
; #define PG8_WAIT_V(n) asm volatile("s_waitcnt vmcnt(" #n ")" ::: "memory")
; #define PG8_WAIT_L(n) asm volatile("s_waitcnt lgkmcnt(" #n ")" ::: "memory")
; template <class Epi, class Sched, bool ALIGN_EPI = false, bool SP2 = false>
; __device__ __forceinline__ void gemm_phase(PG8_LAS unsigned char* lds, const Gemm g, const Sched& S, const Epi& E) {
;     ...
;         for (int t = 0; t < nt; t += 2) {
;             const bool last = (t == nt - 2);
;             const char* a1 = cA + (size_t)(t + 1) * kstep;
;             const char* a2 = last ? nA : cA + (size_t)(t + 2) * kstep; const char* b2 = last ? nB : cB + (size_t)(t + 2) * kstep;
;             const char* a3 = a2 + kstep; const char* b3 = b2 + kstep;
;             if (last && has_next) S.a_ready(nxt);
;             if constexpr (Epi::MIDK) { if (t == E.midk_step(nt)) E.midk(acc, cur, wr, wc, fr, fq); }
;             if constexpr (SP2) {
;             PG8_LDB(B0, 0, 0); PG8_LDB(B1, 0, 1); PG8_SCHED; PG8_LDA(At, 0, 0); PG8_STAGE(PG8_SA(1, 1), a1 + hstepA, voffA);
;             PG8_WAIT_V(8); PG8_WAIT_L(0); PG8_BAR; PG8_MMA(0, 0, At, B0); PG8_MMA(0, 1, At, B1); PG8_BAR; PG8_SCHED;
;             PG8_LDA(At, 0, 1); PG8_STAGE(PG8_SB(0, 0), b2, voffB); PG8_STAGE(PG8_SB(0, 1), b2 + hstepB, voffB); PG8_STAGE(PG8_SA(0, 0), a2, voffA);
.LBB0_478:
	ds_read_b128 v[130:133], v170
	ds_read_b128 v[134:137], v170 offset:1024
	ds_read_b128 v[138:141], v170 offset:2048
	ds_read_b128 v[142:145], v170 offset:3072
	ds_read_b128 v[164:167], v171
	ds_read_b128 v[174:177], v171 offset:1024
	ds_read_b128 v[178:181], v171 offset:2048
	ds_read_b128 v[182:185], v171 offset:3072
	s_add_u32 s36, s6, 0xfff80080
	s_addc_u32 s37, s7, -1
	s_cmp_eq_u32 s79, 4
	s_cselect_b32 s59, s27, s37
	s_cselect_b32 s58, s26, s36
	s_cselect_b32 s37, s23, s78
	s_cselect_b32 s36, s25, s77
	v_lshl_add_u64 v[218:219], s[6:7], 0, v[154:155]
	s_add_i32 m0, s31, 0xc000
	ds_read_b128 v[186:189], v172
	ds_read_b128 v[190:193], v172 offset:1024
	ds_read_b128 v[194:197], v172 offset:2048
	ds_read_b128 v[198:201], v172 offset:3072
	ds_read_b128 v[202:205], v172 offset:4096
	ds_read_b128 v[206:209], v172 offset:5120
	ds_read_b128 v[210:213], v172 offset:6144
	ds_read_b128 v[214:217], v172 offset:7168
	global_load_lds_dwordx4 v[218:219], off
	v_lshl_add_u64 v[218:219], s[6:7], 0, v[156:157]
	s_add_i32 m0, s31, 0xe000
	s_nop 0
	global_load_lds_dwordx4 v[218:219], off
	s_waitcnt vmcnt(8)
	s_waitcnt lgkmcnt(0)
	s_barrier
	s_setprio 3
	s_waitcnt lgkmcnt(0)
	v_mfma_f32_16x16x32_bf16 v[126:129], v[130:133], v[186:189], v[126:129]
	v_mfma_f32_16x16x32_bf16 v[126:129], v[134:137], v[190:193], v[126:129]
	v_mfma_f32_16x16x32_bf16 v[122:125], v[138:141], v[186:189], v[122:125]
	v_mfma_f32_16x16x32_bf16 v[122:125], v[142:145], v[190:193], v[122:125]
	v_mfma_f32_16x16x32_bf16 v[114:117], v[138:141], v[194:197], v[114:117]
	v_mfma_f32_16x16x32_bf16 v[114:117], v[142:145], v[198:201], v[114:117]
	v_mfma_f32_16x16x32_bf16 v[118:121], v[130:133], v[194:197], v[118:121]
	v_mfma_f32_16x16x32_bf16 v[118:121], v[134:137], v[198:201], v[118:121]
	v_mfma_f32_16x16x32_bf16 v[110:113], v[130:133], v[202:205], v[110:113]
	v_mfma_f32_16x16x32_bf16 v[110:113], v[134:137], v[206:209], v[110:113]
	v_mfma_f32_16x16x32_bf16 v[102:105], v[138:141], v[202:205], v[102:105]
	v_mfma_f32_16x16x32_bf16 v[102:105], v[142:145], v[206:209], v[102:105]
	v_mfma_f32_16x16x32_bf16 v[74:77], v[138:141], v[210:213], v[74:77]
	v_mfma_f32_16x16x32_bf16 v[74:77], v[142:145], v[214:217], v[74:77]
	v_mfma_f32_16x16x32_bf16 v[78:81], v[130:133], v[210:213], v[78:81]
	v_mfma_f32_16x16x32_bf16 v[78:81], v[134:137], v[214:217], v[78:81]
	v_mfma_f32_16x16x32_bf16 v[106:109], v[164:167], v[186:189], v[106:109]
	v_mfma_f32_16x16x32_bf16 v[106:109], v[174:177], v[190:193], v[106:109]
	v_mfma_f32_16x16x32_bf16 v[98:101], v[178:181], v[186:189], v[98:101]
	v_mfma_f32_16x16x32_bf16 v[98:101], v[182:185], v[190:193], v[98:101]
	v_mfma_f32_16x16x32_bf16 v[90:93], v[178:181], v[194:197], v[90:93]
	v_mfma_f32_16x16x32_bf16 v[90:93], v[182:185], v[198:201], v[90:93]
	v_mfma_f32_16x16x32_bf16 v[94:97], v[164:167], v[194:197], v[94:97]
	v_mfma_f32_16x16x32_bf16 v[94:97], v[174:177], v[198:201], v[94:97]
	v_mfma_f32_16x16x32_bf16 v[86:89], v[164:167], v[202:205], v[86:89]
	v_mfma_f32_16x16x32_bf16 v[86:89], v[174:177], v[206:209], v[86:89]
	v_mfma_f32_16x16x32_bf16 v[82:85], v[178:181], v[202:205], v[82:85]
	v_mfma_f32_16x16x32_bf16 v[82:85], v[182:185], v[206:209], v[82:85]
	v_mfma_f32_16x16x32_bf16 v[66:69], v[178:181], v[210:213], v[66:69]
	v_mfma_f32_16x16x32_bf16 v[66:69], v[182:185], v[214:217], v[66:69]
	v_mfma_f32_16x16x32_bf16 v[70:73], v[164:167], v[210:213], v[70:73]
	v_mfma_f32_16x16x32_bf16 v[70:73], v[174:177], v[214:217], v[70:73]
	s_setprio 0
	s_barrier
	s_add_i32 s83, s72, s44
	v_lshl_add_u64 v[218:219], s[36:37], 0, v[148:149]
	s_mov_b32 m0, s83
	ds_read_b128 v[186:189], v172 offset:16384
	ds_read_b128 v[190:193], v172 offset:17408
	ds_read_b128 v[194:197], v172 offset:18432
	ds_read_b128 v[198:201], v172 offset:19456
	ds_read_b128 v[202:205], v172 offset:20480
	ds_read_b128 v[206:209], v172 offset:21504
	ds_read_b128 v[210:213], v172 offset:22528
	ds_read_b128 v[214:217], v172 offset:23552
	global_load_lds_dwordx4 v[218:219], off
	s_add_i32 m0, s83, 0x2000
	s_add_u32 s84, s36, 0x20000
	v_lshl_add_u64 v[220:221], s[36:37], 0, v[152:153]
	s_addc_u32 s85, s37, 0
	s_add_i32 s83, s73, s44
	global_load_lds_dwordx4 v[220:221], off
	v_lshl_add_u64 v[222:223], s[84:85], 0, v[148:149]
	s_mov_b32 m0, s83
	v_lshl_add_u64 v[224:225], s[58:59], 0, v[150:151]
	global_load_lds_dwordx4 v[222:223], off
	v_lshl_add_u64 v[222:223], s[84:85], 0, v[152:153]
	s_add_i32 m0, s83, 0x2000
	s_nop 0
	global_load_lds_dwordx4 v[222:223], off
	v_lshl_add_u64 v[222:223], s[58:59], 0, v[146:147]
	s_mov_b32 m0, s31
	s_nop 0
	global_load_lds_dwordx4 v[222:223], off
	s_mov_b32 m0, s45
	s_nop 0
	global_load_lds_dwordx4 v[224:225], off
	s_waitcnt vmcnt(8)
	s_waitcnt lgkmcnt(0)
	s_barrier
; #define PG8_STAGE(bufoff, gbase, voff) do { _Pragma("unroll") for (int _i = 0; _i < 2; ++_i) \
;         __builtin_amdgcn_global_load_lds((const unsigned*)((const char*)(gbase) + (voff)[_i]), (PG8_LAS unsigned*)(lds + (bufoff) + ldsw + _i * 8192), 16, 0, 0); } while (0)
; #define PG8_LDA(dst, b, h) do { _Pragma("unroll") for (int m = 0; m < 4; ++m) _Pragma("unroll") for (int k = 0; k < 2; ++k) dst[m][k] = *(const PG8_LAS bf16x8*)(lds + PG8_SA(b, h) + aoff + m * 2048 + k * 1024); } while (0)
; #define PG8_LDB(dst, b, h) do { _Pragma("unroll") for (int n = 0; n < 2; ++n) _Pragma("unroll") for (int k = 0; k < 2; ++k) dst[n][k] = *(const PG8_LAS bf16x8*)(lds + PG8_SB(b, h) + boff + n * 2048 + k * 1024); } while (0)
; #define PG8_MMA(ai, bj, At, Bt) do { __builtin_amdgcn_s_setprio(3); _Pragma("unroll") for (int m = 0; m < 4; ++m) _Pragma("unroll") for (int n = 0; n < 2; ++n) _Pragma("unroll") for (int k = 0; k < 2; ++k) \
;         acc[ai][bj][m][n] = __builtin_amdgcn_mfma_f32_16x16x32_bf16(Bt[n][k], At[m][k], acc[ai][bj][m][n], 0, 0, 0); __builtin_amdgcn_s_setprio(0); } while (0)
; #define PG8_WAIT_V(n) asm volatile("s_waitcnt vmcnt(" #n ")" ::: "memory")
; #define PG8_WAIT_L(n) asm volatile("s_waitcnt lgkmcnt(" #n ")" ::: "memory")
; #define PG8_BAR __builtin_amdgcn_s_barrier()
; #define PG8_SCHED __builtin_amdgcn_sched_barrier(0)
; template <class Epi, class Sched, bool ALIGN_EPI = false, bool SP2 = false>
; __device__ __forceinline__ void gemm_phase(PG8_LAS unsigned char* lds, const Gemm g, const Sched& S, const Epi& E) {
;     ...
;             PG8_WAIT_V(8); PG8_WAIT_L(0); PG8_BAR; PG8_MMA(1, 0, At, B0); PG8_MMA(1, 1, At, B1); PG8_BAR; PG8_SCHED;
;             PG8_LDB(B0, 1, 0); PG8_LDB(B1, 1, 1); PG8_SCHED; PG8_LDA(At, 1, 0); PG8_STAGE(PG8_SA(0, 1), a2 + hstepA, voffA);
;             PG8_WAIT_V(8); PG8_WAIT_L(0); PG8_BAR; PG8_MMA(0, 0, At, B0); PG8_MMA(0, 1, At, B1); PG8_BAR; PG8_SCHED;
	s_setprio 3
	s_waitcnt lgkmcnt(0)
	v_mfma_f32_16x16x32_bf16 v[62:65], v[130:133], v[186:189], v[62:65]
	v_mfma_f32_16x16x32_bf16 v[62:65], v[134:137], v[190:193], v[62:65]
	v_mfma_f32_16x16x32_bf16 v[58:61], v[138:141], v[186:189], v[58:61]
	v_mfma_f32_16x16x32_bf16 v[58:61], v[142:145], v[190:193], v[58:61]
	v_mfma_f32_16x16x32_bf16 v[46:49], v[138:141], v[194:197], v[46:49]
	v_mfma_f32_16x16x32_bf16 v[46:49], v[142:145], v[198:201], v[46:49]
	v_mfma_f32_16x16x32_bf16 v[54:57], v[130:133], v[194:197], v[54:57]
	v_mfma_f32_16x16x32_bf16 v[54:57], v[134:137], v[198:201], v[54:57]
	v_mfma_f32_16x16x32_bf16 v[38:41], v[130:133], v[202:205], v[38:41]
	v_mfma_f32_16x16x32_bf16 v[38:41], v[134:137], v[206:209], v[38:41]
	v_mfma_f32_16x16x32_bf16 v[30:33], v[138:141], v[202:205], v[30:33]
	v_mfma_f32_16x16x32_bf16 v[30:33], v[142:145], v[206:209], v[30:33]
	v_mfma_f32_16x16x32_bf16 v[14:17], v[138:141], v[210:213], v[14:17]
	v_mfma_f32_16x16x32_bf16 v[14:17], v[142:145], v[214:217], v[14:17]
	v_mfma_f32_16x16x32_bf16 v[22:25], v[130:133], v[210:213], v[22:25]
	v_mfma_f32_16x16x32_bf16 v[22:25], v[134:137], v[214:217], v[22:25]
	v_mfma_f32_16x16x32_bf16 v[50:53], v[164:167], v[186:189], v[50:53]
	v_mfma_f32_16x16x32_bf16 v[50:53], v[174:177], v[190:193], v[50:53]
	v_mfma_f32_16x16x32_bf16 v[42:45], v[178:181], v[186:189], v[42:45]
	v_mfma_f32_16x16x32_bf16 v[42:45], v[182:185], v[190:193], v[42:45]
	v_mfma_f32_16x16x32_bf16 v[26:29], v[178:181], v[194:197], v[26:29]
	v_mfma_f32_16x16x32_bf16 v[26:29], v[182:185], v[198:201], v[26:29]
	v_mfma_f32_16x16x32_bf16 v[34:37], v[164:167], v[194:197], v[34:37]
	v_mfma_f32_16x16x32_bf16 v[34:37], v[174:177], v[198:201], v[34:37]
	v_mfma_f32_16x16x32_bf16 v[18:21], v[164:167], v[202:205], v[18:21]
	v_mfma_f32_16x16x32_bf16 v[18:21], v[174:177], v[206:209], v[18:21]
	v_mfma_f32_16x16x32_bf16 v[10:13], v[178:181], v[202:205], v[10:13]
	v_mfma_f32_16x16x32_bf16 v[10:13], v[182:185], v[206:209], v[10:13]
	v_mfma_f32_16x16x32_bf16 v[2:5], v[178:181], v[210:213], v[2:5]
	v_mfma_f32_16x16x32_bf16 v[2:5], v[182:185], v[214:217], v[2:5]
	v_mfma_f32_16x16x32_bf16 v[6:9], v[164:167], v[210:213], v[6:9]
	v_mfma_f32_16x16x32_bf16 v[6:9], v[174:177], v[214:217], v[6:9]
	s_setprio 0
	s_barrier
	s_add_i32 s83, 0, 0x18000
	s_add_i32 s84, 0, 0x1c000
	v_add_u32_e32 v142, s83, v168
	v_add_u32_e32 v173, s84, v168
	ds_read_b128 v[130:133], v142
	ds_read_b128 v[134:137], v142 offset:1024
	ds_read_b128 v[138:141], v142 offset:2048
	ds_read_b128 v[142:145], v142 offset:3072
	ds_read_b128 v[164:167], v173
	ds_read_b128 v[174:177], v173 offset:1024
	ds_read_b128 v[178:181], v173 offset:2048
	ds_read_b128 v[182:185], v173 offset:3072
	s_add_u32 s58, s58, 0x80000
	s_addc_u32 s59, s59, 0
	s_mov_b32 m0, s54
	v_lshl_add_u64 v[226:227], s[58:59], 0, v[146:147]
	ds_read_b128 v[186:189], v172 offset:32768
	ds_read_b128 v[190:193], v172 offset:33792
	ds_read_b128 v[194:197], v172 offset:34816
	ds_read_b128 v[198:201], v172 offset:35840
	ds_read_b128 v[202:205], v172 offset:36864
	ds_read_b128 v[206:209], v172 offset:37888
	ds_read_b128 v[210:213], v172 offset:38912
	ds_read_b128 v[214:217], v172 offset:39936
	global_load_lds_dwordx4 v[226:227], off
	v_lshl_add_u64 v[226:227], s[58:59], 0, v[150:151]
	s_mov_b32 m0, s55
	s_nop 0
	global_load_lds_dwordx4 v[226:227], off
	s_waitcnt vmcnt(8)
	s_waitcnt lgkmcnt(0)
	s_barrier
	s_setprio 3
	s_waitcnt lgkmcnt(0)
	v_mfma_f32_16x16x32_bf16 v[126:129], v[130:133], v[186:189], v[126:129]
	v_mfma_f32_16x16x32_bf16 v[126:129], v[134:137], v[190:193], v[126:129]
	v_mfma_f32_16x16x32_bf16 v[122:125], v[138:141], v[186:189], v[122:125]
	v_mfma_f32_16x16x32_bf16 v[122:125], v[142:145], v[190:193], v[122:125]
	v_mfma_f32_16x16x32_bf16 v[114:117], v[138:141], v[194:197], v[114:117]
	v_mfma_f32_16x16x32_bf16 v[114:117], v[142:145], v[198:201], v[114:117]
	v_mfma_f32_16x16x32_bf16 v[118:121], v[130:133], v[194:197], v[118:121]
	v_mfma_f32_16x16x32_bf16 v[118:121], v[134:137], v[198:201], v[118:121]
	v_mfma_f32_16x16x32_bf16 v[110:113], v[130:133], v[202:205], v[110:113]
	v_mfma_f32_16x16x32_bf16 v[110:113], v[134:137], v[206:209], v[110:113]
	v_mfma_f32_16x16x32_bf16 v[102:105], v[138:141], v[202:205], v[102:105]
	v_mfma_f32_16x16x32_bf16 v[102:105], v[142:145], v[206:209], v[102:105]
	v_mfma_f32_16x16x32_bf16 v[74:77], v[138:141], v[210:213], v[74:77]
	v_mfma_f32_16x16x32_bf16 v[74:77], v[142:145], v[214:217], v[74:77]
	v_mfma_f32_16x16x32_bf16 v[78:81], v[130:133], v[210:213], v[78:81]
	v_mfma_f32_16x16x32_bf16 v[78:81], v[134:137], v[214:217], v[78:81]
	v_mfma_f32_16x16x32_bf16 v[106:109], v[164:167], v[186:189], v[106:109]
	v_mfma_f32_16x16x32_bf16 v[106:109], v[174:177], v[190:193], v[106:109]
	v_mfma_f32_16x16x32_bf16 v[98:101], v[178:181], v[186:189], v[98:101]
	v_mfma_f32_16x16x32_bf16 v[98:101], v[182:185], v[190:193], v[98:101]
	v_mfma_f32_16x16x32_bf16 v[90:93], v[178:181], v[194:197], v[90:93]
	v_mfma_f32_16x16x32_bf16 v[90:93], v[182:185], v[198:201], v[90:93]
	v_mfma_f32_16x16x32_bf16 v[94:97], v[164:167], v[194:197], v[94:97]
	v_mfma_f32_16x16x32_bf16 v[94:97], v[174:177], v[198:201], v[94:97]
	v_mfma_f32_16x16x32_bf16 v[86:89], v[164:167], v[202:205], v[86:89]
	v_mfma_f32_16x16x32_bf16 v[86:89], v[174:177], v[206:209], v[86:89]
	v_mfma_f32_16x16x32_bf16 v[82:85], v[178:181], v[202:205], v[82:85]
	v_mfma_f32_16x16x32_bf16 v[82:85], v[182:185], v[206:209], v[82:85]
	v_mfma_f32_16x16x32_bf16 v[66:69], v[178:181], v[210:213], v[66:69]
	v_mfma_f32_16x16x32_bf16 v[66:69], v[182:185], v[214:217], v[66:69]
	v_mfma_f32_16x16x32_bf16 v[70:73], v[164:167], v[210:213], v[70:73]
	v_mfma_f32_16x16x32_bf16 v[70:73], v[174:177], v[214:217], v[70:73]
	s_setprio 0
	s_barrier
; #define PG8_STAGE(bufoff, gbase, voff) do { _Pragma("unroll") for (int _i = 0; _i < 2; ++_i) \
;         __builtin_amdgcn_global_load_lds((const unsigned*)((const char*)(gbase) + (voff)[_i]), (PG8_LAS unsigned*)(lds + (bufoff) + ldsw + _i * 8192), 16, 0, 0); } while (0)
; #define PG8_LDA(dst, b, h) do { _Pragma("unroll") for (int m = 0; m < 4; ++m) _Pragma("unroll") for (int k = 0; k < 2; ++k) dst[m][k] = *(const PG8_LAS bf16x8*)(lds + PG8_SA(b, h) + aoff + m * 2048 + k * 1024); } while (0)
; #define PG8_MMA(ai, bj, At, Bt) do { __builtin_amdgcn_s_setprio(3); _Pragma("unroll") for (int m = 0; m < 4; ++m) _Pragma("unroll") for (int n = 0; n < 2; ++n) _Pragma("unroll") for (int k = 0; k < 2; ++k) \
;         acc[ai][bj][m][n] = __builtin_amdgcn_mfma_f32_16x16x32_bf16(Bt[n][k], At[m][k], acc[ai][bj][m][n], 0, 0, 0); __builtin_amdgcn_s_setprio(0); } while (0)
; #define PG8_WAIT_V(n) asm volatile("s_waitcnt vmcnt(" #n ")" ::: "memory")
; #define PG8_WAIT_L(n) asm volatile("s_waitcnt lgkmcnt(" #n ")" ::: "memory")
; #define PG8_BAR __builtin_amdgcn_s_barrier()
; #define PG8_SCHED __builtin_amdgcn_sched_barrier(0)
; template <class Epi, class Sched, bool ALIGN_EPI = false, bool SP2 = false>
; __device__ __forceinline__ void gemm_phase(PG8_LAS unsigned char* lds, const Gemm g, const Sched& S, const Epi& E) {
;     ...
;             PG8_LDA(At, 1, 1); PG8_STAGE(PG8_SB(1, 0), b3, voffB); PG8_STAGE(PG8_SB(1, 1), b3 + hstepB, voffB); PG8_STAGE(PG8_SA(1, 0), a3, voffA);
;             PG8_WAIT_V(8); PG8_WAIT_L(0); PG8_BAR; PG8_MMA(1, 0, At, B0); PG8_MMA(1, 1, At, B1); PG8_BAR; PG8_SCHED;
;     ...
;         if constexpr (ALIGN_EPI) { if (wr == 0) PG8_BAR; }
	s_add_i32 s58, s83, s44
	v_lshl_add_u64 v[218:219], v[218:219], 0, s[18:19]
	s_mov_b32 m0, s58
	ds_read_b128 v[186:189], v172 offset:49152
	ds_read_b128 v[190:193], v172 offset:50176
	ds_read_b128 v[194:197], v172 offset:51200
	ds_read_b128 v[198:201], v172 offset:52224
	ds_read_b128 v[202:205], v172 offset:53248
	ds_read_b128 v[206:209], v172 offset:54272
	ds_read_b128 v[210:213], v172 offset:55296
	ds_read_b128 v[214:217], v172 offset:56320
	global_load_lds_dwordx4 v[218:219], off
	s_add_i32 m0, s58, 0x2000
	s_add_u32 s36, s36, 0x20080
	v_lshl_add_u64 v[218:219], v[220:221], 0, s[18:19]
	s_addc_u32 s37, s37, 0
	s_add_i32 s58, s84, s44
	global_load_lds_dwordx4 v[218:219], off
	v_lshl_add_u64 v[218:219], s[36:37], 0, v[148:149]
	s_mov_b32 m0, s58
	s_nop 0
	global_load_lds_dwordx4 v[218:219], off
	v_lshl_add_u64 v[218:219], s[36:37], 0, v[152:153]
	s_add_i32 m0, s58, 0x2000
	s_nop 0
	global_load_lds_dwordx4 v[218:219], off
	v_lshl_add_u64 v[218:219], v[222:223], 0, s[18:19]
	s_mov_b32 m0, s63
	s_nop 0
	global_load_lds_dwordx4 v[218:219], off
	v_lshl_add_u64 v[218:219], v[224:225], 0, s[18:19]
	s_mov_b32 m0, s66
	s_nop 0
	global_load_lds_dwordx4 v[218:219], off
	s_waitcnt vmcnt(8)
	s_waitcnt lgkmcnt(0)
	s_barrier
	s_setprio 3
	s_waitcnt lgkmcnt(0)
	v_mfma_f32_16x16x32_bf16 v[62:65], v[130:133], v[186:189], v[62:65]
	v_mfma_f32_16x16x32_bf16 v[62:65], v[134:137], v[190:193], v[62:65]
	v_mfma_f32_16x16x32_bf16 v[58:61], v[138:141], v[186:189], v[58:61]
	v_mfma_f32_16x16x32_bf16 v[58:61], v[142:145], v[190:193], v[58:61]
	v_mfma_f32_16x16x32_bf16 v[46:49], v[138:141], v[194:197], v[46:49]
	v_mfma_f32_16x16x32_bf16 v[46:49], v[142:145], v[198:201], v[46:49]
	v_mfma_f32_16x16x32_bf16 v[54:57], v[130:133], v[194:197], v[54:57]
	v_mfma_f32_16x16x32_bf16 v[54:57], v[134:137], v[198:201], v[54:57]
	v_mfma_f32_16x16x32_bf16 v[38:41], v[130:133], v[202:205], v[38:41]
	v_mfma_f32_16x16x32_bf16 v[38:41], v[134:137], v[206:209], v[38:41]
	v_mfma_f32_16x16x32_bf16 v[30:33], v[138:141], v[202:205], v[30:33]
	v_mfma_f32_16x16x32_bf16 v[30:33], v[142:145], v[206:209], v[30:33]
	v_mfma_f32_16x16x32_bf16 v[14:17], v[138:141], v[210:213], v[14:17]
	v_mfma_f32_16x16x32_bf16 v[14:17], v[142:145], v[214:217], v[14:17]
	v_mfma_f32_16x16x32_bf16 v[22:25], v[130:133], v[210:213], v[22:25]
	v_mfma_f32_16x16x32_bf16 v[22:25], v[134:137], v[214:217], v[22:25]
	v_mfma_f32_16x16x32_bf16 v[50:53], v[164:167], v[186:189], v[50:53]
	v_mfma_f32_16x16x32_bf16 v[50:53], v[174:177], v[190:193], v[50:53]
	v_mfma_f32_16x16x32_bf16 v[42:45], v[178:181], v[186:189], v[42:45]
	v_mfma_f32_16x16x32_bf16 v[42:45], v[182:185], v[190:193], v[42:45]
	v_mfma_f32_16x16x32_bf16 v[26:29], v[178:181], v[194:197], v[26:29]
	v_mfma_f32_16x16x32_bf16 v[26:29], v[182:185], v[198:201], v[26:29]
	v_mfma_f32_16x16x32_bf16 v[34:37], v[164:167], v[194:197], v[34:37]
	v_mfma_f32_16x16x32_bf16 v[34:37], v[174:177], v[198:201], v[34:37]
	v_mfma_f32_16x16x32_bf16 v[18:21], v[164:167], v[202:205], v[18:21]
	v_mfma_f32_16x16x32_bf16 v[18:21], v[174:177], v[206:209], v[18:21]
	v_mfma_f32_16x16x32_bf16 v[10:13], v[178:181], v[202:205], v[10:13]
	v_mfma_f32_16x16x32_bf16 v[10:13], v[182:185], v[206:209], v[10:13]
	v_mfma_f32_16x16x32_bf16 v[2:5], v[178:181], v[210:213], v[2:5]
	v_mfma_f32_16x16x32_bf16 v[2:5], v[182:185], v[214:217], v[2:5]
	v_mfma_f32_16x16x32_bf16 v[6:9], v[164:167], v[210:213], v[6:9]
	v_mfma_f32_16x16x32_bf16 v[6:9], v[174:177], v[214:217], v[6:9]
	s_setprio 0
	s_barrier
	s_add_i32 s79, s79, 2
	s_add_u32 s6, s6, 0x100
	s_addc_u32 s7, s7, 0
	s_add_u32 s77, s77, 0x100
	s_addc_u32 s78, s78, 0
	s_cmp_gt_u32 s79, 5
	s_cbranch_scc0 .LBB0_478
	s_and_b64 vcc, exec, s[20:21]
	s_cbranch_vccz .LBB0_481
	s_barrier

; #define PG8_STAGE(bufoff, gbase, voff) do { _Pragma("unroll") for (int _i = 0; _i < 2; ++_i) \
;         __builtin_amdgcn_global_load_lds((const unsigned*)((const char*)(gbase) + (voff)[_i]), (PG8_LAS unsigned*)(lds + (bufoff) + ldsw + _i * 8192), 16, 0, 0); } while (0)
; #define PG8_LDA(dst, b, h) do { _Pragma("unroll") for (int m = 0; m < 4; ++m) _Pragma("unroll") for (int k = 0; k < 2; ++k) dst[m][k] = *(const PG8_LAS bf16x8*)(lds + PG8_SA(b, h) + aoff + m * 2048 + k * 1024); } while (0)
; #define PG8_LDB(dst, b, h) do { _Pragma("unroll") for (int n = 0; n < 2; ++n) _Pragma("unroll") for (int k = 0; k < 2; ++k) dst[n][k] = *(const PG8_LAS bf16x8*)(lds + PG8_SB(b, h) + boff + n * 2048 + k * 1024); } while (0)
; #define PG8_MMA(ai, bj, At, Bt) do { __builtin_amdgcn_s_setprio(3); _Pragma("unroll") for (int m = 0; m < 4; ++m) _Pragma("unroll") for (int n = 0; n < 2; ++n) _Pragma("unroll") for (int k = 0; k < 2; ++k) \
;         acc[ai][bj][m][n] = __builtin_amdgcn_mfma_f32_16x16x32_bf16(Bt[n][k], At[m][k], acc[ai][bj][m][n], 0, 0, 0); __builtin_amdgcn_s_setprio(0); } while (0)
; #define PG8_WAIT_V(n) asm volatile("s_waitcnt vmcnt(" #n ")" ::: "memory")
; #define PG8_WAIT_L(n) asm volatile("s_waitcnt lgkmcnt(" #n ")" ::: "memory")
; template <class Epi, class Sched, bool ALIGN_EPI = false, bool SP2 = false>
; __device__ __forceinline__ void gemm_phase(PG8_LAS unsigned char* lds, const Gemm g, const Sched& S, const Epi& E) {
;     ...
;         for (int t = 0; t < nt; t += 2) {
;             const bool last = (t == nt - 2);
;             const char* a1 = cA + (size_t)(t + 1) * kstep;
;             const char* a2 = last ? nA : cA + (size_t)(t + 2) * kstep; const char* b2 = last ? nB : cB + (size_t)(t + 2) * kstep;
;             const char* a3 = a2 + kstep; const char* b3 = b2 + kstep;
;             if (last && has_next) S.a_ready(nxt);
;             if constexpr (Epi::MIDK) { if (t == E.midk_step(nt)) E.midk(acc, cur, wr, wc, fr, fq); }
;             if constexpr (SP2) {
;             PG8_LDB(B0, 0, 0); PG8_LDB(B1, 0, 1); PG8_SCHED; PG8_LDA(At, 0, 0); PG8_STAGE(PG8_SA(1, 1), a1 + hstepA, voffA);
;             PG8_WAIT_V(8); PG8_WAIT_L(0); PG8_BAR; PG8_MMA(0, 0, At, B0); PG8_MMA(0, 1, At, B1); PG8_BAR; PG8_SCHED;
;             PG8_LDA(At, 0, 1); PG8_STAGE(PG8_SB(0, 0), b2, voffB); PG8_STAGE(PG8_SB(0, 1), b2 + hstepB, voffB); PG8_STAGE(PG8_SA(0, 0), a2, voffA);
.LBB0_727:
	v_add_u32_e32 v160, s66, v157
	ds_read_b128 v[130:133], v160
	ds_read_b128 v[164:167], v160 offset:1024
	ds_read_b128 v[168:171], v160 offset:2048
	ds_read_b128 v[172:175], v160 offset:3072
	v_add_u32_e32 v160, s67, v157
	s_add_u32 s0, s28, s30
	ds_read_b128 v[176:179], v160
	ds_read_b128 v[180:183], v160 offset:1024
	ds_read_b128 v[184:187], v160 offset:2048
	ds_read_b128 v[188:191], v160 offset:3072
	s_addc_u32 s1, s29, s31
	s_add_u32 s0, s0, 0x100
	s_addc_u32 s1, s1, 0
	s_add_u32 s84, s79, s30
	s_addc_u32 s85, s81, s31
	s_cmpk_eq_i32 s30, 0x1f00
	s_cselect_b32 s37, s23, s1
	s_cselect_b32 s36, s72, s0
	s_cselect_b32 s1, s75, s85
	s_cselect_b32 s0, s76, s84
	v_lshl_add_u64 v[160:161], v[150:151], 0, s[30:31]
	s_add_i32 m0, s44, 0xc000
	ds_read_b128 v[192:195], v159
	ds_read_b128 v[196:199], v159 offset:1024
	ds_read_b128 v[200:203], v159 offset:2048
	ds_read_b128 v[204:207], v159 offset:3072
	ds_read_b128 v[208:211], v159 offset:4096
	ds_read_b128 v[212:215], v159 offset:5120
	ds_read_b128 v[216:219], v159 offset:6144
	ds_read_b128 v[220:223], v159 offset:7168
	global_load_lds_dwordx4 v[160:161], off
	v_lshl_add_u64 v[160:161], v[152:153], 0, s[30:31]
	s_add_i32 m0, s44, 0xe000
	s_nop 0
	global_load_lds_dwordx4 v[160:161], off
	s_waitcnt vmcnt(8)
	s_waitcnt lgkmcnt(0)
	s_barrier
	s_setprio 3
	s_waitcnt lgkmcnt(0)
	v_mfma_f32_16x16x32_bf16 v[126:129], v[130:133], v[192:195], v[126:129]
	v_mfma_f32_16x16x32_bf16 v[126:129], v[164:167], v[196:199], v[126:129]
	v_mfma_f32_16x16x32_bf16 v[122:125], v[168:171], v[192:195], v[122:125]
	v_mfma_f32_16x16x32_bf16 v[122:125], v[172:175], v[196:199], v[122:125]
	v_mfma_f32_16x16x32_bf16 v[106:109], v[168:171], v[200:203], v[106:109]
	v_mfma_f32_16x16x32_bf16 v[106:109], v[172:175], v[204:207], v[106:109]
	v_mfma_f32_16x16x32_bf16 v[110:113], v[130:133], v[200:203], v[110:113]
	v_mfma_f32_16x16x32_bf16 v[110:113], v[164:167], v[204:207], v[110:113]
	v_mfma_f32_16x16x32_bf16 v[94:97], v[130:133], v[208:211], v[94:97]
	v_mfma_f32_16x16x32_bf16 v[94:97], v[164:167], v[212:215], v[94:97]
	v_mfma_f32_16x16x32_bf16 v[90:93], v[168:171], v[208:211], v[90:93]
	v_mfma_f32_16x16x32_bf16 v[90:93], v[172:175], v[212:215], v[90:93]
	v_mfma_f32_16x16x32_bf16 v[74:77], v[168:171], v[216:219], v[74:77]
	v_mfma_f32_16x16x32_bf16 v[74:77], v[172:175], v[220:223], v[74:77]
	v_mfma_f32_16x16x32_bf16 v[78:81], v[130:133], v[216:219], v[78:81]
	v_mfma_f32_16x16x32_bf16 v[78:81], v[164:167], v[220:223], v[78:81]
	v_mfma_f32_16x16x32_bf16 v[118:121], v[176:179], v[192:195], v[118:121]
	v_mfma_f32_16x16x32_bf16 v[118:121], v[180:183], v[196:199], v[118:121]
	v_mfma_f32_16x16x32_bf16 v[114:117], v[184:187], v[192:195], v[114:117]
	v_mfma_f32_16x16x32_bf16 v[114:117], v[188:191], v[196:199], v[114:117]
	v_mfma_f32_16x16x32_bf16 v[98:101], v[184:187], v[200:203], v[98:101]
	v_mfma_f32_16x16x32_bf16 v[98:101], v[188:191], v[204:207], v[98:101]
	v_mfma_f32_16x16x32_bf16 v[102:105], v[176:179], v[200:203], v[102:105]
	v_mfma_f32_16x16x32_bf16 v[102:105], v[180:183], v[204:207], v[102:105]
	v_mfma_f32_16x16x32_bf16 v[86:89], v[176:179], v[208:211], v[86:89]
	v_mfma_f32_16x16x32_bf16 v[86:89], v[180:183], v[212:215], v[86:89]
	v_mfma_f32_16x16x32_bf16 v[82:85], v[184:187], v[208:211], v[82:85]
	v_mfma_f32_16x16x32_bf16 v[82:85], v[188:191], v[212:215], v[82:85]
	v_mfma_f32_16x16x32_bf16 v[66:69], v[184:187], v[216:219], v[66:69]
	v_mfma_f32_16x16x32_bf16 v[66:69], v[188:191], v[220:223], v[66:69]
	v_mfma_f32_16x16x32_bf16 v[70:73], v[176:179], v[216:219], v[70:73]
	v_mfma_f32_16x16x32_bf16 v[70:73], v[180:183], v[220:223], v[70:73]
	s_setprio 0
	s_barrier
	s_add_i32 s84, s66, s33
	v_lshl_add_u64 v[160:161], s[0:1], 0, v[136:137]
	s_mov_b32 m0, s84
	ds_read_b128 v[192:195], v159 offset:16384
	ds_read_b128 v[196:199], v159 offset:17408
	ds_read_b128 v[200:203], v159 offset:18432
	ds_read_b128 v[204:207], v159 offset:19456
	ds_read_b128 v[208:211], v159 offset:20480
	ds_read_b128 v[212:215], v159 offset:21504
	ds_read_b128 v[216:219], v159 offset:22528
	ds_read_b128 v[220:223], v159 offset:23552
	global_load_lds_dwordx4 v[160:161], off
	s_add_i32 m0, s84, 0x2000
	s_add_u32 s84, s0, 0x100000
	v_lshl_add_u64 v[224:225], s[0:1], 0, v[140:141]
	s_addc_u32 s85, s1, 0
	s_add_i32 s86, s67, s33
	global_load_lds_dwordx4 v[224:225], off
	v_lshl_add_u64 v[226:227], s[84:85], 0, v[136:137]
	s_mov_b32 m0, s86
	v_lshl_add_u64 v[228:229], s[36:37], 0, v[138:139]
	global_load_lds_dwordx4 v[226:227], off
	v_lshl_add_u64 v[226:227], s[84:85], 0, v[140:141]
	s_add_i32 m0, s86, 0x2000
	s_nop 0
	global_load_lds_dwordx4 v[226:227], off
	v_lshl_add_u64 v[226:227], s[36:37], 0, v[134:135]
	s_mov_b32 m0, s44
	s_nop 0
	global_load_lds_dwordx4 v[226:227], off
	s_mov_b32 m0, s45
	s_nop 0
	global_load_lds_dwordx4 v[228:229], off
	s_waitcnt vmcnt(8)
	s_waitcnt lgkmcnt(0)
	s_barrier
; #define PG8_STAGE(bufoff, gbase, voff) do { _Pragma("unroll") for (int _i = 0; _i < 2; ++_i) \
;         __builtin_amdgcn_global_load_lds((const unsigned*)((const char*)(gbase) + (voff)[_i]), (PG8_LAS unsigned*)(lds + (bufoff) + ldsw + _i * 8192), 16, 0, 0); } while (0)
; #define PG8_LDA(dst, b, h) do { _Pragma("unroll") for (int m = 0; m < 4; ++m) _Pragma("unroll") for (int k = 0; k < 2; ++k) dst[m][k] = *(const PG8_LAS bf16x8*)(lds + PG8_SA(b, h) + aoff + m * 2048 + k * 1024); } while (0)
; #define PG8_LDB(dst, b, h) do { _Pragma("unroll") for (int n = 0; n < 2; ++n) _Pragma("unroll") for (int k = 0; k < 2; ++k) dst[n][k] = *(const PG8_LAS bf16x8*)(lds + PG8_SB(b, h) + boff + n * 2048 + k * 1024); } while (0)
; #define PG8_MMA(ai, bj, At, Bt) do { __builtin_amdgcn_s_setprio(3); _Pragma("unroll") for (int m = 0; m < 4; ++m) _Pragma("unroll") for (int n = 0; n < 2; ++n) _Pragma("unroll") for (int k = 0; k < 2; ++k) \
;         acc[ai][bj][m][n] = __builtin_amdgcn_mfma_f32_16x16x32_bf16(Bt[n][k], At[m][k], acc[ai][bj][m][n], 0, 0, 0); __builtin_amdgcn_s_setprio(0); } while (0)
; #define PG8_WAIT_V(n) asm volatile("s_waitcnt vmcnt(" #n ")" ::: "memory")
; #define PG8_WAIT_L(n) asm volatile("s_waitcnt lgkmcnt(" #n ")" ::: "memory")
; #define PG8_BAR __builtin_amdgcn_s_barrier()
; #define PG8_SCHED __builtin_amdgcn_sched_barrier(0)
; template <class Epi, class Sched, bool ALIGN_EPI = false, bool SP2 = false>
; __device__ __forceinline__ void gemm_phase(PG8_LAS unsigned char* lds, const Gemm g, const Sched& S, const Epi& E) {
;     ...
;             PG8_WAIT_V(8); PG8_WAIT_L(0); PG8_BAR; PG8_MMA(1, 0, At, B0); PG8_MMA(1, 1, At, B1); PG8_BAR; PG8_SCHED;
;             PG8_LDB(B0, 1, 0); PG8_LDB(B1, 1, 1); PG8_SCHED; PG8_LDA(At, 1, 0); PG8_STAGE(PG8_SA(0, 1), a2 + hstepA, voffA);
;             PG8_WAIT_V(8); PG8_WAIT_L(0); PG8_BAR; PG8_MMA(0, 0, At, B0); PG8_MMA(0, 1, At, B1); PG8_BAR; PG8_SCHED;
	s_setprio 3
	s_waitcnt lgkmcnt(0)
	v_mfma_f32_16x16x32_bf16 v[62:65], v[130:133], v[192:195], v[62:65]
	v_mfma_f32_16x16x32_bf16 v[62:65], v[164:167], v[196:199], v[62:65]
	v_mfma_f32_16x16x32_bf16 v[58:61], v[168:171], v[192:195], v[58:61]
	v_mfma_f32_16x16x32_bf16 v[58:61], v[172:175], v[196:199], v[58:61]
	v_mfma_f32_16x16x32_bf16 v[42:45], v[168:171], v[200:203], v[42:45]
	v_mfma_f32_16x16x32_bf16 v[42:45], v[172:175], v[204:207], v[42:45]
	v_mfma_f32_16x16x32_bf16 v[46:49], v[130:133], v[200:203], v[46:49]
	v_mfma_f32_16x16x32_bf16 v[46:49], v[164:167], v[204:207], v[46:49]
	v_mfma_f32_16x16x32_bf16 v[30:33], v[130:133], v[208:211], v[30:33]
	v_mfma_f32_16x16x32_bf16 v[30:33], v[164:167], v[212:215], v[30:33]
	v_mfma_f32_16x16x32_bf16 v[26:29], v[168:171], v[208:211], v[26:29]
	v_mfma_f32_16x16x32_bf16 v[26:29], v[172:175], v[212:215], v[26:29]
	v_mfma_f32_16x16x32_bf16 v[10:13], v[168:171], v[216:219], v[10:13]
	v_mfma_f32_16x16x32_bf16 v[10:13], v[172:175], v[220:223], v[10:13]
	v_mfma_f32_16x16x32_bf16 v[14:17], v[130:133], v[216:219], v[14:17]
	v_mfma_f32_16x16x32_bf16 v[14:17], v[164:167], v[220:223], v[14:17]
	v_mfma_f32_16x16x32_bf16 v[54:57], v[176:179], v[192:195], v[54:57]
	v_mfma_f32_16x16x32_bf16 v[54:57], v[180:183], v[196:199], v[54:57]
	v_mfma_f32_16x16x32_bf16 v[50:53], v[184:187], v[192:195], v[50:53]
	v_mfma_f32_16x16x32_bf16 v[50:53], v[188:191], v[196:199], v[50:53]
	v_mfma_f32_16x16x32_bf16 v[34:37], v[184:187], v[200:203], v[34:37]
	v_mfma_f32_16x16x32_bf16 v[34:37], v[188:191], v[204:207], v[34:37]
	v_mfma_f32_16x16x32_bf16 v[38:41], v[176:179], v[200:203], v[38:41]
	v_mfma_f32_16x16x32_bf16 v[38:41], v[180:183], v[204:207], v[38:41]
	v_mfma_f32_16x16x32_bf16 v[22:25], v[176:179], v[208:211], v[22:25]
	v_mfma_f32_16x16x32_bf16 v[22:25], v[180:183], v[212:215], v[22:25]
	v_mfma_f32_16x16x32_bf16 v[18:21], v[184:187], v[208:211], v[18:21]
	v_mfma_f32_16x16x32_bf16 v[18:21], v[188:191], v[212:215], v[18:21]
	v_mfma_f32_16x16x32_bf16 v[2:5], v[184:187], v[216:219], v[2:5]
	v_mfma_f32_16x16x32_bf16 v[2:5], v[188:191], v[220:223], v[2:5]
	v_mfma_f32_16x16x32_bf16 v[6:9], v[176:179], v[216:219], v[6:9]
	v_mfma_f32_16x16x32_bf16 v[6:9], v[180:183], v[220:223], v[6:9]
	s_setprio 0
	s_barrier
	s_add_i32 s84, 0, 0x18000
	v_add_u32_e32 v163, s84, v157
	s_add_i32 s85, 0, 0x1c000
	ds_read_b128 v[130:133], v163
	ds_read_b128 v[164:167], v163 offset:1024
	ds_read_b128 v[168:171], v163 offset:2048
	ds_read_b128 v[172:175], v163 offset:3072
	v_add_u32_e32 v163, s85, v157
	ds_read_b128 v[176:179], v163
	ds_read_b128 v[180:183], v163 offset:1024
	ds_read_b128 v[184:187], v163 offset:2048
	ds_read_b128 v[188:191], v163 offset:3072
	s_add_u32 s36, s36, 0x100000
	s_addc_u32 s37, s37, 0
	s_mov_b32 m0, s54
	v_lshl_add_u64 v[230:231], s[36:37], 0, v[134:135]
	ds_read_b128 v[192:195], v159 offset:32768
	ds_read_b128 v[196:199], v159 offset:33792
	ds_read_b128 v[200:203], v159 offset:34816
	ds_read_b128 v[204:207], v159 offset:35840
	ds_read_b128 v[208:211], v159 offset:36864
	ds_read_b128 v[212:215], v159 offset:37888
	ds_read_b128 v[216:219], v159 offset:38912
	ds_read_b128 v[220:223], v159 offset:39936
	global_load_lds_dwordx4 v[230:231], off
	v_lshl_add_u64 v[230:231], s[36:37], 0, v[138:139]
	s_mov_b32 m0, s55
	s_nop 0
	global_load_lds_dwordx4 v[230:231], off
	s_waitcnt vmcnt(8)
	s_waitcnt lgkmcnt(0)
	s_barrier
	s_setprio 3
	s_waitcnt lgkmcnt(0)
	v_mfma_f32_16x16x32_bf16 v[126:129], v[130:133], v[192:195], v[126:129]
	v_mfma_f32_16x16x32_bf16 v[126:129], v[164:167], v[196:199], v[126:129]
	v_mfma_f32_16x16x32_bf16 v[122:125], v[168:171], v[192:195], v[122:125]
	v_mfma_f32_16x16x32_bf16 v[122:125], v[172:175], v[196:199], v[122:125]
	v_mfma_f32_16x16x32_bf16 v[106:109], v[168:171], v[200:203], v[106:109]
	v_mfma_f32_16x16x32_bf16 v[106:109], v[172:175], v[204:207], v[106:109]
	v_mfma_f32_16x16x32_bf16 v[110:113], v[130:133], v[200:203], v[110:113]
	v_mfma_f32_16x16x32_bf16 v[110:113], v[164:167], v[204:207], v[110:113]
	v_mfma_f32_16x16x32_bf16 v[94:97], v[130:133], v[208:211], v[94:97]
	v_mfma_f32_16x16x32_bf16 v[94:97], v[164:167], v[212:215], v[94:97]
	v_mfma_f32_16x16x32_bf16 v[90:93], v[168:171], v[208:211], v[90:93]
	v_mfma_f32_16x16x32_bf16 v[90:93], v[172:175], v[212:215], v[90:93]
	v_mfma_f32_16x16x32_bf16 v[74:77], v[168:171], v[216:219], v[74:77]
	v_mfma_f32_16x16x32_bf16 v[74:77], v[172:175], v[220:223], v[74:77]
	v_mfma_f32_16x16x32_bf16 v[78:81], v[130:133], v[216:219], v[78:81]
	v_mfma_f32_16x16x32_bf16 v[78:81], v[164:167], v[220:223], v[78:81]
	v_mfma_f32_16x16x32_bf16 v[118:121], v[176:179], v[192:195], v[118:121]
	v_mfma_f32_16x16x32_bf16 v[118:121], v[180:183], v[196:199], v[118:121]
	v_mfma_f32_16x16x32_bf16 v[114:117], v[184:187], v[192:195], v[114:117]
	v_mfma_f32_16x16x32_bf16 v[114:117], v[188:191], v[196:199], v[114:117]
	v_mfma_f32_16x16x32_bf16 v[98:101], v[184:187], v[200:203], v[98:101]
	v_mfma_f32_16x16x32_bf16 v[98:101], v[188:191], v[204:207], v[98:101]
	v_mfma_f32_16x16x32_bf16 v[102:105], v[176:179], v[200:203], v[102:105]
	v_mfma_f32_16x16x32_bf16 v[102:105], v[180:183], v[204:207], v[102:105]
	v_mfma_f32_16x16x32_bf16 v[86:89], v[176:179], v[208:211], v[86:89]
	v_mfma_f32_16x16x32_bf16 v[86:89], v[180:183], v[212:215], v[86:89]
	v_mfma_f32_16x16x32_bf16 v[82:85], v[184:187], v[208:211], v[82:85]
	v_mfma_f32_16x16x32_bf16 v[82:85], v[188:191], v[212:215], v[82:85]
	v_mfma_f32_16x16x32_bf16 v[66:69], v[184:187], v[216:219], v[66:69]
	v_mfma_f32_16x16x32_bf16 v[66:69], v[188:191], v[220:223], v[66:69]
	v_mfma_f32_16x16x32_bf16 v[70:73], v[176:179], v[216:219], v[70:73]
	v_mfma_f32_16x16x32_bf16 v[70:73], v[180:183], v[220:223], v[70:73]
	s_setprio 0
	s_barrier
; #define PG8_STAGE(bufoff, gbase, voff) do { _Pragma("unroll") for (int _i = 0; _i < 2; ++_i) \
;         __builtin_amdgcn_global_load_lds((const unsigned*)((const char*)(gbase) + (voff)[_i]), (PG8_LAS unsigned*)(lds + (bufoff) + ldsw + _i * 8192), 16, 0, 0); } while (0)
; #define PG8_LDA(dst, b, h) do { _Pragma("unroll") for (int m = 0; m < 4; ++m) _Pragma("unroll") for (int k = 0; k < 2; ++k) dst[m][k] = *(const PG8_LAS bf16x8*)(lds + PG8_SA(b, h) + aoff + m * 2048 + k * 1024); } while (0)
; #define PG8_MMA(ai, bj, At, Bt) do { __builtin_amdgcn_s_setprio(3); _Pragma("unroll") for (int m = 0; m < 4; ++m) _Pragma("unroll") for (int n = 0; n < 2; ++n) _Pragma("unroll") for (int k = 0; k < 2; ++k) \
;         acc[ai][bj][m][n] = __builtin_amdgcn_mfma_f32_16x16x32_bf16(Bt[n][k], At[m][k], acc[ai][bj][m][n], 0, 0, 0); __builtin_amdgcn_s_setprio(0); } while (0)
; #define PG8_WAIT_V(n) asm volatile("s_waitcnt vmcnt(" #n ")" ::: "memory")
; #define PG8_WAIT_L(n) asm volatile("s_waitcnt lgkmcnt(" #n ")" ::: "memory")
; #define PG8_BAR __builtin_amdgcn_s_barrier()
; #define PG8_SCHED __builtin_amdgcn_sched_barrier(0)
; template <class Epi, class Sched, bool ALIGN_EPI = false, bool SP2 = false>
; __device__ __forceinline__ void gemm_phase(PG8_LAS unsigned char* lds, const Gemm g, const Sched& S, const Epi& E) {
;     ...
;         for (int t = 0; t < nt; t += 2) {
;             const bool last = (t == nt - 2);
;     ...
;             PG8_LDA(At, 1, 1); PG8_STAGE(PG8_SB(1, 0), b3, voffB); PG8_STAGE(PG8_SB(1, 1), b3 + hstepB, voffB); PG8_STAGE(PG8_SA(1, 0), a3, voffA);
;             PG8_WAIT_V(8); PG8_WAIT_L(0); PG8_BAR; PG8_MMA(1, 0, At, B0); PG8_MMA(1, 1, At, B1); PG8_BAR; PG8_SCHED;
	s_add_i32 s36, s84, s33
	v_lshl_add_u64 v[160:161], v[160:161], 0, s[10:11]
	s_mov_b32 m0, s36
	ds_read_b128 v[192:195], v159 offset:49152
	ds_read_b128 v[196:199], v159 offset:50176
	ds_read_b128 v[200:203], v159 offset:51200
	ds_read_b128 v[204:207], v159 offset:52224
	ds_read_b128 v[208:211], v159 offset:53248
	ds_read_b128 v[212:215], v159 offset:54272
	ds_read_b128 v[216:219], v159 offset:55296
	ds_read_b128 v[220:223], v159 offset:56320
	global_load_lds_dwordx4 v[160:161], off
	s_add_i32 m0, s36, 0x2000
	s_add_u32 s0, s0, 0x100080
	v_lshl_add_u64 v[160:161], v[224:225], 0, s[10:11]
	s_addc_u32 s1, s1, 0
	s_add_i32 s36, s85, s33
	global_load_lds_dwordx4 v[160:161], off
	v_lshl_add_u64 v[160:161], s[0:1], 0, v[136:137]
	s_mov_b32 m0, s36
	s_nop 0
	global_load_lds_dwordx4 v[160:161], off
	v_lshl_add_u64 v[160:161], s[0:1], 0, v[140:141]
	s_add_i32 m0, s36, 0x2000
	s_nop 0
	global_load_lds_dwordx4 v[160:161], off
	v_lshl_add_u64 v[160:161], v[226:227], 0, s[10:11]
	s_mov_b32 m0, s61
	s_nop 0
	global_load_lds_dwordx4 v[160:161], off
	v_lshl_add_u64 v[160:161], v[228:229], 0, s[10:11]
	s_mov_b32 m0, s62
	s_nop 0
	global_load_lds_dwordx4 v[160:161], off
	s_waitcnt vmcnt(8)
	s_waitcnt lgkmcnt(0)
	s_barrier
	s_setprio 3
	s_waitcnt lgkmcnt(0)
	v_mfma_f32_16x16x32_bf16 v[62:65], v[130:133], v[192:195], v[62:65]
	v_mfma_f32_16x16x32_bf16 v[62:65], v[164:167], v[196:199], v[62:65]
	v_mfma_f32_16x16x32_bf16 v[58:61], v[168:171], v[192:195], v[58:61]
	v_mfma_f32_16x16x32_bf16 v[58:61], v[172:175], v[196:199], v[58:61]
	v_mfma_f32_16x16x32_bf16 v[42:45], v[168:171], v[200:203], v[42:45]
	v_mfma_f32_16x16x32_bf16 v[42:45], v[172:175], v[204:207], v[42:45]
	v_mfma_f32_16x16x32_bf16 v[46:49], v[130:133], v[200:203], v[46:49]
	v_mfma_f32_16x16x32_bf16 v[46:49], v[164:167], v[204:207], v[46:49]
	v_mfma_f32_16x16x32_bf16 v[30:33], v[130:133], v[208:211], v[30:33]
	v_mfma_f32_16x16x32_bf16 v[30:33], v[164:167], v[212:215], v[30:33]
	v_mfma_f32_16x16x32_bf16 v[26:29], v[168:171], v[208:211], v[26:29]
	v_mfma_f32_16x16x32_bf16 v[26:29], v[172:175], v[212:215], v[26:29]
	v_mfma_f32_16x16x32_bf16 v[10:13], v[168:171], v[216:219], v[10:13]
	v_mfma_f32_16x16x32_bf16 v[10:13], v[172:175], v[220:223], v[10:13]
	v_mfma_f32_16x16x32_bf16 v[14:17], v[130:133], v[216:219], v[14:17]
	v_mfma_f32_16x16x32_bf16 v[14:17], v[164:167], v[220:223], v[14:17]
	v_mfma_f32_16x16x32_bf16 v[54:57], v[176:179], v[192:195], v[54:57]
	v_mfma_f32_16x16x32_bf16 v[54:57], v[180:183], v[196:199], v[54:57]
	v_mfma_f32_16x16x32_bf16 v[50:53], v[184:187], v[192:195], v[50:53]
	v_mfma_f32_16x16x32_bf16 v[50:53], v[188:191], v[196:199], v[50:53]
	v_mfma_f32_16x16x32_bf16 v[34:37], v[184:187], v[200:203], v[34:37]
	v_mfma_f32_16x16x32_bf16 v[34:37], v[188:191], v[204:207], v[34:37]
	v_mfma_f32_16x16x32_bf16 v[38:41], v[176:179], v[200:203], v[38:41]
	v_mfma_f32_16x16x32_bf16 v[38:41], v[180:183], v[204:207], v[38:41]
	v_mfma_f32_16x16x32_bf16 v[22:25], v[176:179], v[208:211], v[22:25]
	v_mfma_f32_16x16x32_bf16 v[22:25], v[180:183], v[212:215], v[22:25]
	v_mfma_f32_16x16x32_bf16 v[18:21], v[184:187], v[208:211], v[18:21]
	v_mfma_f32_16x16x32_bf16 v[18:21], v[188:191], v[212:215], v[18:21]
	v_mfma_f32_16x16x32_bf16 v[2:5], v[184:187], v[216:219], v[2:5]
	v_mfma_f32_16x16x32_bf16 v[2:5], v[188:191], v[220:223], v[2:5]
	v_mfma_f32_16x16x32_bf16 v[6:9], v[176:179], v[216:219], v[6:9]
	v_mfma_f32_16x16x32_bf16 v[6:9], v[180:183], v[220:223], v[6:9]
	s_setprio 0
	s_barrier
	s_add_i32 s83, s83, 2
	s_add_u32 s30, s30, 0x100
	s_addc_u32 s31, s31, 0
	s_cmp_gt_u32 s83, 61
	s_cbranch_scc1 .LBB0_730

; #define PG8_STAGE(bufoff, gbase, voff) do { _Pragma("unroll") for (int _i = 0; _i < 2; ++_i) \
;         __builtin_amdgcn_global_load_lds((const unsigned*)((const char*)(gbase) + (voff)[_i]), (PG8_LAS unsigned*)(lds + (bufoff) + ldsw + _i * 8192), 16, 0, 0); } while (0)
; #define PG8_LDA(dst, b, h) do { _Pragma("unroll") for (int m = 0; m < 4; ++m) _Pragma("unroll") for (int k = 0; k < 2; ++k) dst[m][k] = *(const PG8_LAS bf16x8*)(lds + PG8_SA(b, h) + aoff + m * 2048 + k * 1024); } while (0)
; #define PG8_LDB(dst, b, h) do { _Pragma("unroll") for (int n = 0; n < 2; ++n) _Pragma("unroll") for (int k = 0; k < 2; ++k) dst[n][k] = *(const PG8_LAS bf16x8*)(lds + PG8_SB(b, h) + boff + n * 2048 + k * 1024); } while (0)
; #define PG8_MMA(ai, bj, At, Bt) do { __builtin_amdgcn_s_setprio(3); _Pragma("unroll") for (int m = 0; m < 4; ++m) _Pragma("unroll") for (int n = 0; n < 2; ++n) _Pragma("unroll") for (int k = 0; k < 2; ++k) \
;         acc[ai][bj][m][n] = __builtin_amdgcn_mfma_f32_16x16x32_bf16(Bt[n][k], At[m][k], acc[ai][bj][m][n], 0, 0, 0); __builtin_amdgcn_s_setprio(0); } while (0)
; #define PG8_WAIT_V(n) asm volatile("s_waitcnt vmcnt(" #n ")" ::: "memory")
; #define PG8_WAIT_L(n) asm volatile("s_waitcnt lgkmcnt(" #n ")" ::: "memory")
; #define PG8_BAR __builtin_amdgcn_s_barrier()
; #define PG8_SCHED __builtin_amdgcn_sched_barrier(0)
; template <class Epi, class Sched, bool ALIGN_EPI = false, bool SP2 = false>
; __device__ __forceinline__ void gemm_phase(PG8_LAS unsigned char* lds, const Gemm g, const Sched& S, const Epi& E) {
;     ...
;             PG8_LDB(B0, 0, 0); PG8_LDB(B1, 0, 1); PG8_SCHED; PG8_LDA(At, 0, 0); PG8_STAGE(PG8_SA(1, 1), a1 + hstepA, voffA);
;             PG8_WAIT_V(8); PG8_WAIT_L(0); PG8_BAR; PG8_MMA(0, 0, At, B0); PG8_MMA(0, 1, At, B1); PG8_BAR; PG8_SCHED;
;             PG8_LDA(At, 0, 1); PG8_STAGE(PG8_SB(0, 0), b2, voffB); PG8_STAGE(PG8_SB(0, 1), b2 + hstepB, voffB); PG8_STAGE(PG8_SA(0, 0), a2, voffA);
.LBB0_808:
	v_add_u32_e32 v3, s65, v186
	ds_read_b128 v[134:137], v3
	ds_read_b128 v[138:141], v3 offset:1024
	ds_read_b128 v[142:145], v3 offset:2048
	ds_read_b128 v[146:149], v3 offset:3072
	v_add_u32_e32 v3, s66, v186
	s_add_u32 s36, s28, s30
	ds_read_b128 v[150:153], v3
	ds_read_b128 v[154:157], v3 offset:1024
	ds_read_b128 v[158:161], v3 offset:2048
	ds_read_b128 v[190:193], v3 offset:3072
	s_addc_u32 s37, s29, s31
	s_add_u32 s36, s36, 0x100
	s_addc_u32 s37, s37, 0
	s_add_u32 s86, s83, s30
	s_addc_u32 s87, s84, s31
	s_cmpk_eq_i32 s30, 0x1f00
	s_cselect_b32 s41, s23, s37
	s_cselect_b32 s40, s75, s36
	s_cselect_b32 s37, s77, s87
	s_cselect_b32 s36, s78, s86
	v_lshl_add_u64 v[4:5], v[180:181], 0, s[30:31]
	s_add_i32 m0, s42, 0xc000
	ds_read_b128 v[194:197], v188
	ds_read_b128 v[198:201], v188 offset:1024
	ds_read_b128 v[202:205], v188 offset:2048
	ds_read_b128 v[206:209], v188 offset:3072
	ds_read_b128 v[210:213], v188 offset:4096
	ds_read_b128 v[214:217], v188 offset:5120
	ds_read_b128 v[218:221], v188 offset:6144
	ds_read_b128 v[222:225], v188 offset:7168
	global_load_lds_dwordx4 v[4:5], off
	v_lshl_add_u64 v[4:5], v[182:183], 0, s[30:31]
	s_add_i32 m0, s42, 0xe000
	s_nop 0
	global_load_lds_dwordx4 v[4:5], off
	s_waitcnt vmcnt(8)
	s_waitcnt lgkmcnt(0)
	s_barrier
	s_setprio 3
	s_waitcnt lgkmcnt(0)
	v_mfma_f32_16x16x32_bf16 v[130:133], v[134:137], v[194:197], v[130:133]
	v_mfma_f32_16x16x32_bf16 v[130:133], v[138:141], v[198:201], v[130:133]
	v_mfma_f32_16x16x32_bf16 v[126:129], v[142:145], v[194:197], v[126:129]
	v_mfma_f32_16x16x32_bf16 v[126:129], v[146:149], v[198:201], v[126:129]
	v_mfma_f32_16x16x32_bf16 v[110:113], v[142:145], v[202:205], v[110:113]
	v_mfma_f32_16x16x32_bf16 v[110:113], v[146:149], v[206:209], v[110:113]
	v_mfma_f32_16x16x32_bf16 v[114:117], v[134:137], v[202:205], v[114:117]
	v_mfma_f32_16x16x32_bf16 v[114:117], v[138:141], v[206:209], v[114:117]
	v_mfma_f32_16x16x32_bf16 v[98:101], v[134:137], v[210:213], v[98:101]
	v_mfma_f32_16x16x32_bf16 v[98:101], v[138:141], v[214:217], v[98:101]
	v_mfma_f32_16x16x32_bf16 v[94:97], v[142:145], v[210:213], v[94:97]
	v_mfma_f32_16x16x32_bf16 v[94:97], v[146:149], v[214:217], v[94:97]
	v_mfma_f32_16x16x32_bf16 v[78:81], v[142:145], v[218:221], v[78:81]
	v_mfma_f32_16x16x32_bf16 v[78:81], v[146:149], v[222:225], v[78:81]
	v_mfma_f32_16x16x32_bf16 v[82:85], v[134:137], v[218:221], v[82:85]
	v_mfma_f32_16x16x32_bf16 v[82:85], v[138:141], v[222:225], v[82:85]
	v_mfma_f32_16x16x32_bf16 v[122:125], v[150:153], v[194:197], v[122:125]
	v_mfma_f32_16x16x32_bf16 v[122:125], v[154:157], v[198:201], v[122:125]
	v_mfma_f32_16x16x32_bf16 v[118:121], v[158:161], v[194:197], v[118:121]
	v_mfma_f32_16x16x32_bf16 v[118:121], v[190:193], v[198:201], v[118:121]
	v_mfma_f32_16x16x32_bf16 v[102:105], v[158:161], v[202:205], v[102:105]
	v_mfma_f32_16x16x32_bf16 v[102:105], v[190:193], v[206:209], v[102:105]
	v_mfma_f32_16x16x32_bf16 v[106:109], v[150:153], v[202:205], v[106:109]
	v_mfma_f32_16x16x32_bf16 v[106:109], v[154:157], v[206:209], v[106:109]
	v_mfma_f32_16x16x32_bf16 v[90:93], v[150:153], v[210:213], v[90:93]
	v_mfma_f32_16x16x32_bf16 v[90:93], v[154:157], v[214:217], v[90:93]
	v_mfma_f32_16x16x32_bf16 v[86:89], v[158:161], v[210:213], v[86:89]
	v_mfma_f32_16x16x32_bf16 v[86:89], v[190:193], v[214:217], v[86:89]
	v_mfma_f32_16x16x32_bf16 v[70:73], v[158:161], v[218:221], v[70:73]
	v_mfma_f32_16x16x32_bf16 v[70:73], v[190:193], v[222:225], v[70:73]
	v_mfma_f32_16x16x32_bf16 v[74:77], v[150:153], v[218:221], v[74:77]
	v_mfma_f32_16x16x32_bf16 v[74:77], v[154:157], v[222:225], v[74:77]
	s_setprio 0
	s_barrier
	s_add_i32 s86, s65, s33
	v_lshl_add_u64 v[226:227], s[36:37], 0, v[166:167]
	s_mov_b32 m0, s86
	ds_read_b128 v[194:197], v188 offset:16384
	ds_read_b128 v[198:201], v188 offset:17408
	ds_read_b128 v[202:205], v188 offset:18432
	ds_read_b128 v[206:209], v188 offset:19456
	ds_read_b128 v[210:213], v188 offset:20480
	ds_read_b128 v[214:217], v188 offset:21504
	ds_read_b128 v[218:221], v188 offset:22528
	ds_read_b128 v[222:225], v188 offset:23552
	global_load_lds_dwordx4 v[226:227], off
	s_add_i32 m0, s86, 0x2000
	s_add_u32 s86, s36, 0x100000
	v_lshl_add_u64 v[228:229], s[36:37], 0, v[170:171]
	s_addc_u32 s87, s37, 0
	s_add_i32 s88, s66, s33
	global_load_lds_dwordx4 v[228:229], off
	v_lshl_add_u64 v[4:5], s[86:87], 0, v[166:167]
	s_mov_b32 m0, s88
	v_lshl_add_u64 v[230:231], s[40:41], 0, v[164:165]
	global_load_lds_dwordx4 v[4:5], off
	v_lshl_add_u64 v[4:5], s[86:87], 0, v[170:171]
	s_add_i32 m0, s88, 0x2000
	v_lshl_add_u64 v[232:233], s[40:41], 0, v[168:169]
	global_load_lds_dwordx4 v[4:5], off
	s_mov_b32 m0, s42
	s_nop 0
	global_load_lds_dwordx4 v[230:231], off
	s_mov_b32 m0, s43
	s_nop 0
	global_load_lds_dwordx4 v[232:233], off
	s_waitcnt vmcnt(8)
	s_waitcnt lgkmcnt(0)
	s_barrier
; #define PG8_STAGE(bufoff, gbase, voff) do { _Pragma("unroll") for (int _i = 0; _i < 2; ++_i) \
;         __builtin_amdgcn_global_load_lds((const unsigned*)((const char*)(gbase) + (voff)[_i]), (PG8_LAS unsigned*)(lds + (bufoff) + ldsw + _i * 8192), 16, 0, 0); } while (0)
; #define PG8_LDA(dst, b, h) do { _Pragma("unroll") for (int m = 0; m < 4; ++m) _Pragma("unroll") for (int k = 0; k < 2; ++k) dst[m][k] = *(const PG8_LAS bf16x8*)(lds + PG8_SA(b, h) + aoff + m * 2048 + k * 1024); } while (0)
; #define PG8_LDB(dst, b, h) do { _Pragma("unroll") for (int n = 0; n < 2; ++n) _Pragma("unroll") for (int k = 0; k < 2; ++k) dst[n][k] = *(const PG8_LAS bf16x8*)(lds + PG8_SB(b, h) + boff + n * 2048 + k * 1024); } while (0)
; #define PG8_MMA(ai, bj, At, Bt) do { __builtin_amdgcn_s_setprio(3); _Pragma("unroll") for (int m = 0; m < 4; ++m) _Pragma("unroll") for (int n = 0; n < 2; ++n) _Pragma("unroll") for (int k = 0; k < 2; ++k) \
;         acc[ai][bj][m][n] = __builtin_amdgcn_mfma_f32_16x16x32_bf16(Bt[n][k], At[m][k], acc[ai][bj][m][n], 0, 0, 0); __builtin_amdgcn_s_setprio(0); } while (0)
; #define PG8_WAIT_V(n) asm volatile("s_waitcnt vmcnt(" #n ")" ::: "memory")
; #define PG8_WAIT_L(n) asm volatile("s_waitcnt lgkmcnt(" #n ")" ::: "memory")
; #define PG8_BAR __builtin_amdgcn_s_barrier()
; #define PG8_SCHED __builtin_amdgcn_sched_barrier(0)
; template <class Epi, class Sched, bool ALIGN_EPI = false, bool SP2 = false>
; __device__ __forceinline__ void gemm_phase(PG8_LAS unsigned char* lds, const Gemm g, const Sched& S, const Epi& E) {
;     ...
;             PG8_WAIT_V(8); PG8_WAIT_L(0); PG8_BAR; PG8_MMA(1, 0, At, B0); PG8_MMA(1, 1, At, B1); PG8_BAR; PG8_SCHED;
;             PG8_LDB(B0, 1, 0); PG8_LDB(B1, 1, 1); PG8_SCHED; PG8_LDA(At, 1, 0); PG8_STAGE(PG8_SA(0, 1), a2 + hstepA, voffA);
;             PG8_WAIT_V(8); PG8_WAIT_L(0); PG8_BAR; PG8_MMA(0, 0, At, B0); PG8_MMA(0, 1, At, B1); PG8_BAR; PG8_SCHED;
	s_setprio 3
	s_waitcnt lgkmcnt(0)
	v_mfma_f32_16x16x32_bf16 v[66:69], v[134:137], v[194:197], v[66:69]
	v_mfma_f32_16x16x32_bf16 v[66:69], v[138:141], v[198:201], v[66:69]
	v_mfma_f32_16x16x32_bf16 v[62:65], v[142:145], v[194:197], v[62:65]
	v_mfma_f32_16x16x32_bf16 v[62:65], v[146:149], v[198:201], v[62:65]
	v_mfma_f32_16x16x32_bf16 v[46:49], v[142:145], v[202:205], v[46:49]
	v_mfma_f32_16x16x32_bf16 v[46:49], v[146:149], v[206:209], v[46:49]
	v_mfma_f32_16x16x32_bf16 v[50:53], v[134:137], v[202:205], v[50:53]
	v_mfma_f32_16x16x32_bf16 v[50:53], v[138:141], v[206:209], v[50:53]
	v_mfma_f32_16x16x32_bf16 v[34:37], v[134:137], v[210:213], v[34:37]
	v_mfma_f32_16x16x32_bf16 v[34:37], v[138:141], v[214:217], v[34:37]
	v_mfma_f32_16x16x32_bf16 v[30:33], v[142:145], v[210:213], v[30:33]
	v_mfma_f32_16x16x32_bf16 v[30:33], v[146:149], v[214:217], v[30:33]
	v_mfma_f32_16x16x32_bf16 v[14:17], v[142:145], v[218:221], v[14:17]
	v_mfma_f32_16x16x32_bf16 v[14:17], v[146:149], v[222:225], v[14:17]
	v_mfma_f32_16x16x32_bf16 v[18:21], v[134:137], v[218:221], v[18:21]
	v_mfma_f32_16x16x32_bf16 v[18:21], v[138:141], v[222:225], v[18:21]
	v_mfma_f32_16x16x32_bf16 v[58:61], v[150:153], v[194:197], v[58:61]
	v_mfma_f32_16x16x32_bf16 v[58:61], v[154:157], v[198:201], v[58:61]
	v_mfma_f32_16x16x32_bf16 v[54:57], v[158:161], v[194:197], v[54:57]
	v_mfma_f32_16x16x32_bf16 v[54:57], v[190:193], v[198:201], v[54:57]
	v_mfma_f32_16x16x32_bf16 v[38:41], v[158:161], v[202:205], v[38:41]
	v_mfma_f32_16x16x32_bf16 v[38:41], v[190:193], v[206:209], v[38:41]
	v_mfma_f32_16x16x32_bf16 v[42:45], v[150:153], v[202:205], v[42:45]
	v_mfma_f32_16x16x32_bf16 v[42:45], v[154:157], v[206:209], v[42:45]
	v_mfma_f32_16x16x32_bf16 v[26:29], v[150:153], v[210:213], v[26:29]
	v_mfma_f32_16x16x32_bf16 v[26:29], v[154:157], v[214:217], v[26:29]
	v_mfma_f32_16x16x32_bf16 v[22:25], v[158:161], v[210:213], v[22:25]
	v_mfma_f32_16x16x32_bf16 v[22:25], v[190:193], v[214:217], v[22:25]
	v_mfma_f32_16x16x32_bf16 v[4:7], v[158:161], v[218:221], v[6:9]
	v_mfma_f32_16x16x32_bf16 v[4:7], v[190:193], v[222:225], v[4:7]
	v_mfma_f32_16x16x32_bf16 v[10:13], v[150:153], v[218:221], v[10:13]
	v_mfma_f32_16x16x32_bf16 v[10:13], v[154:157], v[222:225], v[10:13]
	s_setprio 0
	s_barrier
	s_add_i32 s86, 0, 0x18000
	v_add_u32_e32 v3, s86, v186
	s_add_i32 s87, 0, 0x1c000
	ds_read_b128 v[134:137], v3
	ds_read_b128 v[138:141], v3 offset:1024
	ds_read_b128 v[142:145], v3 offset:2048
	ds_read_b128 v[146:149], v3 offset:3072
	v_add_u32_e32 v3, s87, v186
	ds_read_b128 v[150:153], v3
	ds_read_b128 v[154:157], v3 offset:1024
	ds_read_b128 v[158:161], v3 offset:2048
	ds_read_b128 v[190:193], v3 offset:3072
	s_add_u32 s40, s40, 0x100000
	s_addc_u32 s41, s41, 0
	s_mov_b32 m0, s44
	v_lshl_add_u64 v[8:9], s[40:41], 0, v[164:165]
	ds_read_b128 v[194:197], v188 offset:32768
	ds_read_b128 v[198:201], v188 offset:33792
	ds_read_b128 v[202:205], v188 offset:34816
	ds_read_b128 v[206:209], v188 offset:35840
	ds_read_b128 v[210:213], v188 offset:36864
	ds_read_b128 v[214:217], v188 offset:37888
	ds_read_b128 v[218:221], v188 offset:38912
	ds_read_b128 v[222:225], v188 offset:39936
	global_load_lds_dwordx4 v[8:9], off
	v_lshl_add_u64 v[8:9], s[40:41], 0, v[168:169]
	s_mov_b32 m0, s45
	s_nop 0
	global_load_lds_dwordx4 v[8:9], off
	s_waitcnt vmcnt(8)
	s_waitcnt lgkmcnt(0)
	s_barrier
	s_setprio 3
	s_waitcnt lgkmcnt(0)
	v_mfma_f32_16x16x32_bf16 v[130:133], v[134:137], v[194:197], v[130:133]
	v_mfma_f32_16x16x32_bf16 v[130:133], v[138:141], v[198:201], v[130:133]
	v_mfma_f32_16x16x32_bf16 v[126:129], v[142:145], v[194:197], v[126:129]
	v_mfma_f32_16x16x32_bf16 v[126:129], v[146:149], v[198:201], v[126:129]
	v_mfma_f32_16x16x32_bf16 v[110:113], v[142:145], v[202:205], v[110:113]
	v_mfma_f32_16x16x32_bf16 v[110:113], v[146:149], v[206:209], v[110:113]
	v_mfma_f32_16x16x32_bf16 v[114:117], v[134:137], v[202:205], v[114:117]
	v_mfma_f32_16x16x32_bf16 v[114:117], v[138:141], v[206:209], v[114:117]
	v_mfma_f32_16x16x32_bf16 v[98:101], v[134:137], v[210:213], v[98:101]
	v_mfma_f32_16x16x32_bf16 v[98:101], v[138:141], v[214:217], v[98:101]
	v_mfma_f32_16x16x32_bf16 v[94:97], v[142:145], v[210:213], v[94:97]
	v_mfma_f32_16x16x32_bf16 v[94:97], v[146:149], v[214:217], v[94:97]
	v_mfma_f32_16x16x32_bf16 v[78:81], v[142:145], v[218:221], v[78:81]
	v_mfma_f32_16x16x32_bf16 v[78:81], v[146:149], v[222:225], v[78:81]
	v_mfma_f32_16x16x32_bf16 v[82:85], v[134:137], v[218:221], v[82:85]
	v_mfma_f32_16x16x32_bf16 v[82:85], v[138:141], v[222:225], v[82:85]
	v_mfma_f32_16x16x32_bf16 v[122:125], v[150:153], v[194:197], v[122:125]
	v_mfma_f32_16x16x32_bf16 v[122:125], v[154:157], v[198:201], v[122:125]
	v_mfma_f32_16x16x32_bf16 v[118:121], v[158:161], v[194:197], v[118:121]
	v_mfma_f32_16x16x32_bf16 v[118:121], v[190:193], v[198:201], v[118:121]
	v_mfma_f32_16x16x32_bf16 v[102:105], v[158:161], v[202:205], v[102:105]
	v_mfma_f32_16x16x32_bf16 v[102:105], v[190:193], v[206:209], v[102:105]
	v_mfma_f32_16x16x32_bf16 v[106:109], v[150:153], v[202:205], v[106:109]
	v_mfma_f32_16x16x32_bf16 v[106:109], v[154:157], v[206:209], v[106:109]
	v_mfma_f32_16x16x32_bf16 v[90:93], v[150:153], v[210:213], v[90:93]
	v_mfma_f32_16x16x32_bf16 v[90:93], v[154:157], v[214:217], v[90:93]
	v_mfma_f32_16x16x32_bf16 v[86:89], v[158:161], v[210:213], v[86:89]
	v_mfma_f32_16x16x32_bf16 v[86:89], v[190:193], v[214:217], v[86:89]
	v_mfma_f32_16x16x32_bf16 v[70:73], v[158:161], v[218:221], v[70:73]
	v_mfma_f32_16x16x32_bf16 v[70:73], v[190:193], v[222:225], v[70:73]
	v_mfma_f32_16x16x32_bf16 v[74:77], v[150:153], v[218:221], v[74:77]
	v_mfma_f32_16x16x32_bf16 v[74:77], v[154:157], v[222:225], v[74:77]
	s_setprio 0
	s_barrier
; #define PG8_STAGE(bufoff, gbase, voff) do { _Pragma("unroll") for (int _i = 0; _i < 2; ++_i) \
;         __builtin_amdgcn_global_load_lds((const unsigned*)((const char*)(gbase) + (voff)[_i]), (PG8_LAS unsigned*)(lds + (bufoff) + ldsw + _i * 8192), 16, 0, 0); } while (0)
; #define PG8_LDA(dst, b, h) do { _Pragma("unroll") for (int m = 0; m < 4; ++m) _Pragma("unroll") for (int k = 0; k < 2; ++k) dst[m][k] = *(const PG8_LAS bf16x8*)(lds + PG8_SA(b, h) + aoff + m * 2048 + k * 1024); } while (0)
; #define PG8_MMA(ai, bj, At, Bt) do { __builtin_amdgcn_s_setprio(3); _Pragma("unroll") for (int m = 0; m < 4; ++m) _Pragma("unroll") for (int n = 0; n < 2; ++n) _Pragma("unroll") for (int k = 0; k < 2; ++k) \
;         acc[ai][bj][m][n] = __builtin_amdgcn_mfma_f32_16x16x32_bf16(Bt[n][k], At[m][k], acc[ai][bj][m][n], 0, 0, 0); __builtin_amdgcn_s_setprio(0); } while (0)
; #define PG8_WAIT_V(n) asm volatile("s_waitcnt vmcnt(" #n ")" ::: "memory")
; #define PG8_WAIT_L(n) asm volatile("s_waitcnt lgkmcnt(" #n ")" ::: "memory")
; #define PG8_BAR __builtin_amdgcn_s_barrier()
; #define PG8_SCHED __builtin_amdgcn_sched_barrier(0)
; template <class Epi, class Sched, bool ALIGN_EPI = false, bool SP2 = false>
; __device__ __forceinline__ void gemm_phase(PG8_LAS unsigned char* lds, const Gemm g, const Sched& S, const Epi& E) {
;     ...
;             PG8_LDA(At, 1, 1); PG8_STAGE(PG8_SB(1, 0), b3, voffB); PG8_STAGE(PG8_SB(1, 1), b3 + hstepB, voffB); PG8_STAGE(PG8_SA(1, 0), a3, voffA);
;             PG8_WAIT_V(8); PG8_WAIT_L(0); PG8_BAR; PG8_MMA(1, 0, At, B0); PG8_MMA(1, 1, At, B1); PG8_BAR; PG8_SCHED;
	s_add_i32 s40, s86, s33
	v_lshl_add_u64 v[8:9], v[226:227], 0, s[10:11]
	s_mov_b32 m0, s40
	ds_read_b128 v[194:197], v188 offset:49152
	ds_read_b128 v[198:201], v188 offset:50176
	ds_read_b128 v[202:205], v188 offset:51200
	ds_read_b128 v[206:209], v188 offset:52224
	ds_read_b128 v[210:213], v188 offset:53248
	ds_read_b128 v[214:217], v188 offset:54272
	ds_read_b128 v[218:221], v188 offset:55296
	ds_read_b128 v[222:225], v188 offset:56320
	global_load_lds_dwordx4 v[8:9], off
	s_add_i32 m0, s40, 0x2000
	s_add_u32 s36, s36, 0x100080
	v_lshl_add_u64 v[8:9], v[228:229], 0, s[10:11]
	s_addc_u32 s37, s37, 0
	s_add_i32 s40, s87, s33
	global_load_lds_dwordx4 v[8:9], off
	v_lshl_add_u64 v[8:9], s[36:37], 0, v[166:167]
	s_mov_b32 m0, s40
	s_nop 0
	global_load_lds_dwordx4 v[8:9], off
	v_lshl_add_u64 v[8:9], s[36:37], 0, v[170:171]
	s_add_i32 m0, s40, 0x2000
	s_nop 0
	global_load_lds_dwordx4 v[8:9], off
	v_lshl_add_u64 v[8:9], v[230:231], 0, s[10:11]
	s_mov_b32 m0, s60
	s_nop 0
	global_load_lds_dwordx4 v[8:9], off
	v_lshl_add_u64 v[8:9], v[232:233], 0, s[10:11]
	s_mov_b32 m0, s61
	s_nop 0
	global_load_lds_dwordx4 v[8:9], off
	s_waitcnt vmcnt(8)
	s_waitcnt lgkmcnt(0)
	s_barrier
	s_setprio 3
	s_waitcnt lgkmcnt(0)
	v_mfma_f32_16x16x32_bf16 v[66:69], v[134:137], v[194:197], v[66:69]
	v_mfma_f32_16x16x32_bf16 v[66:69], v[138:141], v[198:201], v[66:69]
	v_mfma_f32_16x16x32_bf16 v[62:65], v[142:145], v[194:197], v[62:65]
	v_mfma_f32_16x16x32_bf16 v[62:65], v[146:149], v[198:201], v[62:65]
	v_mfma_f32_16x16x32_bf16 v[46:49], v[142:145], v[202:205], v[46:49]
	v_mfma_f32_16x16x32_bf16 v[46:49], v[146:149], v[206:209], v[46:49]
	v_mfma_f32_16x16x32_bf16 v[50:53], v[134:137], v[202:205], v[50:53]
	v_mfma_f32_16x16x32_bf16 v[50:53], v[138:141], v[206:209], v[50:53]
	v_mfma_f32_16x16x32_bf16 v[34:37], v[134:137], v[210:213], v[34:37]
	v_mfma_f32_16x16x32_bf16 v[34:37], v[138:141], v[214:217], v[34:37]
	v_mfma_f32_16x16x32_bf16 v[30:33], v[142:145], v[210:213], v[30:33]
	v_mfma_f32_16x16x32_bf16 v[30:33], v[146:149], v[214:217], v[30:33]
	v_mfma_f32_16x16x32_bf16 v[14:17], v[142:145], v[218:221], v[14:17]
	v_mfma_f32_16x16x32_bf16 v[14:17], v[146:149], v[222:225], v[14:17]
	v_mfma_f32_16x16x32_bf16 v[18:21], v[134:137], v[218:221], v[18:21]
	v_mfma_f32_16x16x32_bf16 v[18:21], v[138:141], v[222:225], v[18:21]
	v_mfma_f32_16x16x32_bf16 v[58:61], v[150:153], v[194:197], v[58:61]
	v_mfma_f32_16x16x32_bf16 v[54:57], v[158:161], v[194:197], v[54:57]
	v_mfma_f32_16x16x32_bf16 v[42:45], v[150:153], v[202:205], v[42:45]
	v_mfma_f32_16x16x32_bf16 v[38:41], v[158:161], v[202:205], v[38:41]
	v_mfma_f32_16x16x32_bf16 v[26:29], v[150:153], v[210:213], v[26:29]
	v_mfma_f32_16x16x32_bf16 v[22:25], v[158:161], v[210:213], v[22:25]
	v_mfma_f32_16x16x32_bf16 v[8:11], v[150:153], v[218:221], v[10:13]
	v_mfma_f32_16x16x32_bf16 v[4:7], v[158:161], v[218:221], v[4:7]
	v_mfma_f32_16x16x32_bf16 v[58:61], v[154:157], v[198:201], v[58:61]
	v_mfma_f32_16x16x32_bf16 v[54:57], v[190:193], v[198:201], v[54:57]
	v_mfma_f32_16x16x32_bf16 v[42:45], v[154:157], v[206:209], v[42:45]
	v_mfma_f32_16x16x32_bf16 v[38:41], v[190:193], v[206:209], v[38:41]
	v_mfma_f32_16x16x32_bf16 v[26:29], v[154:157], v[214:217], v[26:29]
	v_mfma_f32_16x16x32_bf16 v[22:25], v[190:193], v[214:217], v[22:25]
	v_mfma_f32_16x16x32_bf16 v[10:13], v[154:157], v[222:225], v[8:11]
	v_mfma_f32_16x16x32_bf16 v[6:9], v[190:193], v[222:225], v[4:7]
	s_setprio 0
	s_barrier
	s_add_i32 s85, s85, 2
	s_add_u32 s30, s30, 0x100
	s_addc_u32 s31, s31, 0
	s_cmp_gt_u32 s85, 61
	s_cbranch_scc1 .LBB0_811

; #define PG8_STAGE(bufoff, gbase, voff) do { _Pragma("unroll") for (int _i = 0; _i < 2; ++_i) \
;         __builtin_amdgcn_global_load_lds((const unsigned*)((const char*)(gbase) + (voff)[_i]), (PG8_LAS unsigned*)(lds + (bufoff) + ldsw + _i * 8192), 16, 0, 0); } while (0)
; #define PG8_LDA(dst, b, h) do { _Pragma("unroll") for (int m = 0; m < 4; ++m) _Pragma("unroll") for (int k = 0; k < 2; ++k) dst[m][k] = *(const PG8_LAS bf16x8*)(lds + PG8_SA(b, h) + aoff + m * 2048 + k * 1024); } while (0)
; #define PG8_LDB(dst, b, h) do { _Pragma("unroll") for (int n = 0; n < 2; ++n) _Pragma("unroll") for (int k = 0; k < 2; ++k) dst[n][k] = *(const PG8_LAS bf16x8*)(lds + PG8_SB(b, h) + boff + n * 2048 + k * 1024); } while (0)
; #define PG8_MMA(ai, bj, At, Bt) do { __builtin_amdgcn_s_setprio(3); _Pragma("unroll") for (int m = 0; m < 4; ++m) _Pragma("unroll") for (int n = 0; n < 2; ++n) _Pragma("unroll") for (int k = 0; k < 2; ++k) \
;         acc[ai][bj][m][n] = __builtin_amdgcn_mfma_f32_16x16x32_bf16(Bt[n][k], At[m][k], acc[ai][bj][m][n], 0, 0, 0); __builtin_amdgcn_s_setprio(0); } while (0)
; #define PG8_WAIT_V(n) asm volatile("s_waitcnt vmcnt(" #n ")" ::: "memory")
; #define PG8_WAIT_L(n) asm volatile("s_waitcnt lgkmcnt(" #n ")" ::: "memory")
; #define PG8_BAR __builtin_amdgcn_s_barrier()
; #define PG8_SCHED __builtin_amdgcn_sched_barrier(0)
; template <class Epi, class Sched, bool ALIGN_EPI = false, bool SP2 = false>
; __device__ __forceinline__ void gemm_phase(PG8_LAS unsigned char* lds, const Gemm g, const Sched& S, const Epi& E) {
;     ...
;             PG8_LDB(B0, 0, 0); PG8_LDB(B1, 0, 1); PG8_SCHED; PG8_LDA(At, 0, 0); PG8_STAGE(PG8_SA(1, 1), a1 + hstepA, voffA);
;             PG8_WAIT_V(8); PG8_WAIT_L(0); PG8_BAR; PG8_MMA(0, 0, At, B0); PG8_MMA(0, 1, At, B1); PG8_BAR; PG8_SCHED;
;             PG8_LDA(At, 0, 1); PG8_STAGE(PG8_SB(0, 0), b2, voffB); PG8_STAGE(PG8_SB(0, 1), b2 + hstepB, voffB); PG8_STAGE(PG8_SA(0, 0), a2, voffA);
.LBB0_908:
	ds_read_b128 v[158:161], v155
	ds_read_b128 v[164:167], v155 offset:1024
	ds_read_b128 v[168:171], v155 offset:2048
	ds_read_b128 v[172:175], v155 offset:3072
	ds_read_b128 v[176:179], v156
	ds_read_b128 v[180:183], v156 offset:1024
	ds_read_b128 v[184:187], v156 offset:2048
	ds_read_b128 v[188:191], v156 offset:3072
	s_add_u32 s26, s24, 0xfff00080
	s_addc_u32 s27, s25, -1
	s_cmp_eq_u32 s55, 60
	s_cselect_b32 s29, s17, s27
	s_cselect_b32 s28, s47, s26
	s_cselect_b32 s27, s15, s54
	s_cselect_b32 s26, s52, s53
	v_lshl_add_u64 v[146:147], s[24:25], 0, v[138:139]
	s_add_i32 m0, s23, 0xc000
	ds_read_b128 v[192:195], v157
	ds_read_b128 v[196:199], v157 offset:1024
	ds_read_b128 v[200:203], v157 offset:2048
	ds_read_b128 v[204:207], v157 offset:3072
	ds_read_b128 v[208:211], v157 offset:4096
	ds_read_b128 v[212:215], v157 offset:5120
	ds_read_b128 v[216:219], v157 offset:6144
	ds_read_b128 v[220:223], v157 offset:7168
	global_load_lds_dwordx4 v[146:147], off
	v_lshl_add_u64 v[146:147], s[24:25], 0, v[140:141]
	s_add_i32 m0, s23, 0xe000
	s_nop 0
	global_load_lds_dwordx4 v[146:147], off
	s_waitcnt vmcnt(8)
	s_waitcnt lgkmcnt(0)
	s_barrier
	s_setprio 3
	s_waitcnt lgkmcnt(0)
	v_mfma_f32_16x16x32_bf16 v[126:129], v[158:161], v[192:195], v[126:129]
	v_mfma_f32_16x16x32_bf16 v[126:129], v[164:167], v[196:199], v[126:129]
	v_mfma_f32_16x16x32_bf16 v[122:125], v[168:171], v[192:195], v[122:125]
	v_mfma_f32_16x16x32_bf16 v[122:125], v[172:175], v[196:199], v[122:125]
	v_mfma_f32_16x16x32_bf16 v[106:109], v[168:171], v[200:203], v[106:109]
	v_mfma_f32_16x16x32_bf16 v[106:109], v[172:175], v[204:207], v[106:109]
	v_mfma_f32_16x16x32_bf16 v[114:117], v[158:161], v[200:203], v[114:117]
	v_mfma_f32_16x16x32_bf16 v[114:117], v[164:167], v[204:207], v[114:117]
	v_mfma_f32_16x16x32_bf16 v[98:101], v[158:161], v[208:211], v[98:101]
	v_mfma_f32_16x16x32_bf16 v[98:101], v[164:167], v[212:215], v[98:101]
	v_mfma_f32_16x16x32_bf16 v[90:93], v[168:171], v[208:211], v[90:93]
	v_mfma_f32_16x16x32_bf16 v[90:93], v[172:175], v[212:215], v[90:93]
	v_mfma_f32_16x16x32_bf16 v[74:77], v[168:171], v[216:219], v[74:77]
	v_mfma_f32_16x16x32_bf16 v[74:77], v[172:175], v[220:223], v[74:77]
	v_mfma_f32_16x16x32_bf16 v[82:85], v[158:161], v[216:219], v[82:85]
	v_mfma_f32_16x16x32_bf16 v[82:85], v[164:167], v[220:223], v[82:85]
	v_mfma_f32_16x16x32_bf16 v[118:121], v[176:179], v[192:195], v[118:121]
	v_mfma_f32_16x16x32_bf16 v[118:121], v[180:183], v[196:199], v[118:121]
	v_mfma_f32_16x16x32_bf16 v[110:113], v[184:187], v[192:195], v[110:113]
	v_mfma_f32_16x16x32_bf16 v[110:113], v[188:191], v[196:199], v[110:113]
	v_mfma_f32_16x16x32_bf16 v[94:97], v[184:187], v[200:203], v[94:97]
	v_mfma_f32_16x16x32_bf16 v[94:97], v[188:191], v[204:207], v[94:97]
	v_mfma_f32_16x16x32_bf16 v[102:105], v[176:179], v[200:203], v[102:105]
	v_mfma_f32_16x16x32_bf16 v[102:105], v[180:183], v[204:207], v[102:105]
	v_mfma_f32_16x16x32_bf16 v[86:89], v[176:179], v[208:211], v[86:89]
	v_mfma_f32_16x16x32_bf16 v[86:89], v[180:183], v[212:215], v[86:89]
	v_mfma_f32_16x16x32_bf16 v[78:81], v[184:187], v[208:211], v[78:81]
	v_mfma_f32_16x16x32_bf16 v[78:81], v[188:191], v[212:215], v[78:81]
	v_mfma_f32_16x16x32_bf16 v[66:69], v[184:187], v[216:219], v[66:69]
	v_mfma_f32_16x16x32_bf16 v[66:69], v[188:191], v[220:223], v[66:69]
	v_mfma_f32_16x16x32_bf16 v[70:73], v[176:179], v[216:219], v[70:73]
	v_mfma_f32_16x16x32_bf16 v[70:73], v[180:183], v[220:223], v[70:73]
	s_setprio 0
	s_barrier
	s_add_i32 s56, s42, s30
	v_lshl_add_u64 v[146:147], s[26:27], 0, v[134:135]
	s_mov_b32 m0, s56
	ds_read_b128 v[192:195], v157 offset:16384
	ds_read_b128 v[196:199], v157 offset:17408
	ds_read_b128 v[200:203], v157 offset:18432
	ds_read_b128 v[204:207], v157 offset:19456
	ds_read_b128 v[208:211], v157 offset:20480
	ds_read_b128 v[212:215], v157 offset:21504
	ds_read_b128 v[216:219], v157 offset:22528
	ds_read_b128 v[220:223], v157 offset:23552
	global_load_lds_dwordx4 v[146:147], off
	s_add_i32 m0, s56, 0x2000
	s_add_u32 s56, s26, 0x100000
	v_lshl_add_u64 v[224:225], s[26:27], 0, v[130:131]
	s_addc_u32 s57, s27, 0
	s_add_i32 s58, s43, s30
	global_load_lds_dwordx4 v[224:225], off
	v_lshl_add_u64 v[226:227], s[56:57], 0, v[134:135]
	s_mov_b32 m0, s58
	v_lshl_add_u64 v[228:229], s[28:29], 0, v[132:133]
	global_load_lds_dwordx4 v[226:227], off
	v_lshl_add_u64 v[226:227], s[56:57], 0, v[130:131]
	s_add_i32 m0, s58, 0x2000
	s_nop 0
	global_load_lds_dwordx4 v[226:227], off
	v_lshl_add_u64 v[226:227], s[28:29], 0, v[136:137]
	s_mov_b32 m0, s23
	s_nop 0
	global_load_lds_dwordx4 v[226:227], off
	s_mov_b32 m0, s33
	s_nop 0
	global_load_lds_dwordx4 v[228:229], off
	s_waitcnt vmcnt(8)
	s_waitcnt lgkmcnt(0)
	s_barrier
; #define PG8_STAGE(bufoff, gbase, voff) do { _Pragma("unroll") for (int _i = 0; _i < 2; ++_i) \
;         __builtin_amdgcn_global_load_lds((const unsigned*)((const char*)(gbase) + (voff)[_i]), (PG8_LAS unsigned*)(lds + (bufoff) + ldsw + _i * 8192), 16, 0, 0); } while (0)
; #define PG8_LDA(dst, b, h) do { _Pragma("unroll") for (int m = 0; m < 4; ++m) _Pragma("unroll") for (int k = 0; k < 2; ++k) dst[m][k] = *(const PG8_LAS bf16x8*)(lds + PG8_SA(b, h) + aoff + m * 2048 + k * 1024); } while (0)
; #define PG8_LDB(dst, b, h) do { _Pragma("unroll") for (int n = 0; n < 2; ++n) _Pragma("unroll") for (int k = 0; k < 2; ++k) dst[n][k] = *(const PG8_LAS bf16x8*)(lds + PG8_SB(b, h) + boff + n * 2048 + k * 1024); } while (0)
; #define PG8_MMA(ai, bj, At, Bt) do { __builtin_amdgcn_s_setprio(3); _Pragma("unroll") for (int m = 0; m < 4; ++m) _Pragma("unroll") for (int n = 0; n < 2; ++n) _Pragma("unroll") for (int k = 0; k < 2; ++k) \
;         acc[ai][bj][m][n] = __builtin_amdgcn_mfma_f32_16x16x32_bf16(Bt[n][k], At[m][k], acc[ai][bj][m][n], 0, 0, 0); __builtin_amdgcn_s_setprio(0); } while (0)
; #define PG8_WAIT_V(n) asm volatile("s_waitcnt vmcnt(" #n ")" ::: "memory")
; #define PG8_WAIT_L(n) asm volatile("s_waitcnt lgkmcnt(" #n ")" ::: "memory")
; #define PG8_BAR __builtin_amdgcn_s_barrier()
; #define PG8_SCHED __builtin_amdgcn_sched_barrier(0)
; template <class Epi, class Sched, bool ALIGN_EPI = false, bool SP2 = false>
; __device__ __forceinline__ void gemm_phase(PG8_LAS unsigned char* lds, const Gemm g, const Sched& S, const Epi& E) {
;     ...
;             PG8_WAIT_V(8); PG8_WAIT_L(0); PG8_BAR; PG8_MMA(1, 0, At, B0); PG8_MMA(1, 1, At, B1); PG8_BAR; PG8_SCHED;
;             PG8_LDB(B0, 1, 0); PG8_LDB(B1, 1, 1); PG8_SCHED; PG8_LDA(At, 1, 0); PG8_STAGE(PG8_SA(0, 1), a2 + hstepA, voffA);
;             PG8_WAIT_V(8); PG8_WAIT_L(0); PG8_BAR; PG8_MMA(0, 0, At, B0); PG8_MMA(0, 1, At, B1); PG8_BAR; PG8_SCHED;
	s_setprio 3
	s_waitcnt lgkmcnt(0)
	v_mfma_f32_16x16x32_bf16 v[62:65], v[158:161], v[192:195], v[62:65]
	v_mfma_f32_16x16x32_bf16 v[62:65], v[164:167], v[196:199], v[62:65]
	v_mfma_f32_16x16x32_bf16 v[58:61], v[168:171], v[192:195], v[58:61]
	v_mfma_f32_16x16x32_bf16 v[58:61], v[172:175], v[196:199], v[58:61]
	v_mfma_f32_16x16x32_bf16 v[42:45], v[168:171], v[200:203], v[42:45]
	v_mfma_f32_16x16x32_bf16 v[42:45], v[172:175], v[204:207], v[42:45]
	v_mfma_f32_16x16x32_bf16 v[50:53], v[158:161], v[200:203], v[50:53]
	v_mfma_f32_16x16x32_bf16 v[50:53], v[164:167], v[204:207], v[50:53]
	v_mfma_f32_16x16x32_bf16 v[34:37], v[158:161], v[208:211], v[34:37]
	v_mfma_f32_16x16x32_bf16 v[34:37], v[164:167], v[212:215], v[34:37]
	v_mfma_f32_16x16x32_bf16 v[26:29], v[168:171], v[208:211], v[26:29]
	v_mfma_f32_16x16x32_bf16 v[26:29], v[172:175], v[212:215], v[26:29]
	v_mfma_f32_16x16x32_bf16 v[10:13], v[168:171], v[216:219], v[10:13]
	v_mfma_f32_16x16x32_bf16 v[10:13], v[172:175], v[220:223], v[10:13]
	v_mfma_f32_16x16x32_bf16 v[14:17], v[158:161], v[216:219], v[14:17]
	v_mfma_f32_16x16x32_bf16 v[14:17], v[164:167], v[220:223], v[14:17]
	v_mfma_f32_16x16x32_bf16 v[54:57], v[176:179], v[192:195], v[54:57]
	v_mfma_f32_16x16x32_bf16 v[54:57], v[180:183], v[196:199], v[54:57]
	v_mfma_f32_16x16x32_bf16 v[46:49], v[184:187], v[192:195], v[46:49]
	v_mfma_f32_16x16x32_bf16 v[46:49], v[188:191], v[196:199], v[46:49]
	v_mfma_f32_16x16x32_bf16 v[30:33], v[184:187], v[200:203], v[30:33]
	v_mfma_f32_16x16x32_bf16 v[30:33], v[188:191], v[204:207], v[30:33]
	v_mfma_f32_16x16x32_bf16 v[38:41], v[176:179], v[200:203], v[38:41]
	v_mfma_f32_16x16x32_bf16 v[38:41], v[180:183], v[204:207], v[38:41]
	v_mfma_f32_16x16x32_bf16 v[22:25], v[176:179], v[208:211], v[22:25]
	v_mfma_f32_16x16x32_bf16 v[22:25], v[180:183], v[212:215], v[22:25]
	v_mfma_f32_16x16x32_bf16 v[18:21], v[184:187], v[208:211], v[18:21]
	v_mfma_f32_16x16x32_bf16 v[18:21], v[188:191], v[212:215], v[18:21]
	v_mfma_f32_16x16x32_bf16 v[2:5], v[184:187], v[216:219], v[2:5]
	v_mfma_f32_16x16x32_bf16 v[2:5], v[188:191], v[220:223], v[2:5]
	v_mfma_f32_16x16x32_bf16 v[6:9], v[176:179], v[216:219], v[6:9]
	v_mfma_f32_16x16x32_bf16 v[6:9], v[180:183], v[220:223], v[6:9]
	s_setprio 0
	s_barrier
	s_add_i32 s56, 0, 0x18000
	v_add_u32_e32 v148, s56, v151
	s_add_i32 s57, 0, 0x1c000
	ds_read_b128 v[158:161], v148
	ds_read_b128 v[164:167], v148 offset:1024
	ds_read_b128 v[168:171], v148 offset:2048
	ds_read_b128 v[172:175], v148 offset:3072
	v_add_u32_e32 v148, s57, v151
	ds_read_b128 v[176:179], v148
	ds_read_b128 v[180:183], v148 offset:1024
	ds_read_b128 v[184:187], v148 offset:2048
	ds_read_b128 v[188:191], v148 offset:3072
	s_add_u32 s28, s28, 0x100000
	s_addc_u32 s29, s29, 0
	s_mov_b32 m0, s36
	v_lshl_add_u64 v[230:231], s[28:29], 0, v[136:137]
	ds_read_b128 v[192:195], v157 offset:32768
	ds_read_b128 v[196:199], v157 offset:33792
	ds_read_b128 v[200:203], v157 offset:34816
	ds_read_b128 v[204:207], v157 offset:35840
	ds_read_b128 v[208:211], v157 offset:36864
	ds_read_b128 v[212:215], v157 offset:37888
	ds_read_b128 v[216:219], v157 offset:38912
	ds_read_b128 v[220:223], v157 offset:39936
	global_load_lds_dwordx4 v[230:231], off
	v_lshl_add_u64 v[230:231], s[28:29], 0, v[132:133]
	s_mov_b32 m0, s37
	s_nop 0
	global_load_lds_dwordx4 v[230:231], off
	s_waitcnt vmcnt(8)
	s_waitcnt lgkmcnt(0)
	s_barrier
	s_setprio 3
	s_waitcnt lgkmcnt(0)
	v_mfma_f32_16x16x32_bf16 v[126:129], v[158:161], v[192:195], v[126:129]
	v_mfma_f32_16x16x32_bf16 v[126:129], v[164:167], v[196:199], v[126:129]
	v_mfma_f32_16x16x32_bf16 v[122:125], v[168:171], v[192:195], v[122:125]
	v_mfma_f32_16x16x32_bf16 v[122:125], v[172:175], v[196:199], v[122:125]
	v_mfma_f32_16x16x32_bf16 v[106:109], v[168:171], v[200:203], v[106:109]
	v_mfma_f32_16x16x32_bf16 v[106:109], v[172:175], v[204:207], v[106:109]
	v_mfma_f32_16x16x32_bf16 v[114:117], v[158:161], v[200:203], v[114:117]
	v_mfma_f32_16x16x32_bf16 v[114:117], v[164:167], v[204:207], v[114:117]
	v_mfma_f32_16x16x32_bf16 v[98:101], v[158:161], v[208:211], v[98:101]
	v_mfma_f32_16x16x32_bf16 v[98:101], v[164:167], v[212:215], v[98:101]
	v_mfma_f32_16x16x32_bf16 v[90:93], v[168:171], v[208:211], v[90:93]
	v_mfma_f32_16x16x32_bf16 v[90:93], v[172:175], v[212:215], v[90:93]
	v_mfma_f32_16x16x32_bf16 v[74:77], v[168:171], v[216:219], v[74:77]
	v_mfma_f32_16x16x32_bf16 v[74:77], v[172:175], v[220:223], v[74:77]
	v_mfma_f32_16x16x32_bf16 v[82:85], v[158:161], v[216:219], v[82:85]
	v_mfma_f32_16x16x32_bf16 v[82:85], v[164:167], v[220:223], v[82:85]
	v_mfma_f32_16x16x32_bf16 v[118:121], v[176:179], v[192:195], v[118:121]
	v_mfma_f32_16x16x32_bf16 v[118:121], v[180:183], v[196:199], v[118:121]
	v_mfma_f32_16x16x32_bf16 v[110:113], v[184:187], v[192:195], v[110:113]
	v_mfma_f32_16x16x32_bf16 v[110:113], v[188:191], v[196:199], v[110:113]
	v_mfma_f32_16x16x32_bf16 v[94:97], v[184:187], v[200:203], v[94:97]
	v_mfma_f32_16x16x32_bf16 v[94:97], v[188:191], v[204:207], v[94:97]
	v_mfma_f32_16x16x32_bf16 v[102:105], v[176:179], v[200:203], v[102:105]
	v_mfma_f32_16x16x32_bf16 v[102:105], v[180:183], v[204:207], v[102:105]
	v_mfma_f32_16x16x32_bf16 v[86:89], v[176:179], v[208:211], v[86:89]
	v_mfma_f32_16x16x32_bf16 v[86:89], v[180:183], v[212:215], v[86:89]
	v_mfma_f32_16x16x32_bf16 v[78:81], v[184:187], v[208:211], v[78:81]
	v_mfma_f32_16x16x32_bf16 v[78:81], v[188:191], v[212:215], v[78:81]
	v_mfma_f32_16x16x32_bf16 v[66:69], v[184:187], v[216:219], v[66:69]
	v_mfma_f32_16x16x32_bf16 v[66:69], v[188:191], v[220:223], v[66:69]
	v_mfma_f32_16x16x32_bf16 v[70:73], v[176:179], v[216:219], v[70:73]
	v_mfma_f32_16x16x32_bf16 v[70:73], v[180:183], v[220:223], v[70:73]
	s_setprio 0
	s_barrier
; #define PG8_STAGE(bufoff, gbase, voff) do { _Pragma("unroll") for (int _i = 0; _i < 2; ++_i) \
;         __builtin_amdgcn_global_load_lds((const unsigned*)((const char*)(gbase) + (voff)[_i]), (PG8_LAS unsigned*)(lds + (bufoff) + ldsw + _i * 8192), 16, 0, 0); } while (0)
; #define PG8_LDA(dst, b, h) do { _Pragma("unroll") for (int m = 0; m < 4; ++m) _Pragma("unroll") for (int k = 0; k < 2; ++k) dst[m][k] = *(const PG8_LAS bf16x8*)(lds + PG8_SA(b, h) + aoff + m * 2048 + k * 1024); } while (0)
; #define PG8_MMA(ai, bj, At, Bt) do { __builtin_amdgcn_s_setprio(3); _Pragma("unroll") for (int m = 0; m < 4; ++m) _Pragma("unroll") for (int n = 0; n < 2; ++n) _Pragma("unroll") for (int k = 0; k < 2; ++k) \
;         acc[ai][bj][m][n] = __builtin_amdgcn_mfma_f32_16x16x32_bf16(Bt[n][k], At[m][k], acc[ai][bj][m][n], 0, 0, 0); __builtin_amdgcn_s_setprio(0); } while (0)
; #define PG8_WAIT_V(n) asm volatile("s_waitcnt vmcnt(" #n ")" ::: "memory")
; #define PG8_WAIT_L(n) asm volatile("s_waitcnt lgkmcnt(" #n ")" ::: "memory")
; #define PG8_BAR __builtin_amdgcn_s_barrier()
; #define PG8_SCHED __builtin_amdgcn_sched_barrier(0)
; template <class Epi, class Sched, bool ALIGN_EPI = false, bool SP2 = false>
; __device__ __forceinline__ void gemm_phase(PG8_LAS unsigned char* lds, const Gemm g, const Sched& S, const Epi& E) {
;     ...
;             PG8_LDA(At, 1, 1); PG8_STAGE(PG8_SB(1, 0), b3, voffB); PG8_STAGE(PG8_SB(1, 1), b3 + hstepB, voffB); PG8_STAGE(PG8_SA(1, 0), a3, voffA);
;             PG8_WAIT_V(8); PG8_WAIT_L(0); PG8_BAR; PG8_MMA(1, 0, At, B0); PG8_MMA(1, 1, At, B1); PG8_BAR; PG8_SCHED;
;     ...
;         if constexpr (ALIGN_EPI) { if (wr == 0) PG8_BAR; }
	s_add_i32 s28, s56, s30
	v_lshl_add_u64 v[146:147], v[146:147], 0, s[12:13]
	s_mov_b32 m0, s28
	ds_read_b128 v[192:195], v157 offset:49152
	ds_read_b128 v[196:199], v157 offset:50176
	ds_read_b128 v[200:203], v157 offset:51200
	ds_read_b128 v[204:207], v157 offset:52224
	ds_read_b128 v[208:211], v157 offset:53248
	ds_read_b128 v[212:215], v157 offset:54272
	ds_read_b128 v[216:219], v157 offset:55296
	ds_read_b128 v[220:223], v157 offset:56320
	global_load_lds_dwordx4 v[146:147], off
	s_add_i32 m0, s28, 0x2000
	s_add_u32 s26, s26, 0x100080
	v_lshl_add_u64 v[146:147], v[224:225], 0, s[12:13]
	s_addc_u32 s27, s27, 0
	s_add_i32 s28, s57, s30
	global_load_lds_dwordx4 v[146:147], off
	v_lshl_add_u64 v[146:147], s[26:27], 0, v[134:135]
	s_mov_b32 m0, s28
	s_nop 0
	global_load_lds_dwordx4 v[146:147], off
	v_lshl_add_u64 v[146:147], s[26:27], 0, v[130:131]
	s_add_i32 m0, s28, 0x2000
	s_nop 0
	global_load_lds_dwordx4 v[146:147], off
	v_lshl_add_u64 v[146:147], v[226:227], 0, s[12:13]
	s_mov_b32 m0, s39
	s_nop 0
	global_load_lds_dwordx4 v[146:147], off
	v_lshl_add_u64 v[146:147], v[228:229], 0, s[12:13]
	s_mov_b32 m0, s40
	s_nop 0
	global_load_lds_dwordx4 v[146:147], off
	s_waitcnt vmcnt(8)
	s_waitcnt lgkmcnt(0)
	s_barrier
	s_setprio 3
	s_waitcnt lgkmcnt(0)
	v_mfma_f32_16x16x32_bf16 v[62:65], v[158:161], v[192:195], v[62:65]
	v_mfma_f32_16x16x32_bf16 v[62:65], v[164:167], v[196:199], v[62:65]
	v_mfma_f32_16x16x32_bf16 v[58:61], v[168:171], v[192:195], v[58:61]
	v_mfma_f32_16x16x32_bf16 v[58:61], v[172:175], v[196:199], v[58:61]
	v_mfma_f32_16x16x32_bf16 v[42:45], v[168:171], v[200:203], v[42:45]
	v_mfma_f32_16x16x32_bf16 v[42:45], v[172:175], v[204:207], v[42:45]
	v_mfma_f32_16x16x32_bf16 v[50:53], v[158:161], v[200:203], v[50:53]
	v_mfma_f32_16x16x32_bf16 v[50:53], v[164:167], v[204:207], v[50:53]
	v_mfma_f32_16x16x32_bf16 v[34:37], v[158:161], v[208:211], v[34:37]
	v_mfma_f32_16x16x32_bf16 v[34:37], v[164:167], v[212:215], v[34:37]
	v_mfma_f32_16x16x32_bf16 v[26:29], v[168:171], v[208:211], v[26:29]
	v_mfma_f32_16x16x32_bf16 v[26:29], v[172:175], v[212:215], v[26:29]
	v_mfma_f32_16x16x32_bf16 v[10:13], v[168:171], v[216:219], v[10:13]
	v_mfma_f32_16x16x32_bf16 v[10:13], v[172:175], v[220:223], v[10:13]
	v_mfma_f32_16x16x32_bf16 v[14:17], v[158:161], v[216:219], v[14:17]
	v_mfma_f32_16x16x32_bf16 v[14:17], v[164:167], v[220:223], v[14:17]
	v_mfma_f32_16x16x32_bf16 v[54:57], v[176:179], v[192:195], v[54:57]
	v_mfma_f32_16x16x32_bf16 v[54:57], v[180:183], v[196:199], v[54:57]
	v_mfma_f32_16x16x32_bf16 v[46:49], v[184:187], v[192:195], v[46:49]
	v_mfma_f32_16x16x32_bf16 v[46:49], v[188:191], v[196:199], v[46:49]
	v_mfma_f32_16x16x32_bf16 v[30:33], v[184:187], v[200:203], v[30:33]
	v_mfma_f32_16x16x32_bf16 v[30:33], v[188:191], v[204:207], v[30:33]
	v_mfma_f32_16x16x32_bf16 v[38:41], v[176:179], v[200:203], v[38:41]
	v_mfma_f32_16x16x32_bf16 v[38:41], v[180:183], v[204:207], v[38:41]
	v_mfma_f32_16x16x32_bf16 v[22:25], v[176:179], v[208:211], v[22:25]
	v_mfma_f32_16x16x32_bf16 v[22:25], v[180:183], v[212:215], v[22:25]
	v_mfma_f32_16x16x32_bf16 v[18:21], v[184:187], v[208:211], v[18:21]
	v_mfma_f32_16x16x32_bf16 v[18:21], v[188:191], v[212:215], v[18:21]
	v_mfma_f32_16x16x32_bf16 v[2:5], v[184:187], v[216:219], v[2:5]
	v_mfma_f32_16x16x32_bf16 v[2:5], v[188:191], v[220:223], v[2:5]
	v_mfma_f32_16x16x32_bf16 v[6:9], v[176:179], v[216:219], v[6:9]
	v_mfma_f32_16x16x32_bf16 v[6:9], v[180:183], v[220:223], v[6:9]
	s_setprio 0
	s_barrier
	s_add_i32 s55, s55, 2
	s_add_u32 s24, s24, 0x100
	s_addc_u32 s25, s25, 0
	s_add_u32 s53, s53, 0x100
	s_addc_u32 s54, s54, 0
	s_cmp_gt_u32 s55, 61
	s_cbranch_scc0 .LBB0_908
	s_and_b64 vcc, exec, s[0:1]
	s_cbranch_vccz .LBB0_911
	s_barrier

; #define PG8_STAGE(bufoff, gbase, voff) do { _Pragma("unroll") for (int _i = 0; _i < 2; ++_i) \
;         __builtin_amdgcn_global_load_lds((const unsigned*)((const char*)(gbase) + (voff)[_i]), (PG8_LAS unsigned*)(lds + (bufoff) + ldsw + _i * 8192), 16, 0, 0); } while (0)
; #define PG8_LDA(dst, b, h) do { _Pragma("unroll") for (int m = 0; m < 4; ++m) _Pragma("unroll") for (int k = 0; k < 2; ++k) dst[m][k] = *(const PG8_LAS bf16x8*)(lds + PG8_SA(b, h) + aoff + m * 2048 + k * 1024); } while (0)
; #define PG8_LDB(dst, b, h) do { _Pragma("unroll") for (int n = 0; n < 2; ++n) _Pragma("unroll") for (int k = 0; k < 2; ++k) dst[n][k] = *(const PG8_LAS bf16x8*)(lds + PG8_SB(b, h) + boff + n * 2048 + k * 1024); } while (0)
; #define PG8_MMA(ai, bj, At, Bt) do { __builtin_amdgcn_s_setprio(3); _Pragma("unroll") for (int m = 0; m < 4; ++m) _Pragma("unroll") for (int n = 0; n < 2; ++n) _Pragma("unroll") for (int k = 0; k < 2; ++k) \
;         acc[ai][bj][m][n] = __builtin_amdgcn_mfma_f32_16x16x32_bf16(Bt[n][k], At[m][k], acc[ai][bj][m][n], 0, 0, 0); __builtin_amdgcn_s_setprio(0); } while (0)
; #define PG8_WAIT_V(n) asm volatile("s_waitcnt vmcnt(" #n ")" ::: "memory")
; #define PG8_WAIT_L(n) asm volatile("s_waitcnt lgkmcnt(" #n ")" ::: "memory")
; #define PG8_BAR __builtin_amdgcn_s_barrier()
; #define PG8_SCHED __builtin_amdgcn_sched_barrier(0)
; template <class Epi, class Sched, bool ALIGN_EPI = false, bool SP2 = false>
; __device__ __forceinline__ void gemm_phase(PG8_LAS unsigned char* lds, const Gemm g, const Sched& S, const Epi& E) {
;     ...
;             PG8_LDB(B0, 0, 0); PG8_LDB(B1, 0, 1); PG8_SCHED; PG8_LDA(At, 0, 0); PG8_STAGE(PG8_SA(1, 1), a1 + hstepA, voffA);
;             PG8_WAIT_V(8); PG8_WAIT_L(0); PG8_BAR; PG8_MMA(0, 0, At, B0); PG8_MMA(0, 1, At, B1); PG8_BAR; PG8_SCHED;
;             PG8_LDA(At, 0, 1); PG8_STAGE(PG8_SB(0, 0), b2, voffB); PG8_STAGE(PG8_SB(0, 1), b2 + hstepB, voffB); PG8_STAGE(PG8_SA(0, 0), a2, voffA);
.LBB0_975:
	v_add_u32_e32 v144, s46, v206
	v_add_u32_e32 v160, s47, v206
	s_add_u32 s28, s2, s12
	ds_read_b128 v[132:135], v144
	ds_read_b128 v[136:139], v144 offset:1024
	ds_read_b128 v[140:143], v144 offset:2048
	ds_read_b128 v[144:147], v144 offset:3072
	ds_read_b128 v[148:151], v160
	ds_read_b128 v[152:155], v160 offset:1024
	ds_read_b128 v[156:159], v160 offset:2048
	ds_read_b128 v[160:163], v160 offset:3072
	s_addc_u32 s29, s3, s13
	s_add_u32 s28, s28, 0x21500100
	s_addc_u32 s29, s29, 0
	s_add_u32 s81, s44, s12
	s_addc_u32 s82, s45, s13
	s_cmpk_eq_i32 s12, 0x5500
	s_cselect_b32 s31, s1, s29
	s_cselect_b32 s30, s0, s28
	s_cselect_b32 s29, s11, s82
	s_cselect_b32 s28, s10, s81
	s_mov_b32 m0, s71
	v_lshl_add_u64 v[234:235], v[2:3], 0, s[12:13]
	ds_read_b128 v[164:167], v207
	ds_read_b128 v[168:171], v207 offset:1024
	ds_read_b128 v[210:213], v207 offset:2048
	ds_read_b128 v[214:217], v207 offset:3072
	ds_read_b128 v[218:221], v207 offset:4096
	ds_read_b128 v[222:225], v207 offset:5120
	ds_read_b128 v[226:229], v207 offset:6144
	ds_read_b128 v[230:233], v207 offset:7168
	global_load_lds_dwordx4 v[234:235], off
	v_lshl_add_u64 v[234:235], v[200:201], 0, s[12:13]
	s_mov_b32 m0, s72
	s_nop 0
	global_load_lds_dwordx4 v[234:235], off
	s_waitcnt vmcnt(8)
	s_waitcnt lgkmcnt(0)
	s_barrier
	s_setprio 3
	s_waitcnt lgkmcnt(0)
	v_mfma_f32_16x16x32_bf16 v[128:131], v[132:135], v[164:167], v[128:131]
	v_mfma_f32_16x16x32_bf16 v[128:131], v[136:139], v[168:171], v[128:131]
	v_mfma_f32_16x16x32_bf16 v[124:127], v[140:143], v[164:167], v[124:127]
	v_mfma_f32_16x16x32_bf16 v[124:127], v[144:147], v[168:171], v[124:127]
	v_mfma_f32_16x16x32_bf16 v[96:99], v[140:143], v[210:213], v[96:99]
	v_mfma_f32_16x16x32_bf16 v[96:99], v[144:147], v[214:217], v[96:99]
	v_mfma_f32_16x16x32_bf16 v[100:103], v[132:135], v[210:213], v[100:103]
	v_mfma_f32_16x16x32_bf16 v[100:103], v[136:139], v[214:217], v[100:103]
	v_mfma_f32_16x16x32_bf16 v[112:115], v[132:135], v[218:221], v[112:115]
	v_mfma_f32_16x16x32_bf16 v[112:115], v[136:139], v[222:225], v[112:115]
	v_mfma_f32_16x16x32_bf16 v[108:111], v[140:143], v[218:221], v[108:111]
	v_mfma_f32_16x16x32_bf16 v[108:111], v[144:147], v[222:225], v[108:111]
	v_mfma_f32_16x16x32_bf16 v[76:79], v[140:143], v[226:229], v[76:79]
	v_mfma_f32_16x16x32_bf16 v[76:79], v[144:147], v[230:233], v[76:79]
	v_mfma_f32_16x16x32_bf16 v[80:83], v[132:135], v[226:229], v[80:83]
	v_mfma_f32_16x16x32_bf16 v[80:83], v[136:139], v[230:233], v[80:83]
	v_mfma_f32_16x16x32_bf16 v[120:123], v[148:151], v[164:167], v[120:123]
	v_mfma_f32_16x16x32_bf16 v[120:123], v[152:155], v[168:171], v[120:123]
	v_mfma_f32_16x16x32_bf16 v[116:119], v[156:159], v[164:167], v[116:119]
	v_mfma_f32_16x16x32_bf16 v[116:119], v[160:163], v[168:171], v[116:119]
	v_mfma_f32_16x16x32_bf16 v[88:91], v[156:159], v[210:213], v[88:91]
	v_mfma_f32_16x16x32_bf16 v[88:91], v[160:163], v[214:217], v[88:91]
	v_mfma_f32_16x16x32_bf16 v[92:95], v[148:151], v[210:213], v[92:95]
	v_mfma_f32_16x16x32_bf16 v[92:95], v[152:155], v[214:217], v[92:95]
	v_mfma_f32_16x16x32_bf16 v[104:107], v[148:151], v[218:221], v[104:107]
	v_mfma_f32_16x16x32_bf16 v[104:107], v[152:155], v[222:225], v[104:107]
	v_mfma_f32_16x16x32_bf16 v[84:87], v[156:159], v[218:221], v[84:87]
	v_mfma_f32_16x16x32_bf16 v[84:87], v[160:163], v[222:225], v[84:87]
	v_mfma_f32_16x16x32_bf16 v[68:71], v[156:159], v[226:229], v[68:71]
	v_mfma_f32_16x16x32_bf16 v[68:71], v[160:163], v[230:233], v[68:71]
	v_mfma_f32_16x16x32_bf16 v[72:75], v[148:151], v[226:229], v[72:75]
	v_mfma_f32_16x16x32_bf16 v[72:75], v[152:155], v[230:233], v[72:75]
	s_setprio 0
	s_barrier
	s_mov_b32 m0, s73
	v_lshl_add_u64 v[234:235], s[28:29], 0, v[174:175]
	s_add_u32 s82, s28, 0x2b0000
	ds_read_b128 v[164:167], v207 offset:16384
	ds_read_b128 v[168:171], v207 offset:17408
	ds_read_b128 v[210:213], v207 offset:18432
	ds_read_b128 v[214:217], v207 offset:19456
	ds_read_b128 v[218:221], v207 offset:20480
	ds_read_b128 v[222:225], v207 offset:21504
	ds_read_b128 v[226:229], v207 offset:22528
	ds_read_b128 v[230:233], v207 offset:23552
	global_load_lds_dwordx4 v[234:235], off
	v_lshl_add_u64 v[236:237], s[28:29], 0, v[178:179]
	s_mov_b32 m0, s74
	s_addc_u32 s83, s29, 0
	global_load_lds_dwordx4 v[236:237], off
	v_lshl_add_u64 v[238:239], s[82:83], 0, v[174:175]
	s_mov_b32 m0, s75
	v_lshl_add_u64 v[240:241], s[30:31], 0, v[176:177]
	global_load_lds_dwordx4 v[238:239], off
	v_lshl_add_u64 v[238:239], s[82:83], 0, v[178:179]
	s_mov_b32 m0, s76
	s_nop 0
	global_load_lds_dwordx4 v[238:239], off
	v_lshl_add_u64 v[238:239], s[30:31], 0, v[172:173]
	s_mov_b32 m0, s42
	s_nop 0
	global_load_lds_dwordx4 v[238:239], off
	s_mov_b32 m0, s54
	s_nop 0
	global_load_lds_dwordx4 v[240:241], off
	s_waitcnt vmcnt(8)
	s_waitcnt lgkmcnt(0)
	s_barrier
; #define PG8_STAGE(bufoff, gbase, voff) do { _Pragma("unroll") for (int _i = 0; _i < 2; ++_i) \
;         __builtin_amdgcn_global_load_lds((const unsigned*)((const char*)(gbase) + (voff)[_i]), (PG8_LAS unsigned*)(lds + (bufoff) + ldsw + _i * 8192), 16, 0, 0); } while (0)
; #define PG8_LDA(dst, b, h) do { _Pragma("unroll") for (int m = 0; m < 4; ++m) _Pragma("unroll") for (int k = 0; k < 2; ++k) dst[m][k] = *(const PG8_LAS bf16x8*)(lds + PG8_SA(b, h) + aoff + m * 2048 + k * 1024); } while (0)
; #define PG8_LDB(dst, b, h) do { _Pragma("unroll") for (int n = 0; n < 2; ++n) _Pragma("unroll") for (int k = 0; k < 2; ++k) dst[n][k] = *(const PG8_LAS bf16x8*)(lds + PG8_SB(b, h) + boff + n * 2048 + k * 1024); } while (0)
; #define PG8_MMA(ai, bj, At, Bt) do { __builtin_amdgcn_s_setprio(3); _Pragma("unroll") for (int m = 0; m < 4; ++m) _Pragma("unroll") for (int n = 0; n < 2; ++n) _Pragma("unroll") for (int k = 0; k < 2; ++k) \
;         acc[ai][bj][m][n] = __builtin_amdgcn_mfma_f32_16x16x32_bf16(Bt[n][k], At[m][k], acc[ai][bj][m][n], 0, 0, 0); __builtin_amdgcn_s_setprio(0); } while (0)
; #define PG8_WAIT_V(n) asm volatile("s_waitcnt vmcnt(" #n ")" ::: "memory")
; #define PG8_WAIT_L(n) asm volatile("s_waitcnt lgkmcnt(" #n ")" ::: "memory")
; #define PG8_BAR __builtin_amdgcn_s_barrier()
; #define PG8_SCHED __builtin_amdgcn_sched_barrier(0)
; template <class Epi, class Sched, bool ALIGN_EPI = false, bool SP2 = false>
; __device__ __forceinline__ void gemm_phase(PG8_LAS unsigned char* lds, const Gemm g, const Sched& S, const Epi& E) {
;     ...
;             PG8_WAIT_V(8); PG8_WAIT_L(0); PG8_BAR; PG8_MMA(1, 0, At, B0); PG8_MMA(1, 1, At, B1); PG8_BAR; PG8_SCHED;
;             PG8_LDB(B0, 1, 0); PG8_LDB(B1, 1, 1); PG8_SCHED; PG8_LDA(At, 1, 0); PG8_STAGE(PG8_SA(0, 1), a2 + hstepA, voffA);
;             PG8_WAIT_V(8); PG8_WAIT_L(0); PG8_BAR; PG8_MMA(0, 0, At, B0); PG8_MMA(0, 1, At, B1); PG8_BAR; PG8_SCHED;
	s_setprio 3
	s_waitcnt lgkmcnt(0)
	v_mfma_f32_16x16x32_bf16 v[64:67], v[132:135], v[164:167], v[64:67]
	v_mfma_f32_16x16x32_bf16 v[64:67], v[136:139], v[168:171], v[64:67]
	v_mfma_f32_16x16x32_bf16 v[60:63], v[140:143], v[164:167], v[60:63]
	v_mfma_f32_16x16x32_bf16 v[60:63], v[144:147], v[168:171], v[60:63]
	v_mfma_f32_16x16x32_bf16 v[44:47], v[140:143], v[210:213], v[44:47]
	v_mfma_f32_16x16x32_bf16 v[44:47], v[144:147], v[214:217], v[44:47]
	v_mfma_f32_16x16x32_bf16 v[48:51], v[132:135], v[210:213], v[48:51]
	v_mfma_f32_16x16x32_bf16 v[48:51], v[136:139], v[214:217], v[48:51]
	v_mfma_f32_16x16x32_bf16 v[32:35], v[132:135], v[218:221], v[32:35]
	v_mfma_f32_16x16x32_bf16 v[32:35], v[136:139], v[222:225], v[32:35]
	v_mfma_f32_16x16x32_bf16 v[28:31], v[140:143], v[218:221], v[28:31]
	v_mfma_f32_16x16x32_bf16 v[28:31], v[144:147], v[222:225], v[28:31]
	v_mfma_f32_16x16x32_bf16 v[12:15], v[140:143], v[226:229], v[12:15]
	v_mfma_f32_16x16x32_bf16 v[12:15], v[144:147], v[230:233], v[12:15]
	v_mfma_f32_16x16x32_bf16 v[16:19], v[132:135], v[226:229], v[16:19]
	v_mfma_f32_16x16x32_bf16 v[16:19], v[136:139], v[230:233], v[16:19]
	v_mfma_f32_16x16x32_bf16 v[56:59], v[148:151], v[164:167], v[56:59]
	v_mfma_f32_16x16x32_bf16 v[56:59], v[152:155], v[168:171], v[56:59]
	v_mfma_f32_16x16x32_bf16 v[52:55], v[156:159], v[164:167], v[52:55]
	v_mfma_f32_16x16x32_bf16 v[52:55], v[160:163], v[168:171], v[52:55]
	v_mfma_f32_16x16x32_bf16 v[36:39], v[156:159], v[210:213], v[36:39]
	v_mfma_f32_16x16x32_bf16 v[36:39], v[160:163], v[214:217], v[36:39]
	v_mfma_f32_16x16x32_bf16 v[40:43], v[148:151], v[210:213], v[40:43]
	v_mfma_f32_16x16x32_bf16 v[40:43], v[152:155], v[214:217], v[40:43]
	v_mfma_f32_16x16x32_bf16 v[24:27], v[148:151], v[218:221], v[24:27]
	v_mfma_f32_16x16x32_bf16 v[24:27], v[152:155], v[222:225], v[24:27]
	v_mfma_f32_16x16x32_bf16 v[20:23], v[156:159], v[218:221], v[20:23]
	v_mfma_f32_16x16x32_bf16 v[20:23], v[160:163], v[222:225], v[20:23]
	v_mfma_f32_16x16x32_bf16 v[4:7], v[156:159], v[226:229], v[4:7]
	v_mfma_f32_16x16x32_bf16 v[4:7], v[160:163], v[230:233], v[4:7]
	v_mfma_f32_16x16x32_bf16 v[8:11], v[148:151], v[226:229], v[8:11]
	v_mfma_f32_16x16x32_bf16 v[8:11], v[152:155], v[230:233], v[8:11]
	s_setprio 0
	s_barrier
	v_add_u32_e32 v144, s52, v206
	v_add_u32_e32 v160, s53, v206
	ds_read_b128 v[132:135], v144
	ds_read_b128 v[136:139], v144 offset:1024
	ds_read_b128 v[140:143], v144 offset:2048
	ds_read_b128 v[144:147], v144 offset:3072
	ds_read_b128 v[148:151], v160
	ds_read_b128 v[152:155], v160 offset:1024
	ds_read_b128 v[156:159], v160 offset:2048
	ds_read_b128 v[160:163], v160 offset:3072
	s_add_u32 s30, s30, 0x2b0000
	s_addc_u32 s31, s31, 0
	s_mov_b32 m0, s55
	v_lshl_add_u64 v[242:243], s[30:31], 0, v[172:173]
	ds_read_b128 v[164:167], v207 offset:32768
	ds_read_b128 v[168:171], v207 offset:33792
	ds_read_b128 v[210:213], v207 offset:34816
	ds_read_b128 v[214:217], v207 offset:35840
	ds_read_b128 v[218:221], v207 offset:36864
	ds_read_b128 v[222:225], v207 offset:37888
	ds_read_b128 v[226:229], v207 offset:38912
	ds_read_b128 v[230:233], v207 offset:39936
	global_load_lds_dwordx4 v[242:243], off
	v_lshl_add_u64 v[242:243], s[30:31], 0, v[176:177]
	s_mov_b32 m0, s56
	s_nop 0
	global_load_lds_dwordx4 v[242:243], off
	s_waitcnt vmcnt(8)
	s_waitcnt lgkmcnt(0)
	s_barrier
	s_setprio 3
	s_waitcnt lgkmcnt(0)
	v_mfma_f32_16x16x32_bf16 v[128:131], v[132:135], v[164:167], v[128:131]
	v_mfma_f32_16x16x32_bf16 v[128:131], v[136:139], v[168:171], v[128:131]
	v_mfma_f32_16x16x32_bf16 v[124:127], v[140:143], v[164:167], v[124:127]
	v_mfma_f32_16x16x32_bf16 v[124:127], v[144:147], v[168:171], v[124:127]
	v_mfma_f32_16x16x32_bf16 v[96:99], v[140:143], v[210:213], v[96:99]
	v_mfma_f32_16x16x32_bf16 v[96:99], v[144:147], v[214:217], v[96:99]
	v_mfma_f32_16x16x32_bf16 v[100:103], v[132:135], v[210:213], v[100:103]
	v_mfma_f32_16x16x32_bf16 v[100:103], v[136:139], v[214:217], v[100:103]
	v_mfma_f32_16x16x32_bf16 v[112:115], v[132:135], v[218:221], v[112:115]
	v_mfma_f32_16x16x32_bf16 v[112:115], v[136:139], v[222:225], v[112:115]
	v_mfma_f32_16x16x32_bf16 v[108:111], v[140:143], v[218:221], v[108:111]
	v_mfma_f32_16x16x32_bf16 v[108:111], v[144:147], v[222:225], v[108:111]
	v_mfma_f32_16x16x32_bf16 v[76:79], v[140:143], v[226:229], v[76:79]
	v_mfma_f32_16x16x32_bf16 v[76:79], v[144:147], v[230:233], v[76:79]
	v_mfma_f32_16x16x32_bf16 v[80:83], v[132:135], v[226:229], v[80:83]
	v_mfma_f32_16x16x32_bf16 v[80:83], v[136:139], v[230:233], v[80:83]
	v_mfma_f32_16x16x32_bf16 v[120:123], v[148:151], v[164:167], v[120:123]
	v_mfma_f32_16x16x32_bf16 v[120:123], v[152:155], v[168:171], v[120:123]
	v_mfma_f32_16x16x32_bf16 v[116:119], v[156:159], v[164:167], v[116:119]
	v_mfma_f32_16x16x32_bf16 v[116:119], v[160:163], v[168:171], v[116:119]
	v_mfma_f32_16x16x32_bf16 v[88:91], v[156:159], v[210:213], v[88:91]
	v_mfma_f32_16x16x32_bf16 v[88:91], v[160:163], v[214:217], v[88:91]
	v_mfma_f32_16x16x32_bf16 v[92:95], v[148:151], v[210:213], v[92:95]
	v_mfma_f32_16x16x32_bf16 v[92:95], v[152:155], v[214:217], v[92:95]
	v_mfma_f32_16x16x32_bf16 v[104:107], v[148:151], v[218:221], v[104:107]
	v_mfma_f32_16x16x32_bf16 v[104:107], v[152:155], v[222:225], v[104:107]
	v_mfma_f32_16x16x32_bf16 v[84:87], v[156:159], v[218:221], v[84:87]
	v_mfma_f32_16x16x32_bf16 v[84:87], v[160:163], v[222:225], v[84:87]
	v_mfma_f32_16x16x32_bf16 v[68:71], v[156:159], v[226:229], v[68:71]
	v_mfma_f32_16x16x32_bf16 v[68:71], v[160:163], v[230:233], v[68:71]
	v_mfma_f32_16x16x32_bf16 v[72:75], v[148:151], v[226:229], v[72:75]
	v_mfma_f32_16x16x32_bf16 v[72:75], v[152:155], v[230:233], v[72:75]
	s_setprio 0
	s_barrier
; #define PG8_STAGE(bufoff, gbase, voff) do { _Pragma("unroll") for (int _i = 0; _i < 2; ++_i) \
;         __builtin_amdgcn_global_load_lds((const unsigned*)((const char*)(gbase) + (voff)[_i]), (PG8_LAS unsigned*)(lds + (bufoff) + ldsw + _i * 8192), 16, 0, 0); } while (0)
; #define PG8_LDA(dst, b, h) do { _Pragma("unroll") for (int m = 0; m < 4; ++m) _Pragma("unroll") for (int k = 0; k < 2; ++k) dst[m][k] = *(const PG8_LAS bf16x8*)(lds + PG8_SA(b, h) + aoff + m * 2048 + k * 1024); } while (0)
; #define PG8_MMA(ai, bj, At, Bt) do { __builtin_amdgcn_s_setprio(3); _Pragma("unroll") for (int m = 0; m < 4; ++m) _Pragma("unroll") for (int n = 0; n < 2; ++n) _Pragma("unroll") for (int k = 0; k < 2; ++k) \
;         acc[ai][bj][m][n] = __builtin_amdgcn_mfma_f32_16x16x32_bf16(Bt[n][k], At[m][k], acc[ai][bj][m][n], 0, 0, 0); __builtin_amdgcn_s_setprio(0); } while (0)
; #define PG8_WAIT_V(n) asm volatile("s_waitcnt vmcnt(" #n ")" ::: "memory")
; #define PG8_WAIT_L(n) asm volatile("s_waitcnt lgkmcnt(" #n ")" ::: "memory")
; #define PG8_BAR __builtin_amdgcn_s_barrier()
; #define PG8_SCHED __builtin_amdgcn_sched_barrier(0)
; template <class Epi, class Sched, bool ALIGN_EPI = false, bool SP2 = false>
; __device__ __forceinline__ void gemm_phase(PG8_LAS unsigned char* lds, const Gemm g, const Sched& S, const Epi& E) {
;     ...
;             PG8_LDA(At, 1, 1); PG8_STAGE(PG8_SB(1, 0), b3, voffB); PG8_STAGE(PG8_SB(1, 1), b3 + hstepB, voffB); PG8_STAGE(PG8_SA(1, 0), a3, voffA);
;             PG8_WAIT_V(8); PG8_WAIT_L(0); PG8_BAR; PG8_MMA(1, 0, At, B0); PG8_MMA(1, 1, At, B1); PG8_BAR; PG8_SCHED;
	s_mov_b32 m0, s77
	v_lshl_add_u64 v[234:235], v[234:235], 0, s[4:5]
	s_add_u32 s28, s28, 0x2b0080
	ds_read_b128 v[164:167], v207 offset:49152
	ds_read_b128 v[168:171], v207 offset:50176
	ds_read_b128 v[210:213], v207 offset:51200
	ds_read_b128 v[214:217], v207 offset:52224
	ds_read_b128 v[218:221], v207 offset:53248
	ds_read_b128 v[222:225], v207 offset:54272
	ds_read_b128 v[226:229], v207 offset:55296
	ds_read_b128 v[230:233], v207 offset:56320
	global_load_lds_dwordx4 v[234:235], off
	v_lshl_add_u64 v[234:235], v[236:237], 0, s[4:5]
	s_mov_b32 m0, s78
	s_addc_u32 s29, s29, 0
	global_load_lds_dwordx4 v[234:235], off
	v_lshl_add_u64 v[234:235], s[28:29], 0, v[174:175]
	s_mov_b32 m0, s79
	s_nop 0
	global_load_lds_dwordx4 v[234:235], off
	v_lshl_add_u64 v[234:235], s[28:29], 0, v[178:179]
	s_mov_b32 m0, s80
	s_nop 0
	global_load_lds_dwordx4 v[234:235], off
	v_lshl_add_u64 v[234:235], v[238:239], 0, s[4:5]
	s_mov_b32 m0, s57
	s_nop 0
	global_load_lds_dwordx4 v[234:235], off
	v_lshl_add_u64 v[234:235], v[240:241], 0, s[4:5]
	s_mov_b32 m0, s58
	s_nop 0
	global_load_lds_dwordx4 v[234:235], off
	s_waitcnt vmcnt(8)
	s_waitcnt lgkmcnt(0)
	s_barrier
	s_setprio 3
	s_waitcnt lgkmcnt(0)
	v_mfma_f32_16x16x32_bf16 v[64:67], v[132:135], v[164:167], v[64:67]
	v_mfma_f32_16x16x32_bf16 v[64:67], v[136:139], v[168:171], v[64:67]
	v_mfma_f32_16x16x32_bf16 v[60:63], v[140:143], v[164:167], v[60:63]
	v_mfma_f32_16x16x32_bf16 v[60:63], v[144:147], v[168:171], v[60:63]
	v_mfma_f32_16x16x32_bf16 v[44:47], v[140:143], v[210:213], v[44:47]
	v_mfma_f32_16x16x32_bf16 v[44:47], v[144:147], v[214:217], v[44:47]
	v_mfma_f32_16x16x32_bf16 v[48:51], v[132:135], v[210:213], v[48:51]
	v_mfma_f32_16x16x32_bf16 v[48:51], v[136:139], v[214:217], v[48:51]
	v_mfma_f32_16x16x32_bf16 v[32:35], v[132:135], v[218:221], v[32:35]
	v_mfma_f32_16x16x32_bf16 v[32:35], v[136:139], v[222:225], v[32:35]
	v_mfma_f32_16x16x32_bf16 v[28:31], v[140:143], v[218:221], v[28:31]
	v_mfma_f32_16x16x32_bf16 v[28:31], v[144:147], v[222:225], v[28:31]
	v_mfma_f32_16x16x32_bf16 v[12:15], v[140:143], v[226:229], v[12:15]
	v_mfma_f32_16x16x32_bf16 v[12:15], v[144:147], v[230:233], v[12:15]
	v_mfma_f32_16x16x32_bf16 v[16:19], v[132:135], v[226:229], v[16:19]
	v_mfma_f32_16x16x32_bf16 v[16:19], v[136:139], v[230:233], v[16:19]
	v_mfma_f32_16x16x32_bf16 v[56:59], v[148:151], v[164:167], v[56:59]
	v_mfma_f32_16x16x32_bf16 v[56:59], v[152:155], v[168:171], v[56:59]
	v_mfma_f32_16x16x32_bf16 v[52:55], v[156:159], v[164:167], v[52:55]
	v_mfma_f32_16x16x32_bf16 v[52:55], v[160:163], v[168:171], v[52:55]
	v_mfma_f32_16x16x32_bf16 v[36:39], v[156:159], v[210:213], v[36:39]
	v_mfma_f32_16x16x32_bf16 v[36:39], v[160:163], v[214:217], v[36:39]
	v_mfma_f32_16x16x32_bf16 v[40:43], v[148:151], v[210:213], v[40:43]
	v_mfma_f32_16x16x32_bf16 v[40:43], v[152:155], v[214:217], v[40:43]
	v_mfma_f32_16x16x32_bf16 v[24:27], v[148:151], v[218:221], v[24:27]
	v_mfma_f32_16x16x32_bf16 v[24:27], v[152:155], v[222:225], v[24:27]
	v_mfma_f32_16x16x32_bf16 v[20:23], v[156:159], v[218:221], v[20:23]
	v_mfma_f32_16x16x32_bf16 v[20:23], v[160:163], v[222:225], v[20:23]
	v_mfma_f32_16x16x32_bf16 v[4:7], v[156:159], v[226:229], v[4:7]
	v_mfma_f32_16x16x32_bf16 v[4:7], v[160:163], v[230:233], v[4:7]
	v_mfma_f32_16x16x32_bf16 v[8:11], v[148:151], v[226:229], v[8:11]
	v_mfma_f32_16x16x32_bf16 v[8:11], v[152:155], v[230:233], v[8:11]
	s_setprio 0
	s_barrier
	s_add_i32 s61, s61, 2
	s_add_u32 s12, s12, 0x100
	s_addc_u32 s13, s13, 0
	s_cmpk_gt_u32 s61, 0xa9
	s_cbranch_scc1 .LBB0_978

; #define PG8_STAGE(bufoff, gbase, voff) do { _Pragma("unroll") for (int _i = 0; _i < 2; ++_i) \
;         __builtin_amdgcn_global_load_lds((const unsigned*)((const char*)(gbase) + (voff)[_i]), (PG8_LAS unsigned*)(lds + (bufoff) + ldsw + _i * 8192), 16, 0, 0); } while (0)
; #define PG8_LDA(dst, b, h) do { _Pragma("unroll") for (int m = 0; m < 4; ++m) _Pragma("unroll") for (int k = 0; k < 2; ++k) dst[m][k] = *(const PG8_LAS bf16x8*)(lds + PG8_SA(b, h) + aoff + m * 2048 + k * 1024); } while (0)
; #define PG8_LDB(dst, b, h) do { _Pragma("unroll") for (int n = 0; n < 2; ++n) _Pragma("unroll") for (int k = 0; k < 2; ++k) dst[n][k] = *(const PG8_LAS bf16x8*)(lds + PG8_SB(b, h) + boff + n * 2048 + k * 1024); } while (0)
; #define PG8_MMA(ai, bj, At, Bt) do { __builtin_amdgcn_s_setprio(3); _Pragma("unroll") for (int m = 0; m < 4; ++m) _Pragma("unroll") for (int n = 0; n < 2; ++n) _Pragma("unroll") for (int k = 0; k < 2; ++k) \
;         acc[ai][bj][m][n] = __builtin_amdgcn_mfma_f32_16x16x32_bf16(Bt[n][k], At[m][k], acc[ai][bj][m][n], 0, 0, 0); __builtin_amdgcn_s_setprio(0); } while (0)
; #define PG8_WAIT_V(n) asm volatile("s_waitcnt vmcnt(" #n ")" ::: "memory")
; #define PG8_WAIT_L(n) asm volatile("s_waitcnt lgkmcnt(" #n ")" ::: "memory")
; #define PG8_BAR __builtin_amdgcn_s_barrier()
; #define PG8_SCHED __builtin_amdgcn_sched_barrier(0)
; template <class Epi, class Sched, bool ALIGN_EPI = false, bool SP2 = false>
; __device__ __forceinline__ void gemm_phase(PG8_LAS unsigned char* lds, const Gemm g, const Sched& S, const Epi& E) {
;     ...
;             PG8_LDB(B0, 0, 0); PG8_LDB(B1, 0, 1); PG8_SCHED; PG8_LDA(At, 0, 0); PG8_STAGE(PG8_SA(1, 1), a1 + hstepA, voffA);
;             PG8_WAIT_V(8); PG8_WAIT_L(0); PG8_BAR; PG8_MMA(0, 0, At, B0); PG8_MMA(0, 1, At, B1); PG8_BAR; PG8_SCHED;
;             PG8_LDA(At, 0, 1); PG8_STAGE(PG8_SB(0, 0), b2, voffB); PG8_STAGE(PG8_SB(0, 1), b2 + hstepB, voffB); PG8_STAGE(PG8_SA(0, 0), a2, voffA);
.LBB0_1018:
	v_add_u32_e32 v142, s46, v189
	v_add_u32_e32 v158, s47, v189
	s_add_u32 s40, s20, s22
	ds_read_b128 v[130:133], v142
	ds_read_b128 v[134:137], v142 offset:1024
	ds_read_b128 v[138:141], v142 offset:2048
	ds_read_b128 v[142:145], v142 offset:3072
	ds_read_b128 v[146:149], v158
	ds_read_b128 v[150:153], v158 offset:1024
	ds_read_b128 v[154:157], v158 offset:2048
	ds_read_b128 v[158:161], v158 offset:3072
	s_addc_u32 s41, s21, s23
	s_add_u32 s40, s40, 0x21500100
	s_addc_u32 s41, s41, 0
	s_add_u32 s87, s44, s22
	s_addc_u32 s88, s45, s23
	s_cmpk_eq_i32 s22, 0x5500
	s_cselect_b32 s43, s17, s41
	s_cselect_b32 s42, s16, s40
	s_cselect_b32 s41, s11, s88
	s_cselect_b32 s40, s10, s87
	s_mov_b32 m0, s77
	v_lshl_add_u64 v[186:187], v[0:1], 0, s[22:23]
	ds_read_b128 v[162:165], v180
	ds_read_b128 v[166:169], v180 offset:1024
	ds_read_b128 v[182:185], v180 offset:2048
	ds_read_b128 v[190:193], v180 offset:3072
	ds_read_b128 v[194:197], v180 offset:4096
	ds_read_b128 v[208:211], v180 offset:5120
	ds_read_b128 v[212:215], v180 offset:6144
	ds_read_b128 v[216:219], v180 offset:7168
	global_load_lds_dwordx4 v[186:187], off
	v_lshl_add_u64 v[186:187], v[170:171], 0, s[22:23]
	s_mov_b32 m0, s78
	s_nop 0
	global_load_lds_dwordx4 v[186:187], off
	s_waitcnt vmcnt(8)
	s_waitcnt lgkmcnt(0)
	s_barrier
	s_setprio 3
	s_waitcnt lgkmcnt(0)
	v_mfma_f32_16x16x32_bf16 v[126:129], v[130:133], v[162:165], v[126:129]
	v_mfma_f32_16x16x32_bf16 v[126:129], v[134:137], v[166:169], v[126:129]
	v_mfma_f32_16x16x32_bf16 v[122:125], v[138:141], v[162:165], v[122:125]
	v_mfma_f32_16x16x32_bf16 v[122:125], v[142:145], v[166:169], v[122:125]
	v_mfma_f32_16x16x32_bf16 v[94:97], v[138:141], v[182:185], v[94:97]
	v_mfma_f32_16x16x32_bf16 v[94:97], v[142:145], v[190:193], v[94:97]
	v_mfma_f32_16x16x32_bf16 v[98:101], v[130:133], v[182:185], v[98:101]
	v_mfma_f32_16x16x32_bf16 v[98:101], v[134:137], v[190:193], v[98:101]
	v_mfma_f32_16x16x32_bf16 v[110:113], v[130:133], v[194:197], v[110:113]
	v_mfma_f32_16x16x32_bf16 v[110:113], v[134:137], v[208:211], v[110:113]
	v_mfma_f32_16x16x32_bf16 v[106:109], v[138:141], v[194:197], v[106:109]
	v_mfma_f32_16x16x32_bf16 v[106:109], v[142:145], v[208:211], v[106:109]
	v_mfma_f32_16x16x32_bf16 v[74:77], v[138:141], v[212:215], v[74:77]
	v_mfma_f32_16x16x32_bf16 v[74:77], v[142:145], v[216:219], v[74:77]
	v_mfma_f32_16x16x32_bf16 v[78:81], v[130:133], v[212:215], v[78:81]
	v_mfma_f32_16x16x32_bf16 v[78:81], v[134:137], v[216:219], v[78:81]
	v_mfma_f32_16x16x32_bf16 v[118:121], v[146:149], v[162:165], v[118:121]
	v_mfma_f32_16x16x32_bf16 v[118:121], v[150:153], v[166:169], v[118:121]
	v_mfma_f32_16x16x32_bf16 v[114:117], v[154:157], v[162:165], v[114:117]
	v_mfma_f32_16x16x32_bf16 v[114:117], v[158:161], v[166:169], v[114:117]
	v_mfma_f32_16x16x32_bf16 v[86:89], v[154:157], v[182:185], v[86:89]
	v_mfma_f32_16x16x32_bf16 v[86:89], v[158:161], v[190:193], v[86:89]
	v_mfma_f32_16x16x32_bf16 v[90:93], v[146:149], v[182:185], v[90:93]
	v_mfma_f32_16x16x32_bf16 v[90:93], v[150:153], v[190:193], v[90:93]
	v_mfma_f32_16x16x32_bf16 v[102:105], v[146:149], v[194:197], v[102:105]
	v_mfma_f32_16x16x32_bf16 v[102:105], v[150:153], v[208:211], v[102:105]
	v_mfma_f32_16x16x32_bf16 v[82:85], v[154:157], v[194:197], v[82:85]
	v_mfma_f32_16x16x32_bf16 v[82:85], v[158:161], v[208:211], v[82:85]
	v_mfma_f32_16x16x32_bf16 v[66:69], v[154:157], v[212:215], v[66:69]
	v_mfma_f32_16x16x32_bf16 v[66:69], v[158:161], v[216:219], v[66:69]
	v_mfma_f32_16x16x32_bf16 v[70:73], v[146:149], v[212:215], v[70:73]
	v_mfma_f32_16x16x32_bf16 v[70:73], v[150:153], v[216:219], v[70:73]
	s_setprio 0
	s_barrier
	s_mov_b32 m0, s79
	v_lshl_add_u64 v[186:187], s[40:41], 0, v[174:175]
	s_add_u32 s88, s40, 0x2b0000
	ds_read_b128 v[162:165], v180 offset:16384
	ds_read_b128 v[166:169], v180 offset:17408
	ds_read_b128 v[182:185], v180 offset:18432
	ds_read_b128 v[190:193], v180 offset:19456
	ds_read_b128 v[194:197], v180 offset:20480
	ds_read_b128 v[208:211], v180 offset:21504
	ds_read_b128 v[212:215], v180 offset:22528
	ds_read_b128 v[216:219], v180 offset:23552
	global_load_lds_dwordx4 v[186:187], off
	v_lshl_add_u64 v[198:199], s[40:41], 0, v[178:179]
	s_mov_b32 m0, s80
	s_addc_u32 s89, s41, 0
	global_load_lds_dwordx4 v[198:199], off
	v_lshl_add_u64 v[204:205], s[88:89], 0, v[174:175]
	s_mov_b32 m0, s81
	v_lshl_add_u64 v[220:221], s[42:43], 0, v[176:177]
	global_load_lds_dwordx4 v[204:205], off
	v_lshl_add_u64 v[204:205], s[88:89], 0, v[178:179]
	s_mov_b32 m0, s82
	s_nop 0
	global_load_lds_dwordx4 v[204:205], off
	v_lshl_add_u64 v[204:205], s[42:43], 0, v[172:173]
	s_mov_b32 m0, s58
	s_nop 0
	global_load_lds_dwordx4 v[204:205], off
	s_mov_b32 m0, s60
	s_nop 0
	global_load_lds_dwordx4 v[220:221], off
	s_waitcnt vmcnt(8)
	s_waitcnt lgkmcnt(0)
	s_barrier
; #define PG8_STAGE(bufoff, gbase, voff) do { _Pragma("unroll") for (int _i = 0; _i < 2; ++_i) \
;         __builtin_amdgcn_global_load_lds((const unsigned*)((const char*)(gbase) + (voff)[_i]), (PG8_LAS unsigned*)(lds + (bufoff) + ldsw + _i * 8192), 16, 0, 0); } while (0)
; #define PG8_LDA(dst, b, h) do { _Pragma("unroll") for (int m = 0; m < 4; ++m) _Pragma("unroll") for (int k = 0; k < 2; ++k) dst[m][k] = *(const PG8_LAS bf16x8*)(lds + PG8_SA(b, h) + aoff + m * 2048 + k * 1024); } while (0)
; #define PG8_LDB(dst, b, h) do { _Pragma("unroll") for (int n = 0; n < 2; ++n) _Pragma("unroll") for (int k = 0; k < 2; ++k) dst[n][k] = *(const PG8_LAS bf16x8*)(lds + PG8_SB(b, h) + boff + n * 2048 + k * 1024); } while (0)
; #define PG8_MMA(ai, bj, At, Bt) do { __builtin_amdgcn_s_setprio(3); _Pragma("unroll") for (int m = 0; m < 4; ++m) _Pragma("unroll") for (int n = 0; n < 2; ++n) _Pragma("unroll") for (int k = 0; k < 2; ++k) \
;         acc[ai][bj][m][n] = __builtin_amdgcn_mfma_f32_16x16x32_bf16(Bt[n][k], At[m][k], acc[ai][bj][m][n], 0, 0, 0); __builtin_amdgcn_s_setprio(0); } while (0)
; #define PG8_WAIT_V(n) asm volatile("s_waitcnt vmcnt(" #n ")" ::: "memory")
; #define PG8_WAIT_L(n) asm volatile("s_waitcnt lgkmcnt(" #n ")" ::: "memory")
; #define PG8_BAR __builtin_amdgcn_s_barrier()
; #define PG8_SCHED __builtin_amdgcn_sched_barrier(0)
; template <class Epi, class Sched, bool ALIGN_EPI = false, bool SP2 = false>
; __device__ __forceinline__ void gemm_phase(PG8_LAS unsigned char* lds, const Gemm g, const Sched& S, const Epi& E) {
;     ...
;             PG8_WAIT_V(8); PG8_WAIT_L(0); PG8_BAR; PG8_MMA(1, 0, At, B0); PG8_MMA(1, 1, At, B1); PG8_BAR; PG8_SCHED;
;             PG8_LDB(B0, 1, 0); PG8_LDB(B1, 1, 1); PG8_SCHED; PG8_LDA(At, 1, 0); PG8_STAGE(PG8_SA(0, 1), a2 + hstepA, voffA);
;             PG8_WAIT_V(8); PG8_WAIT_L(0); PG8_BAR; PG8_MMA(0, 0, At, B0); PG8_MMA(0, 1, At, B1); PG8_BAR; PG8_SCHED;
	s_setprio 3
	s_waitcnt lgkmcnt(0)
	v_mfma_f32_16x16x32_bf16 v[62:65], v[130:133], v[162:165], v[62:65]
	v_mfma_f32_16x16x32_bf16 v[62:65], v[134:137], v[166:169], v[62:65]
	v_mfma_f32_16x16x32_bf16 v[58:61], v[138:141], v[162:165], v[58:61]
	v_mfma_f32_16x16x32_bf16 v[58:61], v[142:145], v[166:169], v[58:61]
	v_mfma_f32_16x16x32_bf16 v[42:45], v[138:141], v[182:185], v[42:45]
	v_mfma_f32_16x16x32_bf16 v[42:45], v[142:145], v[190:193], v[42:45]
	v_mfma_f32_16x16x32_bf16 v[46:49], v[130:133], v[182:185], v[46:49]
	v_mfma_f32_16x16x32_bf16 v[46:49], v[134:137], v[190:193], v[46:49]
	v_mfma_f32_16x16x32_bf16 v[30:33], v[130:133], v[194:197], v[30:33]
	v_mfma_f32_16x16x32_bf16 v[30:33], v[134:137], v[208:211], v[30:33]
	v_mfma_f32_16x16x32_bf16 v[26:29], v[138:141], v[194:197], v[26:29]
	v_mfma_f32_16x16x32_bf16 v[26:29], v[142:145], v[208:211], v[26:29]
	v_mfma_f32_16x16x32_bf16 v[10:13], v[138:141], v[212:215], v[10:13]
	v_mfma_f32_16x16x32_bf16 v[10:13], v[142:145], v[216:219], v[10:13]
	v_mfma_f32_16x16x32_bf16 v[14:17], v[130:133], v[212:215], v[14:17]
	v_mfma_f32_16x16x32_bf16 v[14:17], v[134:137], v[216:219], v[14:17]
	v_mfma_f32_16x16x32_bf16 v[54:57], v[146:149], v[162:165], v[54:57]
	v_mfma_f32_16x16x32_bf16 v[54:57], v[150:153], v[166:169], v[54:57]
	v_mfma_f32_16x16x32_bf16 v[50:53], v[154:157], v[162:165], v[50:53]
	v_mfma_f32_16x16x32_bf16 v[50:53], v[158:161], v[166:169], v[50:53]
	v_mfma_f32_16x16x32_bf16 v[34:37], v[154:157], v[182:185], v[34:37]
	v_mfma_f32_16x16x32_bf16 v[34:37], v[158:161], v[190:193], v[34:37]
	v_mfma_f32_16x16x32_bf16 v[38:41], v[146:149], v[182:185], v[38:41]
	v_mfma_f32_16x16x32_bf16 v[38:41], v[150:153], v[190:193], v[38:41]
	v_mfma_f32_16x16x32_bf16 v[22:25], v[146:149], v[194:197], v[22:25]
	v_mfma_f32_16x16x32_bf16 v[22:25], v[150:153], v[208:211], v[22:25]
	v_mfma_f32_16x16x32_bf16 v[18:21], v[154:157], v[194:197], v[18:21]
	v_mfma_f32_16x16x32_bf16 v[18:21], v[158:161], v[208:211], v[18:21]
	v_mfma_f32_16x16x32_bf16 v[2:5], v[154:157], v[212:215], v[2:5]
	v_mfma_f32_16x16x32_bf16 v[2:5], v[158:161], v[216:219], v[2:5]
	v_mfma_f32_16x16x32_bf16 v[6:9], v[146:149], v[212:215], v[6:9]
	v_mfma_f32_16x16x32_bf16 v[6:9], v[150:153], v[216:219], v[6:9]
	s_setprio 0
	s_barrier
	v_add_u32_e32 v142, s52, v189
	v_add_u32_e32 v158, s53, v189
	ds_read_b128 v[130:133], v142
	ds_read_b128 v[134:137], v142 offset:1024
	ds_read_b128 v[138:141], v142 offset:2048
	ds_read_b128 v[142:145], v142 offset:3072
	ds_read_b128 v[146:149], v158
	ds_read_b128 v[150:153], v158 offset:1024
	ds_read_b128 v[154:157], v158 offset:2048
	ds_read_b128 v[158:161], v158 offset:3072
	s_add_u32 s42, s42, 0x2b0000
	s_addc_u32 s43, s43, 0
	s_mov_b32 m0, s61
	v_lshl_add_u64 v[222:223], s[42:43], 0, v[172:173]
	ds_read_b128 v[162:165], v180 offset:32768
	ds_read_b128 v[166:169], v180 offset:33792
	ds_read_b128 v[182:185], v180 offset:34816
	ds_read_b128 v[190:193], v180 offset:35840
	ds_read_b128 v[194:197], v180 offset:36864
	ds_read_b128 v[208:211], v180 offset:37888
	ds_read_b128 v[212:215], v180 offset:38912
	ds_read_b128 v[216:219], v180 offset:39936
	global_load_lds_dwordx4 v[222:223], off
	v_lshl_add_u64 v[222:223], s[42:43], 0, v[176:177]
	s_mov_b32 m0, s62
	s_nop 0
	global_load_lds_dwordx4 v[222:223], off
	s_waitcnt vmcnt(8)
	s_waitcnt lgkmcnt(0)
	s_barrier
	s_setprio 3
	s_waitcnt lgkmcnt(0)
	v_mfma_f32_16x16x32_bf16 v[126:129], v[130:133], v[162:165], v[126:129]
	v_mfma_f32_16x16x32_bf16 v[126:129], v[134:137], v[166:169], v[126:129]
	v_mfma_f32_16x16x32_bf16 v[122:125], v[138:141], v[162:165], v[122:125]
	v_mfma_f32_16x16x32_bf16 v[122:125], v[142:145], v[166:169], v[122:125]
	v_mfma_f32_16x16x32_bf16 v[94:97], v[138:141], v[182:185], v[94:97]
	v_mfma_f32_16x16x32_bf16 v[94:97], v[142:145], v[190:193], v[94:97]
	v_mfma_f32_16x16x32_bf16 v[98:101], v[130:133], v[182:185], v[98:101]
	v_mfma_f32_16x16x32_bf16 v[98:101], v[134:137], v[190:193], v[98:101]
	v_mfma_f32_16x16x32_bf16 v[110:113], v[130:133], v[194:197], v[110:113]
	v_mfma_f32_16x16x32_bf16 v[110:113], v[134:137], v[208:211], v[110:113]
	v_mfma_f32_16x16x32_bf16 v[106:109], v[138:141], v[194:197], v[106:109]
	v_mfma_f32_16x16x32_bf16 v[106:109], v[142:145], v[208:211], v[106:109]
	v_mfma_f32_16x16x32_bf16 v[74:77], v[138:141], v[212:215], v[74:77]
	v_mfma_f32_16x16x32_bf16 v[74:77], v[142:145], v[216:219], v[74:77]
	v_mfma_f32_16x16x32_bf16 v[78:81], v[130:133], v[212:215], v[78:81]
	v_mfma_f32_16x16x32_bf16 v[78:81], v[134:137], v[216:219], v[78:81]
	v_mfma_f32_16x16x32_bf16 v[118:121], v[146:149], v[162:165], v[118:121]
	v_mfma_f32_16x16x32_bf16 v[118:121], v[150:153], v[166:169], v[118:121]
	v_mfma_f32_16x16x32_bf16 v[114:117], v[154:157], v[162:165], v[114:117]
	v_mfma_f32_16x16x32_bf16 v[114:117], v[158:161], v[166:169], v[114:117]
	v_mfma_f32_16x16x32_bf16 v[86:89], v[154:157], v[182:185], v[86:89]
	v_mfma_f32_16x16x32_bf16 v[86:89], v[158:161], v[190:193], v[86:89]
	v_mfma_f32_16x16x32_bf16 v[90:93], v[146:149], v[182:185], v[90:93]
	v_mfma_f32_16x16x32_bf16 v[90:93], v[150:153], v[190:193], v[90:93]
	v_mfma_f32_16x16x32_bf16 v[102:105], v[146:149], v[194:197], v[102:105]
	v_mfma_f32_16x16x32_bf16 v[102:105], v[150:153], v[208:211], v[102:105]
	v_mfma_f32_16x16x32_bf16 v[82:85], v[154:157], v[194:197], v[82:85]
	v_mfma_f32_16x16x32_bf16 v[82:85], v[158:161], v[208:211], v[82:85]
	v_mfma_f32_16x16x32_bf16 v[66:69], v[154:157], v[212:215], v[66:69]
	v_mfma_f32_16x16x32_bf16 v[66:69], v[158:161], v[216:219], v[66:69]
	v_mfma_f32_16x16x32_bf16 v[70:73], v[146:149], v[212:215], v[70:73]
	v_mfma_f32_16x16x32_bf16 v[70:73], v[150:153], v[216:219], v[70:73]
	s_setprio 0
	s_barrier
; #define PG8_STAGE(bufoff, gbase, voff) do { _Pragma("unroll") for (int _i = 0; _i < 2; ++_i) \
;         __builtin_amdgcn_global_load_lds((const unsigned*)((const char*)(gbase) + (voff)[_i]), (PG8_LAS unsigned*)(lds + (bufoff) + ldsw + _i * 8192), 16, 0, 0); } while (0)
; #define PG8_LDA(dst, b, h) do { _Pragma("unroll") for (int m = 0; m < 4; ++m) _Pragma("unroll") for (int k = 0; k < 2; ++k) dst[m][k] = *(const PG8_LAS bf16x8*)(lds + PG8_SA(b, h) + aoff + m * 2048 + k * 1024); } while (0)
; #define PG8_MMA(ai, bj, At, Bt) do { __builtin_amdgcn_s_setprio(3); _Pragma("unroll") for (int m = 0; m < 4; ++m) _Pragma("unroll") for (int n = 0; n < 2; ++n) _Pragma("unroll") for (int k = 0; k < 2; ++k) \
;         acc[ai][bj][m][n] = __builtin_amdgcn_mfma_f32_16x16x32_bf16(Bt[n][k], At[m][k], acc[ai][bj][m][n], 0, 0, 0); __builtin_amdgcn_s_setprio(0); } while (0)
; #define PG8_WAIT_V(n) asm volatile("s_waitcnt vmcnt(" #n ")" ::: "memory")
; #define PG8_WAIT_L(n) asm volatile("s_waitcnt lgkmcnt(" #n ")" ::: "memory")
; #define PG8_BAR __builtin_amdgcn_s_barrier()
; #define PG8_SCHED __builtin_amdgcn_sched_barrier(0)
; template <class Epi, class Sched, bool ALIGN_EPI = false, bool SP2 = false>
; __device__ __forceinline__ void gemm_phase(PG8_LAS unsigned char* lds, const Gemm g, const Sched& S, const Epi& E) {
;     ...
;             PG8_LDA(At, 1, 1); PG8_STAGE(PG8_SB(1, 0), b3, voffB); PG8_STAGE(PG8_SB(1, 1), b3 + hstepB, voffB); PG8_STAGE(PG8_SA(1, 0), a3, voffA);
;             PG8_WAIT_V(8); PG8_WAIT_L(0); PG8_BAR; PG8_MMA(1, 0, At, B0); PG8_MMA(1, 1, At, B1); PG8_BAR; PG8_SCHED;
	s_mov_b32 m0, s83
	v_lshl_add_u64 v[186:187], v[186:187], 0, s[18:19]
	s_add_u32 s40, s40, 0x2b0080
	ds_read_b128 v[162:165], v180 offset:49152
	ds_read_b128 v[166:169], v180 offset:50176
	ds_read_b128 v[182:185], v180 offset:51200
	ds_read_b128 v[190:193], v180 offset:52224
	ds_read_b128 v[194:197], v180 offset:53248
	ds_read_b128 v[208:211], v180 offset:54272
	ds_read_b128 v[212:215], v180 offset:55296
	ds_read_b128 v[216:219], v180 offset:56320
	global_load_lds_dwordx4 v[186:187], off
	v_lshl_add_u64 v[186:187], v[198:199], 0, s[18:19]
	s_mov_b32 m0, s84
	s_addc_u32 s41, s41, 0
	global_load_lds_dwordx4 v[186:187], off
	v_lshl_add_u64 v[186:187], s[40:41], 0, v[174:175]
	s_mov_b32 m0, s85
	s_nop 0
	global_load_lds_dwordx4 v[186:187], off
	v_lshl_add_u64 v[186:187], s[40:41], 0, v[178:179]
	s_mov_b32 m0, s86
	s_nop 0
	global_load_lds_dwordx4 v[186:187], off
	v_lshl_add_u64 v[186:187], v[204:205], 0, s[18:19]
	s_mov_b32 m0, s63
	s_nop 0
	global_load_lds_dwordx4 v[186:187], off
	v_lshl_add_u64 v[186:187], v[220:221], 0, s[18:19]
	s_mov_b32 m0, s64
	s_nop 0
	global_load_lds_dwordx4 v[186:187], off
	s_waitcnt vmcnt(8)
	s_waitcnt lgkmcnt(0)
	s_barrier
	s_setprio 3
	s_waitcnt lgkmcnt(0)
	v_mfma_f32_16x16x32_bf16 v[62:65], v[130:133], v[162:165], v[62:65]
	v_mfma_f32_16x16x32_bf16 v[62:65], v[134:137], v[166:169], v[62:65]
	v_mfma_f32_16x16x32_bf16 v[58:61], v[138:141], v[162:165], v[58:61]
	v_mfma_f32_16x16x32_bf16 v[58:61], v[142:145], v[166:169], v[58:61]
	v_mfma_f32_16x16x32_bf16 v[42:45], v[138:141], v[182:185], v[42:45]
	v_mfma_f32_16x16x32_bf16 v[42:45], v[142:145], v[190:193], v[42:45]
	v_mfma_f32_16x16x32_bf16 v[46:49], v[130:133], v[182:185], v[46:49]
	v_mfma_f32_16x16x32_bf16 v[46:49], v[134:137], v[190:193], v[46:49]
	v_mfma_f32_16x16x32_bf16 v[30:33], v[130:133], v[194:197], v[30:33]
	v_mfma_f32_16x16x32_bf16 v[30:33], v[134:137], v[208:211], v[30:33]
	v_mfma_f32_16x16x32_bf16 v[26:29], v[138:141], v[194:197], v[26:29]
	v_mfma_f32_16x16x32_bf16 v[26:29], v[142:145], v[208:211], v[26:29]
	v_mfma_f32_16x16x32_bf16 v[10:13], v[138:141], v[212:215], v[10:13]
	v_mfma_f32_16x16x32_bf16 v[10:13], v[142:145], v[216:219], v[10:13]
	v_mfma_f32_16x16x32_bf16 v[14:17], v[130:133], v[212:215], v[14:17]
	v_mfma_f32_16x16x32_bf16 v[14:17], v[134:137], v[216:219], v[14:17]
	v_mfma_f32_16x16x32_bf16 v[54:57], v[146:149], v[162:165], v[54:57]
	v_mfma_f32_16x16x32_bf16 v[54:57], v[150:153], v[166:169], v[54:57]
	v_mfma_f32_16x16x32_bf16 v[50:53], v[154:157], v[162:165], v[50:53]
	v_mfma_f32_16x16x32_bf16 v[50:53], v[158:161], v[166:169], v[50:53]
	v_mfma_f32_16x16x32_bf16 v[34:37], v[154:157], v[182:185], v[34:37]
	v_mfma_f32_16x16x32_bf16 v[34:37], v[158:161], v[190:193], v[34:37]
	v_mfma_f32_16x16x32_bf16 v[38:41], v[146:149], v[182:185], v[38:41]
	v_mfma_f32_16x16x32_bf16 v[38:41], v[150:153], v[190:193], v[38:41]
	v_mfma_f32_16x16x32_bf16 v[22:25], v[146:149], v[194:197], v[22:25]
	v_mfma_f32_16x16x32_bf16 v[22:25], v[150:153], v[208:211], v[22:25]
	v_mfma_f32_16x16x32_bf16 v[18:21], v[154:157], v[194:197], v[18:21]
	v_mfma_f32_16x16x32_bf16 v[18:21], v[158:161], v[208:211], v[18:21]
	v_mfma_f32_16x16x32_bf16 v[2:5], v[154:157], v[212:215], v[2:5]
	v_mfma_f32_16x16x32_bf16 v[2:5], v[158:161], v[216:219], v[2:5]
	v_mfma_f32_16x16x32_bf16 v[6:9], v[146:149], v[212:215], v[6:9]
	v_mfma_f32_16x16x32_bf16 v[6:9], v[150:153], v[216:219], v[6:9]
	s_setprio 0
	s_barrier
	s_add_i32 s67, s67, 2
	s_add_u32 s22, s22, 0x100
	s_addc_u32 s23, s23, 0
	s_cmpk_gt_u32 s67, 0xa9
	s_cbranch_scc1 .LBB0_1021
